# GEMM K-loops: flips deleted + one static s_setprio 1 for waves 4-7 before each K-loop
# baseline (speedup 1.0000x reference)
; #define PG8_STAGE(bufoff, gbase, voff) do { _Pragma("unroll") for (int _i = 0; _i < 2; ++_i) \
;     __builtin_amdgcn_global_load_lds((const unsigned*)((const char*)(gbase) + (voff)[_i]), (PG8_LAS unsigned*)(lds + (bufoff) + ldsw + _i * 8192), 16, 0, 0); } while (0)
; #define PG8_LDA(dst, b, h) do { _Pragma("unroll") for (int m = 0; m < 4; ++m) _Pragma("unroll") for (int k = 0; k < 2; ++k) dst[m][k] = *(const PG8_LAS bf16x8*)(lds + PG8_SA(b, h) + aoff + m * 2048 + k * 1024); } while (0)
; #define PG8_LDB(dst, b, h) do { _Pragma("unroll") for (int n = 0; n < 2; ++n) _Pragma("unroll") for (int k = 0; k < 2; ++k) dst[n][k] = *(const PG8_LAS bf16x8*)(lds + PG8_SB(b, h) + boff + n * 2048 + k * 1024); } while (0)
; #define PG8_SCHED __builtin_amdgcn_sched_barrier(0)
; template <class Epi, class Sched>
; DI void gemm_phase(PG8_LAS unsigned char* lds, const Gemm g, const Sched& S, const Epi& E) {
;     ...
;   for (;;) {
;     const bool has_next = S.next(ui + 1, nxt);
;     const char* nA = has_next ? (const char*)g.A + (size_t)nxt.pm * tstepA : cA; const char* nB = has_next ? (const char*)g.Bt + (size_t)nxt.pn * tstepB : cB;
; #pragma unroll 1
;     for (int t = 0; t < nt; t += 2) {
;       const bool last = (t == nt - 2);
;       const char* a1 = cA + (size_t)(t + 1) * kstep;
;       const char* a2 = last ? nA : cA + (size_t)(t + 2) * kstep; const char* b2 = last ? nB : cB + (size_t)(t + 2) * kstep;
;       const char* a3 = a2 + kstep; const char* b3 = b2 + kstep;
;       PG8_LDB(B0, 0, 0); PG8_LDB(B1, 0, 1); PG8_SCHED; PG8_LDA(At, 0, 0); PG8_STAGE(PG8_SA(1, 1), a1 + hstepA, voffA);
;     ...
; #pragma unroll
;     for (int a = 0; a < 2; ++a)
; #pragma unroll
;       for (int b = 0; b < 2; ++b)
; #pragma unroll
;         for (int m = 0; m < 4; ++m)
; #pragma unroll
;           for (int n = 0; n < 2; ++n) acc[a][b][m][n] = (f32x4){0.f, 0.f, 0.f, 0.f};
.LBB0_285:
	s_ashr_i32 s23, s22, 31
	s_lshl_b64 s[26:27], s[22:23], 19
	s_add_u32 s26, s50, s26
	s_addc_u32 s27, s51, s27
	s_and_b64 s[28:29], s[24:25], exec
	s_cselect_b32 s1, s27, s7
	s_cselect_b32 s5, s26, s6
	s_ashr_i32 s21, s20, 31
	s_lshl_b64 s[28:29], s[20:21], 19
	s_add_u32 s28, s86, s28
	s_addc_u32 s29, s87, s29
	s_and_b64 s[34:35], s[24:25], exec
	s_cselect_b32 s21, s29, s31
	s_cselect_b32 s23, s28, s30
	s_add_u32 s6, s6, 0x40080
	s_addc_u32 s7, s7, 0
	s_add_u32 s67, s30, 0x100
	v_mov_b32_e32 v2, 0
	s_addc_u32 s68, s31, 0
	s_mov_b32 s69, -2
	v_mov_b32_e32 v3, v2
	v_mov_b32_e32 v4, v2
	v_mov_b32_e32 v5, v2
	v_mov_b32_e32 v6, v2
	v_mov_b32_e32 v7, v2
	v_mov_b32_e32 v8, v2
	v_mov_b32_e32 v9, v2
	v_mov_b32_e32 v22, v2
	v_mov_b32_e32 v23, v2
	v_mov_b32_e32 v24, v2
	v_mov_b32_e32 v25, v2
	v_mov_b32_e32 v18, v2
	v_mov_b32_e32 v19, v2
	v_mov_b32_e32 v20, v2
	v_mov_b32_e32 v21, v2
	v_mov_b32_e32 v38, v2
	v_mov_b32_e32 v39, v2
	v_mov_b32_e32 v40, v2
	v_mov_b32_e32 v41, v2
	v_mov_b32_e32 v34, v2
	v_mov_b32_e32 v35, v2
	v_mov_b32_e32 v36, v2
	v_mov_b32_e32 v37, v2
	v_mov_b32_e32 v54, v2
	v_mov_b32_e32 v55, v2
	v_mov_b32_e32 v56, v2
	v_mov_b32_e32 v57, v2
	v_mov_b32_e32 v50, v2
	v_mov_b32_e32 v51, v2
	v_mov_b32_e32 v52, v2
	v_mov_b32_e32 v53, v2
	v_mov_b32_e32 v14, v2
	v_mov_b32_e32 v15, v2
	v_mov_b32_e32 v16, v2
	v_mov_b32_e32 v17, v2
	v_mov_b32_e32 v10, v2
	v_mov_b32_e32 v11, v2
	v_mov_b32_e32 v12, v2
	v_mov_b32_e32 v13, v2
	v_mov_b32_e32 v30, v2
	v_mov_b32_e32 v31, v2
	v_mov_b32_e32 v32, v2
	v_mov_b32_e32 v33, v2
	v_mov_b32_e32 v26, v2
	v_mov_b32_e32 v27, v2
	v_mov_b32_e32 v28, v2
	v_mov_b32_e32 v29, v2
	v_mov_b32_e32 v46, v2
	v_mov_b32_e32 v47, v2
	v_mov_b32_e32 v48, v2
	v_mov_b32_e32 v49, v2
	v_mov_b32_e32 v42, v2
	v_mov_b32_e32 v43, v2
	v_mov_b32_e32 v44, v2
	v_mov_b32_e32 v45, v2
	v_mov_b32_e32 v62, v2
	v_mov_b32_e32 v63, v2
	v_mov_b32_e32 v64, v2
	v_mov_b32_e32 v65, v2
	v_mov_b32_e32 v58, v2
	v_mov_b32_e32 v59, v2
	v_mov_b32_e32 v60, v2
	v_mov_b32_e32 v61, v2
	v_mov_b32_e32 v70, v2
	v_mov_b32_e32 v71, v2
	v_mov_b32_e32 v72, v2
	v_mov_b32_e32 v73, v2
	v_mov_b32_e32 v66, v2
	v_mov_b32_e32 v67, v2
	v_mov_b32_e32 v68, v2
	v_mov_b32_e32 v69, v2
	v_mov_b32_e32 v86, v2
	v_mov_b32_e32 v87, v2
	v_mov_b32_e32 v88, v2
	v_mov_b32_e32 v89, v2
	v_mov_b32_e32 v82, v2
	v_mov_b32_e32 v83, v2
	v_mov_b32_e32 v84, v2
	v_mov_b32_e32 v85, v2
	v_mov_b32_e32 v102, v2
	v_mov_b32_e32 v103, v2
	v_mov_b32_e32 v104, v2
	v_mov_b32_e32 v105, v2
	v_mov_b32_e32 v98, v2
	v_mov_b32_e32 v99, v2
	v_mov_b32_e32 v100, v2
	v_mov_b32_e32 v101, v2
	v_mov_b32_e32 v118, v2
	v_mov_b32_e32 v119, v2
	v_mov_b32_e32 v120, v2
	v_mov_b32_e32 v121, v2
	v_mov_b32_e32 v114, v2
	v_mov_b32_e32 v115, v2
	v_mov_b32_e32 v116, v2
	v_mov_b32_e32 v117, v2
	v_mov_b32_e32 v78, v2
	v_mov_b32_e32 v79, v2
	v_mov_b32_e32 v80, v2
	v_mov_b32_e32 v81, v2
	v_mov_b32_e32 v74, v2
	v_mov_b32_e32 v75, v2
	v_mov_b32_e32 v76, v2
	v_mov_b32_e32 v77, v2
	v_mov_b32_e32 v94, v2
	v_mov_b32_e32 v95, v2
	v_mov_b32_e32 v96, v2
	v_mov_b32_e32 v97, v2
	v_mov_b32_e32 v90, v2
	v_mov_b32_e32 v91, v2
	v_mov_b32_e32 v92, v2
	v_mov_b32_e32 v93, v2
	v_mov_b32_e32 v110, v2
	v_mov_b32_e32 v111, v2
	v_mov_b32_e32 v112, v2
	v_mov_b32_e32 v113, v2
	v_mov_b32_e32 v106, v2
	v_mov_b32_e32 v107, v2
	v_mov_b32_e32 v108, v2
	v_mov_b32_e32 v109, v2
	v_mov_b32_e32 v126, v2
	v_mov_b32_e32 v127, v2
	v_mov_b32_e32 v128, v2
	v_mov_b32_e32 v129, v2
	v_mov_b32_e32 v122, v2
	v_mov_b32_e32 v123, v2
	v_mov_b32_e32 v124, v2
	v_mov_b32_e32 v125, v2
	v_readfirstlane_b32 s100, v212
	s_nop 3
	s_lshr_b32 s100, s100, 8
	s_cmp_lg_u32 s100, 0
	s_cbranch_scc0 .Lgp_0
	s_setprio 1
.Lgp_0:
.LBB0_286:
	ds_read_b128 v[146:149], v180
	ds_read_b128 v[150:153], v180 offset:1024
	ds_read_b128 v[154:157], v180 offset:2048
	ds_read_b128 v[158:161], v180 offset:3072
	ds_read_b128 v[162:165], v181
	ds_read_b128 v[166:169], v181 offset:1024
	ds_read_b128 v[170:173], v181 offset:2048
	ds_read_b128 v[174:177], v181 offset:3072
	s_add_u32 s16, s6, 0xfffc0080
	s_addc_u32 s30, s7, -1
	s_cmp_eq_u32 s69, 12
	s_cselect_b32 s35, s1, s30
	s_cselect_b32 s34, s5, s16
	s_cselect_b32 s31, s21, s68
	s_cselect_b32 s30, s23, s67
	v_lshl_add_u64 v[178:179], s[6:7], 0, v[140:141]
	s_add_i32 m0, s3, 0xc000
	ds_read_b128 v[186:189], v182
	ds_read_b128 v[190:193], v182 offset:1024
	ds_read_b128 v[194:197], v182 offset:2048
	ds_read_b128 v[198:201], v182 offset:3072
	ds_read_b128 v[202:205], v182 offset:4096
	ds_read_b128 v[206:209], v182 offset:5120
	ds_read_b128 v[214:217], v182 offset:6144
	ds_read_b128 v[218:221], v182 offset:7168
	global_load_lds_dwordx4 v[178:179], off
	v_lshl_add_u64 v[178:179], s[6:7], 0, v[142:143]
	s_add_i32 m0, s3, 0xe000
	s_nop 0
	global_load_lds_dwordx4 v[178:179], off
	s_waitcnt vmcnt(8)
	s_waitcnt lgkmcnt(0)
	s_barrier
; #define PG8_STAGE(bufoff, gbase, voff) do { _Pragma("unroll") for (int _i = 0; _i < 2; ++_i) \
;     __builtin_amdgcn_global_load_lds((const unsigned*)((const char*)(gbase) + (voff)[_i]), (PG8_LAS unsigned*)(lds + (bufoff) + ldsw + _i * 8192), 16, 0, 0); } while (0)
; #define PG8_LDA(dst, b, h) do { _Pragma("unroll") for (int m = 0; m < 4; ++m) _Pragma("unroll") for (int k = 0; k < 2; ++k) dst[m][k] = *(const PG8_LAS bf16x8*)(lds + PG8_SA(b, h) + aoff + m * 2048 + k * 1024); } while (0)
; #define PG8_MMA(ai, bj, At, Bt) do { __builtin_amdgcn_s_setprio(1); _Pragma("unroll") for (int m = 0; m < 4; ++m) _Pragma("unroll") for (int n = 0; n < 2; ++n) _Pragma("unroll") for (int k = 0; k < 2; ++k) \
;     acc[ai][bj][m][n] = __builtin_amdgcn_mfma_f32_16x16x32_bf16(Bt[n][k], At[m][k], acc[ai][bj][m][n], 0, 0, 0); __builtin_amdgcn_s_setprio(0); } while (0)
; #define PG8_WAIT_V(n) asm volatile("s_waitcnt vmcnt(" #n ")" ::: "memory")
; #define PG8_WAIT_L(n) asm volatile("s_waitcnt lgkmcnt(" #n ")" ::: "memory")
; #define PG8_BAR __builtin_amdgcn_s_barrier()
; #define PG8_SCHED __builtin_amdgcn_sched_barrier(0)
; template <class Epi, class Sched>
; DI void gemm_phase(PG8_LAS unsigned char* lds, const Gemm g, const Sched& S, const Epi& E) {
;     ...
;       PG8_WAIT_V(8); PG8_WAIT_L(0); PG8_BAR; PG8_MMA(0, 0, At, B0); PG8_MMA(0, 1, At, B1); PG8_BAR; PG8_SCHED;
;       PG8_LDA(At, 0, 1); PG8_STAGE(PG8_SB(0, 0), b2, voffB); PG8_STAGE(PG8_SB(0, 1), b2 + hstepB, voffB); PG8_STAGE(PG8_SA(0, 0), a2, voffA);
;       PG8_WAIT_V(8); PG8_WAIT_L(0); PG8_BAR; PG8_MMA(1, 0, At, B0); PG8_MMA(1, 1, At, B1); PG8_BAR; PG8_SCHED;
	s_waitcnt lgkmcnt(0)
	v_mfma_f32_16x16x32_bf16 v[122:125], v[146:149], v[186:189], v[122:125]
	v_mfma_f32_16x16x32_bf16 v[126:129], v[154:157], v[186:189], v[126:129]
	v_mfma_f32_16x16x32_bf16 v[106:109], v[146:149], v[194:197], v[106:109]
	v_mfma_f32_16x16x32_bf16 v[110:113], v[154:157], v[194:197], v[110:113]
	v_mfma_f32_16x16x32_bf16 v[90:93], v[146:149], v[202:205], v[90:93]
	v_mfma_f32_16x16x32_bf16 v[94:97], v[154:157], v[202:205], v[94:97]
	v_mfma_f32_16x16x32_bf16 v[74:77], v[146:149], v[214:217], v[74:77]
	v_mfma_f32_16x16x32_bf16 v[78:81], v[154:157], v[214:217], v[78:81]
	v_mfma_f32_16x16x32_bf16 v[122:125], v[150:153], v[190:193], v[122:125]
	v_mfma_f32_16x16x32_bf16 v[126:129], v[158:161], v[190:193], v[126:129]
	v_mfma_f32_16x16x32_bf16 v[106:109], v[150:153], v[198:201], v[106:109]
	v_mfma_f32_16x16x32_bf16 v[110:113], v[158:161], v[198:201], v[110:113]
	v_mfma_f32_16x16x32_bf16 v[90:93], v[150:153], v[206:209], v[90:93]
	v_mfma_f32_16x16x32_bf16 v[94:97], v[158:161], v[206:209], v[94:97]
	v_mfma_f32_16x16x32_bf16 v[74:77], v[150:153], v[218:221], v[74:77]
	v_mfma_f32_16x16x32_bf16 v[78:81], v[158:161], v[218:221], v[78:81]
	v_mfma_f32_16x16x32_bf16 v[114:117], v[162:165], v[186:189], v[114:117]
	v_mfma_f32_16x16x32_bf16 v[118:121], v[170:173], v[186:189], v[118:121]
	v_mfma_f32_16x16x32_bf16 v[98:101], v[162:165], v[194:197], v[98:101]
	v_mfma_f32_16x16x32_bf16 v[102:105], v[170:173], v[194:197], v[102:105]
	v_mfma_f32_16x16x32_bf16 v[82:85], v[162:165], v[202:205], v[82:85]
	v_mfma_f32_16x16x32_bf16 v[86:89], v[170:173], v[202:205], v[86:89]
	v_mfma_f32_16x16x32_bf16 v[66:69], v[162:165], v[214:217], v[66:69]
	v_mfma_f32_16x16x32_bf16 v[70:73], v[170:173], v[214:217], v[70:73]
	v_mfma_f32_16x16x32_bf16 v[114:117], v[166:169], v[190:193], v[114:117]
	v_mfma_f32_16x16x32_bf16 v[118:121], v[174:177], v[190:193], v[118:121]
	v_mfma_f32_16x16x32_bf16 v[98:101], v[166:169], v[198:201], v[98:101]
	v_mfma_f32_16x16x32_bf16 v[102:105], v[174:177], v[198:201], v[102:105]
	v_mfma_f32_16x16x32_bf16 v[82:85], v[166:169], v[206:209], v[82:85]
	v_mfma_f32_16x16x32_bf16 v[86:89], v[174:177], v[206:209], v[86:89]
	v_mfma_f32_16x16x32_bf16 v[66:69], v[166:169], v[218:221], v[66:69]
	v_mfma_f32_16x16x32_bf16 v[70:73], v[174:177], v[218:221], v[70:73]
	s_barrier
	s_add_i32 s16, s40, s2
	v_lshl_add_u64 v[178:179], s[30:31], 0, v[132:133]
	s_mov_b32 m0, s16
	ds_read_b128 v[186:189], v182 offset:16384
	ds_read_b128 v[190:193], v182 offset:17408
	ds_read_b128 v[194:197], v182 offset:18432
	ds_read_b128 v[198:201], v182 offset:19456
	ds_read_b128 v[202:205], v182 offset:20480
	ds_read_b128 v[206:209], v182 offset:21504
	ds_read_b128 v[214:217], v182 offset:22528
	ds_read_b128 v[218:221], v182 offset:23552
	global_load_lds_dwordx4 v[178:179], off
	s_add_i32 m0, s16, 0x2000
	s_add_u32 s56, s30, 0x40000
	v_lshl_add_u64 v[210:211], s[30:31], 0, v[136:137]
	s_addc_u32 s57, s31, 0
	s_add_i32 s16, s41, s2
	global_load_lds_dwordx4 v[210:211], off
	v_lshl_add_u64 v[222:223], s[56:57], 0, v[132:133]
	s_mov_b32 m0, s16
	v_lshl_add_u64 v[224:225], s[34:35], 0, v[134:135]
	global_load_lds_dwordx4 v[222:223], off
	v_lshl_add_u64 v[222:223], s[56:57], 0, v[136:137]
	s_add_i32 m0, s16, 0x2000
	s_nop 0
	global_load_lds_dwordx4 v[222:223], off
	v_lshl_add_u64 v[222:223], s[34:35], 0, v[130:131]
	s_mov_b32 m0, s3
	s_nop 0
	global_load_lds_dwordx4 v[222:223], off
	s_mov_b32 m0, s17
	s_nop 0
	global_load_lds_dwordx4 v[224:225], off
	s_waitcnt vmcnt(8)
	s_waitcnt lgkmcnt(0)
	s_barrier
	s_waitcnt lgkmcnt(0)
	v_mfma_f32_16x16x32_bf16 v[58:61], v[146:149], v[186:189], v[58:61]
	v_mfma_f32_16x16x32_bf16 v[62:65], v[154:157], v[186:189], v[62:65]
	v_mfma_f32_16x16x32_bf16 v[42:45], v[146:149], v[194:197], v[42:45]
	v_mfma_f32_16x16x32_bf16 v[46:49], v[154:157], v[194:197], v[46:49]
	v_mfma_f32_16x16x32_bf16 v[26:29], v[146:149], v[202:205], v[26:29]
	v_mfma_f32_16x16x32_bf16 v[30:33], v[154:157], v[202:205], v[30:33]
	v_mfma_f32_16x16x32_bf16 v[10:13], v[146:149], v[214:217], v[10:13]
	v_mfma_f32_16x16x32_bf16 v[14:17], v[154:157], v[214:217], v[14:17]
	v_mfma_f32_16x16x32_bf16 v[58:61], v[150:153], v[190:193], v[58:61]
	v_mfma_f32_16x16x32_bf16 v[62:65], v[158:161], v[190:193], v[62:65]
	v_mfma_f32_16x16x32_bf16 v[42:45], v[150:153], v[198:201], v[42:45]
	v_mfma_f32_16x16x32_bf16 v[46:49], v[158:161], v[198:201], v[46:49]
	v_mfma_f32_16x16x32_bf16 v[26:29], v[150:153], v[206:209], v[26:29]
	v_mfma_f32_16x16x32_bf16 v[30:33], v[158:161], v[206:209], v[30:33]
	v_mfma_f32_16x16x32_bf16 v[10:13], v[150:153], v[218:221], v[10:13]
	v_mfma_f32_16x16x32_bf16 v[14:17], v[158:161], v[218:221], v[14:17]
	v_mfma_f32_16x16x32_bf16 v[50:53], v[162:165], v[186:189], v[50:53]
	v_mfma_f32_16x16x32_bf16 v[54:57], v[170:173], v[186:189], v[54:57]
	v_mfma_f32_16x16x32_bf16 v[34:37], v[162:165], v[194:197], v[34:37]
	v_mfma_f32_16x16x32_bf16 v[38:41], v[170:173], v[194:197], v[38:41]
	v_mfma_f32_16x16x32_bf16 v[18:21], v[162:165], v[202:205], v[18:21]
	v_mfma_f32_16x16x32_bf16 v[22:25], v[170:173], v[202:205], v[22:25]
	v_mfma_f32_16x16x32_bf16 v[6:9], v[162:165], v[214:217], v[6:9]
	v_mfma_f32_16x16x32_bf16 v[2:5], v[170:173], v[214:217], v[2:5]
	v_mfma_f32_16x16x32_bf16 v[50:53], v[166:169], v[190:193], v[50:53]
	v_mfma_f32_16x16x32_bf16 v[54:57], v[174:177], v[190:193], v[54:57]
	v_mfma_f32_16x16x32_bf16 v[34:37], v[166:169], v[198:201], v[34:37]
	v_mfma_f32_16x16x32_bf16 v[38:41], v[174:177], v[198:201], v[38:41]
	v_mfma_f32_16x16x32_bf16 v[18:21], v[166:169], v[206:209], v[18:21]
	v_mfma_f32_16x16x32_bf16 v[22:25], v[174:177], v[206:209], v[22:25]
	v_mfma_f32_16x16x32_bf16 v[6:9], v[166:169], v[218:221], v[6:9]
	v_mfma_f32_16x16x32_bf16 v[2:5], v[174:177], v[218:221], v[2:5]
	s_barrier
; #define PG8_STAGE(bufoff, gbase, voff) do { _Pragma("unroll") for (int _i = 0; _i < 2; ++_i) \
;     __builtin_amdgcn_global_load_lds((const unsigned*)((const char*)(gbase) + (voff)[_i]), (PG8_LAS unsigned*)(lds + (bufoff) + ldsw + _i * 8192), 16, 0, 0); } while (0)
; #define PG8_LDA(dst, b, h) do { _Pragma("unroll") for (int m = 0; m < 4; ++m) _Pragma("unroll") for (int k = 0; k < 2; ++k) dst[m][k] = *(const PG8_LAS bf16x8*)(lds + PG8_SA(b, h) + aoff + m * 2048 + k * 1024); } while (0)
; #define PG8_LDB(dst, b, h) do { _Pragma("unroll") for (int n = 0; n < 2; ++n) _Pragma("unroll") for (int k = 0; k < 2; ++k) dst[n][k] = *(const PG8_LAS bf16x8*)(lds + PG8_SB(b, h) + boff + n * 2048 + k * 1024); } while (0)
; #define PG8_MMA(ai, bj, At, Bt) do { __builtin_amdgcn_s_setprio(1); _Pragma("unroll") for (int m = 0; m < 4; ++m) _Pragma("unroll") for (int n = 0; n < 2; ++n) _Pragma("unroll") for (int k = 0; k < 2; ++k) \
;     acc[ai][bj][m][n] = __builtin_amdgcn_mfma_f32_16x16x32_bf16(Bt[n][k], At[m][k], acc[ai][bj][m][n], 0, 0, 0); __builtin_amdgcn_s_setprio(0); } while (0)
; #define PG8_WAIT_V(n) asm volatile("s_waitcnt vmcnt(" #n ")" ::: "memory")
; #define PG8_WAIT_L(n) asm volatile("s_waitcnt lgkmcnt(" #n ")" ::: "memory")
; #define PG8_BAR __builtin_amdgcn_s_barrier()
; #define PG8_SCHED __builtin_amdgcn_sched_barrier(0)
; template <class Epi, class Sched>
; DI void gemm_phase(PG8_LAS unsigned char* lds, const Gemm g, const Sched& S, const Epi& E) {
;     ...
;       PG8_LDB(B0, 1, 0); PG8_LDB(B1, 1, 1); PG8_SCHED; PG8_LDA(At, 1, 0); PG8_STAGE(PG8_SA(0, 1), a2 + hstepA, voffA);
;       PG8_WAIT_V(8); PG8_WAIT_L(0); PG8_BAR; PG8_MMA(0, 0, At, B0); PG8_MMA(0, 1, At, B1); PG8_BAR; PG8_SCHED;
;       PG8_LDA(At, 1, 1); PG8_STAGE(PG8_SB(1, 0), b3, voffB); PG8_STAGE(PG8_SB(1, 1), b3 + hstepB, voffB); PG8_STAGE(PG8_SA(1, 0), a3, voffA);
	ds_read_b128 v[146:149], v184
	ds_read_b128 v[150:153], v184 offset:1024
	ds_read_b128 v[154:157], v184 offset:2048
	ds_read_b128 v[158:161], v184 offset:3072
	ds_read_b128 v[162:165], v185
	ds_read_b128 v[166:169], v185 offset:1024
	ds_read_b128 v[170:173], v185 offset:2048
	ds_read_b128 v[174:177], v185 offset:3072
	s_add_u32 s34, s34, 0x40000
	s_addc_u32 s35, s35, 0
	s_mov_b32 m0, s19
	v_lshl_add_u64 v[226:227], s[34:35], 0, v[130:131]
	ds_read_b128 v[186:189], v182 offset:32768
	ds_read_b128 v[190:193], v182 offset:33792
	ds_read_b128 v[194:197], v182 offset:34816
	ds_read_b128 v[198:201], v182 offset:35840
	ds_read_b128 v[202:205], v182 offset:36864
	ds_read_b128 v[206:209], v182 offset:37888
	ds_read_b128 v[214:217], v182 offset:38912
	ds_read_b128 v[218:221], v182 offset:39936
	global_load_lds_dwordx4 v[226:227], off
	v_lshl_add_u64 v[226:227], s[34:35], 0, v[134:135]
	s_mov_b32 m0, s33
	s_nop 0
	global_load_lds_dwordx4 v[226:227], off
	s_waitcnt vmcnt(8)
	s_waitcnt lgkmcnt(0)
	s_barrier
	s_waitcnt lgkmcnt(0)
	v_mfma_f32_16x16x32_bf16 v[122:125], v[146:149], v[186:189], v[122:125]
	v_mfma_f32_16x16x32_bf16 v[126:129], v[154:157], v[186:189], v[126:129]
	v_mfma_f32_16x16x32_bf16 v[106:109], v[146:149], v[194:197], v[106:109]
	v_mfma_f32_16x16x32_bf16 v[110:113], v[154:157], v[194:197], v[110:113]
	v_mfma_f32_16x16x32_bf16 v[90:93], v[146:149], v[202:205], v[90:93]
	v_mfma_f32_16x16x32_bf16 v[94:97], v[154:157], v[202:205], v[94:97]
	v_mfma_f32_16x16x32_bf16 v[74:77], v[146:149], v[214:217], v[74:77]
	v_mfma_f32_16x16x32_bf16 v[78:81], v[154:157], v[214:217], v[78:81]
	v_mfma_f32_16x16x32_bf16 v[122:125], v[150:153], v[190:193], v[122:125]
	v_mfma_f32_16x16x32_bf16 v[126:129], v[158:161], v[190:193], v[126:129]
	v_mfma_f32_16x16x32_bf16 v[106:109], v[150:153], v[198:201], v[106:109]
	v_mfma_f32_16x16x32_bf16 v[110:113], v[158:161], v[198:201], v[110:113]
	v_mfma_f32_16x16x32_bf16 v[90:93], v[150:153], v[206:209], v[90:93]
	v_mfma_f32_16x16x32_bf16 v[94:97], v[158:161], v[206:209], v[94:97]
	v_mfma_f32_16x16x32_bf16 v[74:77], v[150:153], v[218:221], v[74:77]
	v_mfma_f32_16x16x32_bf16 v[78:81], v[158:161], v[218:221], v[78:81]
	v_mfma_f32_16x16x32_bf16 v[114:117], v[162:165], v[186:189], v[114:117]
	v_mfma_f32_16x16x32_bf16 v[118:121], v[170:173], v[186:189], v[118:121]
	v_mfma_f32_16x16x32_bf16 v[98:101], v[162:165], v[194:197], v[98:101]
	v_mfma_f32_16x16x32_bf16 v[102:105], v[170:173], v[194:197], v[102:105]
	v_mfma_f32_16x16x32_bf16 v[82:85], v[162:165], v[202:205], v[82:85]
	v_mfma_f32_16x16x32_bf16 v[86:89], v[170:173], v[202:205], v[86:89]
	v_mfma_f32_16x16x32_bf16 v[66:69], v[162:165], v[214:217], v[66:69]
	v_mfma_f32_16x16x32_bf16 v[70:73], v[170:173], v[214:217], v[70:73]
	v_mfma_f32_16x16x32_bf16 v[114:117], v[166:169], v[190:193], v[114:117]
	v_mfma_f32_16x16x32_bf16 v[118:121], v[174:177], v[190:193], v[118:121]
	v_mfma_f32_16x16x32_bf16 v[98:101], v[166:169], v[198:201], v[98:101]
	v_mfma_f32_16x16x32_bf16 v[102:105], v[174:177], v[198:201], v[102:105]
	v_mfma_f32_16x16x32_bf16 v[82:85], v[166:169], v[206:209], v[82:85]
	v_mfma_f32_16x16x32_bf16 v[86:89], v[174:177], v[206:209], v[86:89]
	v_mfma_f32_16x16x32_bf16 v[66:69], v[166:169], v[218:221], v[66:69]
	v_mfma_f32_16x16x32_bf16 v[70:73], v[174:177], v[218:221], v[70:73]
	s_barrier
	s_add_i32 s16, s65, s2
	v_lshl_add_u64 v[178:179], v[178:179], 0, s[12:13]
	s_mov_b32 m0, s16
	ds_read_b128 v[186:189], v182 offset:49152
	ds_read_b128 v[190:193], v182 offset:50176
	ds_read_b128 v[194:197], v182 offset:51200
	ds_read_b128 v[198:201], v182 offset:52224
	ds_read_b128 v[202:205], v182 offset:53248
	ds_read_b128 v[206:209], v182 offset:54272
	ds_read_b128 v[214:217], v182 offset:55296
	ds_read_b128 v[218:221], v182 offset:56320
	global_load_lds_dwordx4 v[178:179], off
	s_add_i32 m0, s16, 0x2000
	s_add_u32 s30, s30, 0x40080
	v_lshl_add_u64 v[178:179], v[210:211], 0, s[12:13]
	s_addc_u32 s31, s31, 0
	s_add_i32 s16, s66, s2
	global_load_lds_dwordx4 v[178:179], off
	v_lshl_add_u64 v[178:179], s[30:31], 0, v[132:133]
	s_mov_b32 m0, s16
	s_nop 0
	global_load_lds_dwordx4 v[178:179], off
	v_lshl_add_u64 v[178:179], s[30:31], 0, v[136:137]
	s_add_i32 m0, s16, 0x2000
	s_nop 0
	global_load_lds_dwordx4 v[178:179], off
	v_lshl_add_u64 v[178:179], v[222:223], 0, s[12:13]
	s_mov_b32 m0, s36
	s_nop 0
	global_load_lds_dwordx4 v[178:179], off
	v_lshl_add_u64 v[178:179], v[224:225], 0, s[12:13]
	s_mov_b32 m0, s37
	s_nop 0
	global_load_lds_dwordx4 v[178:179], off
	s_waitcnt vmcnt(8)
	s_waitcnt lgkmcnt(0)
	s_barrier
; #define PG8_MMA(ai, bj, At, Bt) do { __builtin_amdgcn_s_setprio(1); _Pragma("unroll") for (int m = 0; m < 4; ++m) _Pragma("unroll") for (int n = 0; n < 2; ++n) _Pragma("unroll") for (int k = 0; k < 2; ++k) \
;     acc[ai][bj][m][n] = __builtin_amdgcn_mfma_f32_16x16x32_bf16(Bt[n][k], At[m][k], acc[ai][bj][m][n], 0, 0, 0); __builtin_amdgcn_s_setprio(0); } while (0)
; #define PG8_WAIT_V(n) asm volatile("s_waitcnt vmcnt(" #n ")" ::: "memory")
; #define PG8_WAIT_L(n) asm volatile("s_waitcnt lgkmcnt(" #n ")" ::: "memory")
; #define PG8_BAR __builtin_amdgcn_s_barrier()
; #define PG8_SCHED __builtin_amdgcn_sched_barrier(0)
; DI void rows_rstd(float (&rs)[2][4], const float* ps, const Unit& u, int wr, int fr, int fq, int p_lo, int p_hi, float inv_dim) {
;   f32x4 pv[2][4];
; #pragma unroll
;   for (int ai = 0; ai < 2; ++ai)
; #pragma unroll
;     for (int m = 0; m < 4; ++m) pv[ai][m] = *(const f32x4*)(ps + (size_t)(u.pm * BM + ai * HALF + wr * 64 + m * 16 + fr) * 16 + 4 * fq);
; template <class Epi, class Sched>
; DI void gemm_phase(PG8_LAS unsigned char* lds, const Gemm g, const Sched& S, const Epi& E) {
;     ...
;       PG8_WAIT_V(8); PG8_WAIT_L(0); PG8_BAR; PG8_MMA(1, 0, At, B0); PG8_MMA(1, 1, At, B1); PG8_BAR; PG8_SCHED;
;     }
;     if (wr == 0) PG8_BAR;
	s_waitcnt lgkmcnt(0)
	v_mfma_f32_16x16x32_bf16 v[58:61], v[146:149], v[186:189], v[58:61]
	v_mfma_f32_16x16x32_bf16 v[62:65], v[154:157], v[186:189], v[62:65]
	v_mfma_f32_16x16x32_bf16 v[42:45], v[146:149], v[194:197], v[42:45]
	v_mfma_f32_16x16x32_bf16 v[46:49], v[154:157], v[194:197], v[46:49]
	v_mfma_f32_16x16x32_bf16 v[26:29], v[146:149], v[202:205], v[26:29]
	v_mfma_f32_16x16x32_bf16 v[30:33], v[154:157], v[202:205], v[30:33]
	v_mfma_f32_16x16x32_bf16 v[10:13], v[146:149], v[214:217], v[10:13]
	v_mfma_f32_16x16x32_bf16 v[14:17], v[154:157], v[214:217], v[14:17]
	v_mfma_f32_16x16x32_bf16 v[58:61], v[150:153], v[190:193], v[58:61]
	v_mfma_f32_16x16x32_bf16 v[62:65], v[158:161], v[190:193], v[62:65]
	v_mfma_f32_16x16x32_bf16 v[42:45], v[150:153], v[198:201], v[42:45]
	v_mfma_f32_16x16x32_bf16 v[46:49], v[158:161], v[198:201], v[46:49]
	v_mfma_f32_16x16x32_bf16 v[26:29], v[150:153], v[206:209], v[26:29]
	v_mfma_f32_16x16x32_bf16 v[30:33], v[158:161], v[206:209], v[30:33]
	v_mfma_f32_16x16x32_bf16 v[10:13], v[150:153], v[218:221], v[10:13]
	v_mfma_f32_16x16x32_bf16 v[14:17], v[158:161], v[218:221], v[14:17]
	v_mfma_f32_16x16x32_bf16 v[50:53], v[162:165], v[186:189], v[50:53]
	v_mfma_f32_16x16x32_bf16 v[54:57], v[170:173], v[186:189], v[54:57]
	v_mfma_f32_16x16x32_bf16 v[34:37], v[162:165], v[194:197], v[34:37]
	v_mfma_f32_16x16x32_bf16 v[38:41], v[170:173], v[194:197], v[38:41]
	v_mfma_f32_16x16x32_bf16 v[18:21], v[162:165], v[202:205], v[18:21]
	v_mfma_f32_16x16x32_bf16 v[22:25], v[170:173], v[202:205], v[22:25]
	v_mfma_f32_16x16x32_bf16 v[6:9], v[162:165], v[214:217], v[6:9]
	v_mfma_f32_16x16x32_bf16 v[2:5], v[170:173], v[214:217], v[2:5]
	v_mfma_f32_16x16x32_bf16 v[50:53], v[166:169], v[190:193], v[50:53]
	v_mfma_f32_16x16x32_bf16 v[54:57], v[174:177], v[190:193], v[54:57]
	v_mfma_f32_16x16x32_bf16 v[34:37], v[166:169], v[198:201], v[34:37]
	v_mfma_f32_16x16x32_bf16 v[38:41], v[174:177], v[198:201], v[38:41]
	v_mfma_f32_16x16x32_bf16 v[18:21], v[166:169], v[206:209], v[18:21]
	v_mfma_f32_16x16x32_bf16 v[22:25], v[174:177], v[206:209], v[22:25]
	v_mfma_f32_16x16x32_bf16 v[6:9], v[166:169], v[218:221], v[6:9]
	v_mfma_f32_16x16x32_bf16 v[2:5], v[174:177], v[218:221], v[2:5]
	s_barrier
	s_add_i32 s69, s69, 2
	s_add_u32 s6, s6, 0x100
	s_addc_u32 s7, s7, 0
	s_add_u32 s67, s67, 0x100
	s_addc_u32 s68, s68, 0
	s_cmp_gt_u32 s69, 13
	s_cbranch_scc0 .LBB0_286
	v_lshl_add_u32 v166, s4, 8, v1
	v_or_b32_e32 v164, 16, v166
	v_ashrrev_i32_e32 v165, 31, v164
	v_or_b32_e32 v158, 32, v166
	v_lshlrev_b64 v[146:147], 6, v[164:165]
	v_ashrrev_i32_e32 v159, 31, v158
	v_lshl_add_u64 v[146:147], v[138:139], 0, v[146:147]
	v_lshlrev_b64 v[148:149], 6, v[158:159]
	v_ashrrev_i32_e32 v167, 31, v166
	v_lshl_add_u64 v[148:149], v[138:139], 0, v[148:149]
	global_load_dwordx4 v[160:163], v[146:147], off
	global_load_dwordx4 v[168:171], v[148:149], off
	v_lshlrev_b64 v[146:147], 6, v[166:167]
	v_lshl_add_u64 v[146:147], v[138:139], 0, v[146:147]
	global_load_dwordx4 v[172:175], v[146:147], off
	v_or_b32_e32 v156, 48, v166
	v_ashrrev_i32_e32 v157, 31, v156
	v_add_u32_e32 v154, 0x80, v166
	v_lshlrev_b64 v[146:147], 6, v[156:157]
	v_ashrrev_i32_e32 v155, 31, v154
	v_add_u32_e32 v150, 0x90, v166
	v_lshl_add_u64 v[146:147], v[138:139], 0, v[146:147]
	v_lshlrev_b64 v[148:149], 6, v[154:155]
	v_ashrrev_i32_e32 v151, 31, v150
	v_lshl_add_u64 v[148:149], v[138:139], 0, v[148:149]
	global_load_dwordx4 v[176:179], v[146:147], off
	global_load_dwordx4 v[186:189], v[148:149], off
	v_lshlrev_b64 v[146:147], 6, v[150:151]
	v_lshl_add_u64 v[146:147], v[138:139], 0, v[146:147]
	global_load_dwordx4 v[190:193], v[146:147], off
	v_add_u32_e32 v148, 0xa0, v166
	v_ashrrev_i32_e32 v149, 31, v148
	v_lshlrev_b64 v[146:147], 6, v[148:149]
	v_lshl_add_u64 v[146:147], v[138:139], 0, v[146:147]
	global_load_dwordx4 v[194:197], v[146:147], off
	v_add_u32_e32 v146, 0xb0, v166
	v_ashrrev_i32_e32 v147, 31, v146
	v_lshlrev_b64 v[152:153], 6, v[146:147]
	v_lshl_add_u64 v[152:153], v[138:139], 0, v[152:153]
	global_load_dwordx4 v[198:201], v[152:153], off
	s_and_b64 vcc, exec, s[14:15]
	s_cbranch_vccz .LBB0_289
	s_barrier

; #define PG8_STAGE(bufoff, gbase, voff) do { _Pragma("unroll") for (int _i = 0; _i < 2; ++_i) \
;     __builtin_amdgcn_global_load_lds((const unsigned*)((const char*)(gbase) + (voff)[_i]), (PG8_LAS unsigned*)(lds + (bufoff) + ldsw + _i * 8192), 16, 0, 0); } while (0)
; #define PG8_LDA(dst, b, h) do { _Pragma("unroll") for (int m = 0; m < 4; ++m) _Pragma("unroll") for (int k = 0; k < 2; ++k) dst[m][k] = *(const PG8_LAS bf16x8*)(lds + PG8_SA(b, h) + aoff + m * 2048 + k * 1024); } while (0)
; #define PG8_LDB(dst, b, h) do { _Pragma("unroll") for (int n = 0; n < 2; ++n) _Pragma("unroll") for (int k = 0; k < 2; ++k) dst[n][k] = *(const PG8_LAS bf16x8*)(lds + PG8_SB(b, h) + boff + n * 2048 + k * 1024); } while (0)
; #define PG8_SCHED __builtin_amdgcn_sched_barrier(0)
; template <class Epi, class Sched>
; DI void gemm_phase(PG8_LAS unsigned char* lds, const Gemm g, const Sched& S, const Epi& E) {
;     ...
;   for (;;) {
;     const bool has_next = S.next(ui + 1, nxt);
;     const char* nA = has_next ? (const char*)g.A + (size_t)nxt.pm * tstepA : cA; const char* nB = has_next ? (const char*)g.Bt + (size_t)nxt.pn * tstepB : cB;
; #pragma unroll 1
;     for (int t = 0; t < nt; t += 2) {
;       const bool last = (t == nt - 2);
;       const char* a1 = cA + (size_t)(t + 1) * kstep;
;       const char* a2 = last ? nA : cA + (size_t)(t + 2) * kstep; const char* b2 = last ? nB : cB + (size_t)(t + 2) * kstep;
;       const char* a3 = a2 + kstep; const char* b3 = b2 + kstep;
;       PG8_LDB(B0, 0, 0); PG8_LDB(B1, 0, 1); PG8_SCHED; PG8_LDA(At, 0, 0); PG8_STAGE(PG8_SA(1, 1), a1 + hstepA, voffA);
;     ...
; #pragma unroll
;     for (int a = 0; a < 2; ++a)
; #pragma unroll
;       for (int b = 0; b < 2; ++b)
; #pragma unroll
;         for (int m = 0; m < 4; ++m)
; #pragma unroll
;           for (int n = 0; n < 2; ++n) acc[a][b][m][n] = (f32x4){0.f, 0.f, 0.f, 0.f};
.LBB0_562:
	s_ashr_i32 s19, s18, 31
	s_lshl_b64 s[16:17], s[18:19], 19
	v_readlane_b32 s15, v254, 23
	s_add_u32 s20, s15, s16
	v_readlane_b32 s15, v254, 24
	s_addc_u32 s21, s15, s17
	s_and_b64 s[16:17], s[22:23], exec
	s_cselect_b32 s19, s21, s29
	s_cselect_b32 s27, s20, s28
	s_ashr_i32 s15, s14, 31
	s_lshl_b64 s[16:17], s[14:15], 19
	s_add_u32 s24, s96, s16
	s_addc_u32 s25, s97, s17
	s_and_b64 s[16:17], s[22:23], exec
	s_cselect_b32 s15, s25, s31
	s_cselect_b32 s67, s24, s30
	s_add_u32 s28, s28, 0x40080
	s_addc_u32 s29, s29, 0
	s_add_u32 s68, s30, 0x100
	v_mov_b32_e32 v0, 0
	s_addc_u32 s69, s31, 0
	s_mov_b32 s70, -2
	s_waitcnt lgkmcnt(0)
	v_mov_b32_e32 v1, v0
	v_mov_b32_e32 v2, v0
	v_mov_b32_e32 v3, v0
	v_mov_b32_e32 v4, v0
	v_mov_b32_e32 v5, v0
	v_mov_b32_e32 v6, v0
	v_mov_b32_e32 v7, v0
	v_mov_b32_e32 v16, v0
	v_mov_b32_e32 v17, v0
	v_mov_b32_e32 v18, v0
	v_mov_b32_e32 v19, v0
	v_mov_b32_e32 v20, v0
	v_mov_b32_e32 v21, v0
	v_mov_b32_e32 v22, v0
	v_mov_b32_e32 v23, v0
	v_mov_b32_e32 v32, v0
	v_mov_b32_e32 v33, v0
	v_mov_b32_e32 v34, v0
	v_mov_b32_e32 v35, v0
	v_mov_b32_e32 v36, v0
	v_mov_b32_e32 v37, v0
	v_mov_b32_e32 v38, v0
	v_mov_b32_e32 v39, v0
	v_mov_b32_e32 v48, v0
	v_mov_b32_e32 v49, v0
	v_mov_b32_e32 v50, v0
	v_mov_b32_e32 v51, v0
	v_mov_b32_e32 v52, v0
	v_mov_b32_e32 v53, v0
	v_mov_b32_e32 v54, v0
	v_mov_b32_e32 v55, v0
	v_mov_b32_e32 v8, v0
	v_mov_b32_e32 v9, v0
	v_mov_b32_e32 v10, v0
	v_mov_b32_e32 v11, v0
	v_mov_b32_e32 v12, v0
	v_mov_b32_e32 v13, v0
	v_mov_b32_e32 v14, v0
	v_mov_b32_e32 v15, v0
	v_mov_b32_e32 v24, v0
	v_mov_b32_e32 v25, v0
	v_mov_b32_e32 v26, v0
	v_mov_b32_e32 v27, v0
	v_mov_b32_e32 v28, v0
	v_mov_b32_e32 v29, v0
	v_mov_b32_e32 v30, v0
	v_mov_b32_e32 v31, v0
	v_mov_b32_e32 v40, v0
	v_mov_b32_e32 v41, v0
	v_mov_b32_e32 v42, v0
	v_mov_b32_e32 v43, v0
	v_mov_b32_e32 v44, v0
	v_mov_b32_e32 v45, v0
	v_mov_b32_e32 v46, v0
	v_mov_b32_e32 v47, v0
	v_mov_b32_e32 v56, v0
	v_mov_b32_e32 v57, v0
	v_mov_b32_e32 v58, v0
	v_mov_b32_e32 v59, v0
	v_mov_b32_e32 v60, v0
	v_mov_b32_e32 v61, v0
	v_mov_b32_e32 v62, v0
	v_mov_b32_e32 v63, v0
	v_mov_b32_e32 v64, v0
	v_mov_b32_e32 v65, v0
	v_mov_b32_e32 v66, v0
	v_mov_b32_e32 v67, v0
	v_mov_b32_e32 v68, v0
	v_mov_b32_e32 v69, v0
	v_mov_b32_e32 v70, v0
	v_mov_b32_e32 v71, v0
	v_mov_b32_e32 v80, v0
	v_mov_b32_e32 v81, v0
	v_mov_b32_e32 v82, v0
	v_mov_b32_e32 v83, v0
	v_mov_b32_e32 v84, v0
	v_mov_b32_e32 v85, v0
	v_mov_b32_e32 v86, v0
	v_mov_b32_e32 v87, v0
	v_mov_b32_e32 v96, v0
	v_mov_b32_e32 v97, v0
	v_mov_b32_e32 v98, v0
	v_mov_b32_e32 v99, v0
	v_mov_b32_e32 v100, v0
	v_mov_b32_e32 v101, v0
	v_mov_b32_e32 v102, v0
	v_mov_b32_e32 v103, v0
	s_waitcnt vmcnt(0)
	v_mov_b32_e32 v112, v0
	v_mov_b32_e32 v113, v0
	v_mov_b32_e32 v114, v0
	v_mov_b32_e32 v115, v0
	v_mov_b32_e32 v116, v0
	v_mov_b32_e32 v117, v0
	v_mov_b32_e32 v118, v0
	v_mov_b32_e32 v119, v0
	v_mov_b32_e32 v72, v0
	v_mov_b32_e32 v73, v0
	v_mov_b32_e32 v74, v0
	v_mov_b32_e32 v75, v0
	v_mov_b32_e32 v76, v0
	v_mov_b32_e32 v77, v0
	v_mov_b32_e32 v78, v0
	v_mov_b32_e32 v79, v0
	v_mov_b32_e32 v88, v0
	v_mov_b32_e32 v89, v0
	v_mov_b32_e32 v90, v0
	v_mov_b32_e32 v91, v0
	v_mov_b32_e32 v92, v0
	v_mov_b32_e32 v93, v0
	v_mov_b32_e32 v94, v0
	v_mov_b32_e32 v95, v0
	v_mov_b32_e32 v104, v0
	v_mov_b32_e32 v105, v0
	v_mov_b32_e32 v106, v0
	v_mov_b32_e32 v107, v0
	v_mov_b32_e32 v108, v0
	v_mov_b32_e32 v109, v0
	v_mov_b32_e32 v110, v0
	v_mov_b32_e32 v111, v0
	v_mov_b32_e32 v120, v0
	v_mov_b32_e32 v121, v0
	v_mov_b32_e32 v122, v0
	v_mov_b32_e32 v123, v0
	v_mov_b32_e32 v124, v0
	v_mov_b32_e32 v125, v0
	v_mov_b32_e32 v126, v0
	v_mov_b32_e32 v127, v0
	v_readfirstlane_b32 s100, v212
	s_nop 3
	s_lshr_b32 s100, s100, 8
	s_cmp_lg_u32 s100, 0
	s_cbranch_scc0 .Lgp_1
	s_setprio 1
.Lgp_1:
.LBB0_563:
	ds_read_b128 v[128:131], v167
	ds_read_b128 v[132:135], v167 offset:1024
	ds_read_b128 v[136:139], v167 offset:2048
	ds_read_b128 v[140:143], v167 offset:3072
	ds_read_b128 v[158:161], v168
	ds_read_b128 v[162:165], v168 offset:1024
	ds_read_b128 v[172:175], v168 offset:2048
	ds_read_b128 v[176:179], v168 offset:3072
	s_add_u32 s16, s28, 0xfffc0080
	s_addc_u32 s17, s29, -1
	s_cmp_eq_u32 s70, 12
	s_cselect_b32 s35, s19, s17
	s_cselect_b32 s34, s27, s16
	s_cselect_b32 s31, s15, s69
	s_cselect_b32 s30, s67, s68
	v_lshl_add_u64 v[214:215], s[28:29], 0, v[154:155]
	s_add_i32 m0, s3, 0xc000
	ds_read_b128 v[180:183], v169
	ds_read_b128 v[184:187], v169 offset:1024
	ds_read_b128 v[188:191], v169 offset:2048
	ds_read_b128 v[192:195], v169 offset:3072
	ds_read_b128 v[196:199], v169 offset:4096
	ds_read_b128 v[200:203], v169 offset:5120
	ds_read_b128 v[204:207], v169 offset:6144
	ds_read_b128 v[208:211], v169 offset:7168
	global_load_lds_dwordx4 v[214:215], off
	v_lshl_add_u64 v[214:215], s[28:29], 0, v[156:157]
	s_add_i32 m0, s3, 0xe000
	s_nop 0
	global_load_lds_dwordx4 v[214:215], off
	s_waitcnt vmcnt(8)
	s_waitcnt lgkmcnt(0)
	s_barrier
; #define PG8_STAGE(bufoff, gbase, voff) do { _Pragma("unroll") for (int _i = 0; _i < 2; ++_i) \
;     __builtin_amdgcn_global_load_lds((const unsigned*)((const char*)(gbase) + (voff)[_i]), (PG8_LAS unsigned*)(lds + (bufoff) + ldsw + _i * 8192), 16, 0, 0); } while (0)
; #define PG8_LDA(dst, b, h) do { _Pragma("unroll") for (int m = 0; m < 4; ++m) _Pragma("unroll") for (int k = 0; k < 2; ++k) dst[m][k] = *(const PG8_LAS bf16x8*)(lds + PG8_SA(b, h) + aoff + m * 2048 + k * 1024); } while (0)
; #define PG8_MMA(ai, bj, At, Bt) do { __builtin_amdgcn_s_setprio(1); _Pragma("unroll") for (int m = 0; m < 4; ++m) _Pragma("unroll") for (int n = 0; n < 2; ++n) _Pragma("unroll") for (int k = 0; k < 2; ++k) \
;     acc[ai][bj][m][n] = __builtin_amdgcn_mfma_f32_16x16x32_bf16(Bt[n][k], At[m][k], acc[ai][bj][m][n], 0, 0, 0); __builtin_amdgcn_s_setprio(0); } while (0)
; #define PG8_WAIT_V(n) asm volatile("s_waitcnt vmcnt(" #n ")" ::: "memory")
; #define PG8_WAIT_L(n) asm volatile("s_waitcnt lgkmcnt(" #n ")" ::: "memory")
; #define PG8_BAR __builtin_amdgcn_s_barrier()
; #define PG8_SCHED __builtin_amdgcn_sched_barrier(0)
; template <class Epi, class Sched>
; DI void gemm_phase(PG8_LAS unsigned char* lds, const Gemm g, const Sched& S, const Epi& E) {
;     ...
;       PG8_WAIT_V(8); PG8_WAIT_L(0); PG8_BAR; PG8_MMA(0, 0, At, B0); PG8_MMA(0, 1, At, B1); PG8_BAR; PG8_SCHED;
;       PG8_LDA(At, 0, 1); PG8_STAGE(PG8_SB(0, 0), b2, voffB); PG8_STAGE(PG8_SB(0, 1), b2 + hstepB, voffB); PG8_STAGE(PG8_SA(0, 0), a2, voffA);
;       PG8_WAIT_V(8); PG8_WAIT_L(0); PG8_BAR; PG8_MMA(1, 0, At, B0); PG8_MMA(1, 1, At, B1); PG8_BAR; PG8_SCHED;
	s_waitcnt lgkmcnt(0)
	v_mfma_f32_16x16x32_bf16 v[124:127], v[128:131], v[180:183], v[124:127]
	v_mfma_f32_16x16x32_bf16 v[120:123], v[136:139], v[180:183], v[120:123]
	v_mfma_f32_16x16x32_bf16 v[108:111], v[128:131], v[188:191], v[108:111]
	v_mfma_f32_16x16x32_bf16 v[104:107], v[136:139], v[188:191], v[104:107]
	v_mfma_f32_16x16x32_bf16 v[92:95], v[128:131], v[196:199], v[92:95]
	v_mfma_f32_16x16x32_bf16 v[88:91], v[136:139], v[196:199], v[88:91]
	v_mfma_f32_16x16x32_bf16 v[76:79], v[128:131], v[204:207], v[76:79]
	v_mfma_f32_16x16x32_bf16 v[72:75], v[136:139], v[204:207], v[72:75]
	v_mfma_f32_16x16x32_bf16 v[124:127], v[132:135], v[184:187], v[124:127]
	v_mfma_f32_16x16x32_bf16 v[120:123], v[140:143], v[184:187], v[120:123]
	v_mfma_f32_16x16x32_bf16 v[108:111], v[132:135], v[192:195], v[108:111]
	v_mfma_f32_16x16x32_bf16 v[104:107], v[140:143], v[192:195], v[104:107]
	v_mfma_f32_16x16x32_bf16 v[92:95], v[132:135], v[200:203], v[92:95]
	v_mfma_f32_16x16x32_bf16 v[88:91], v[140:143], v[200:203], v[88:91]
	v_mfma_f32_16x16x32_bf16 v[76:79], v[132:135], v[208:211], v[76:79]
	v_mfma_f32_16x16x32_bf16 v[72:75], v[140:143], v[208:211], v[72:75]
	v_mfma_f32_16x16x32_bf16 v[116:119], v[158:161], v[180:183], v[116:119]
	v_mfma_f32_16x16x32_bf16 v[112:115], v[172:175], v[180:183], v[112:115]
	v_mfma_f32_16x16x32_bf16 v[100:103], v[158:161], v[188:191], v[100:103]
	v_mfma_f32_16x16x32_bf16 v[96:99], v[172:175], v[188:191], v[96:99]
	v_mfma_f32_16x16x32_bf16 v[84:87], v[158:161], v[196:199], v[84:87]
	v_mfma_f32_16x16x32_bf16 v[80:83], v[172:175], v[196:199], v[80:83]
	v_mfma_f32_16x16x32_bf16 v[68:71], v[158:161], v[204:207], v[68:71]
	v_mfma_f32_16x16x32_bf16 v[64:67], v[172:175], v[204:207], v[64:67]
	v_mfma_f32_16x16x32_bf16 v[116:119], v[162:165], v[184:187], v[116:119]
	v_mfma_f32_16x16x32_bf16 v[112:115], v[176:179], v[184:187], v[112:115]
	v_mfma_f32_16x16x32_bf16 v[100:103], v[162:165], v[192:195], v[100:103]
	v_mfma_f32_16x16x32_bf16 v[96:99], v[176:179], v[192:195], v[96:99]
	v_mfma_f32_16x16x32_bf16 v[84:87], v[162:165], v[200:203], v[84:87]
	v_mfma_f32_16x16x32_bf16 v[80:83], v[176:179], v[200:203], v[80:83]
	v_mfma_f32_16x16x32_bf16 v[68:71], v[162:165], v[208:211], v[68:71]
	v_mfma_f32_16x16x32_bf16 v[64:67], v[176:179], v[208:211], v[64:67]
	s_barrier
	s_add_i32 s16, s55, s2
	v_lshl_add_u64 v[214:215], s[30:31], 0, v[146:147]
	s_mov_b32 m0, s16
	ds_read_b128 v[180:183], v169 offset:16384
	ds_read_b128 v[184:187], v169 offset:17408
	ds_read_b128 v[188:191], v169 offset:18432
	ds_read_b128 v[192:195], v169 offset:19456
	ds_read_b128 v[196:199], v169 offset:20480
	ds_read_b128 v[200:203], v169 offset:21504
	ds_read_b128 v[204:207], v169 offset:22528
	ds_read_b128 v[208:211], v169 offset:23552
	global_load_lds_dwordx4 v[214:215], off
	s_add_i32 m0, s16, 0x2000
	s_add_u32 s16, s30, 0x40000
	v_lshl_add_u64 v[216:217], s[30:31], 0, v[150:151]
	s_addc_u32 s17, s31, 0
	s_add_i32 s33, s64, s2
	global_load_lds_dwordx4 v[216:217], off
	v_lshl_add_u64 v[218:219], s[16:17], 0, v[146:147]
	s_mov_b32 m0, s33
	v_lshl_add_u64 v[220:221], s[34:35], 0, v[148:149]
	global_load_lds_dwordx4 v[218:219], off
	v_lshl_add_u64 v[218:219], s[16:17], 0, v[150:151]
	s_add_i32 m0, s33, 0x2000
	s_nop 0
	global_load_lds_dwordx4 v[218:219], off
	v_lshl_add_u64 v[218:219], s[34:35], 0, v[144:145]
	s_mov_b32 m0, s3
	s_nop 0
	global_load_lds_dwordx4 v[218:219], off
	s_mov_b32 m0, s36
	s_nop 0
	global_load_lds_dwordx4 v[220:221], off
	s_waitcnt vmcnt(8)
	s_waitcnt lgkmcnt(0)
	s_barrier
	s_waitcnt lgkmcnt(0)
	v_mfma_f32_16x16x32_bf16 v[60:63], v[128:131], v[180:183], v[60:63]
	v_mfma_f32_16x16x32_bf16 v[56:59], v[136:139], v[180:183], v[56:59]
	v_mfma_f32_16x16x32_bf16 v[44:47], v[128:131], v[188:191], v[44:47]
	v_mfma_f32_16x16x32_bf16 v[40:43], v[136:139], v[188:191], v[40:43]
	v_mfma_f32_16x16x32_bf16 v[28:31], v[128:131], v[196:199], v[28:31]
	v_mfma_f32_16x16x32_bf16 v[24:27], v[136:139], v[196:199], v[24:27]
	v_mfma_f32_16x16x32_bf16 v[12:15], v[128:131], v[204:207], v[12:15]
	v_mfma_f32_16x16x32_bf16 v[8:11], v[136:139], v[204:207], v[8:11]
	v_mfma_f32_16x16x32_bf16 v[60:63], v[132:135], v[184:187], v[60:63]
	v_mfma_f32_16x16x32_bf16 v[56:59], v[140:143], v[184:187], v[56:59]
	v_mfma_f32_16x16x32_bf16 v[44:47], v[132:135], v[192:195], v[44:47]
	v_mfma_f32_16x16x32_bf16 v[40:43], v[140:143], v[192:195], v[40:43]
	v_mfma_f32_16x16x32_bf16 v[28:31], v[132:135], v[200:203], v[28:31]
	v_mfma_f32_16x16x32_bf16 v[24:27], v[140:143], v[200:203], v[24:27]
	v_mfma_f32_16x16x32_bf16 v[12:15], v[132:135], v[208:211], v[12:15]
	v_mfma_f32_16x16x32_bf16 v[8:11], v[140:143], v[208:211], v[8:11]
	v_mfma_f32_16x16x32_bf16 v[52:55], v[158:161], v[180:183], v[52:55]
	v_mfma_f32_16x16x32_bf16 v[48:51], v[172:175], v[180:183], v[48:51]
	v_mfma_f32_16x16x32_bf16 v[36:39], v[158:161], v[188:191], v[36:39]
	v_mfma_f32_16x16x32_bf16 v[32:35], v[172:175], v[188:191], v[32:35]
	v_mfma_f32_16x16x32_bf16 v[20:23], v[158:161], v[196:199], v[20:23]
	v_mfma_f32_16x16x32_bf16 v[16:19], v[172:175], v[196:199], v[16:19]
	v_mfma_f32_16x16x32_bf16 v[4:7], v[158:161], v[204:207], v[4:7]
	v_mfma_f32_16x16x32_bf16 v[0:3], v[172:175], v[204:207], v[0:3]
	v_mfma_f32_16x16x32_bf16 v[52:55], v[162:165], v[184:187], v[52:55]
	v_mfma_f32_16x16x32_bf16 v[48:51], v[176:179], v[184:187], v[48:51]
	v_mfma_f32_16x16x32_bf16 v[36:39], v[162:165], v[192:195], v[36:39]
	v_mfma_f32_16x16x32_bf16 v[32:35], v[176:179], v[192:195], v[32:35]
	v_mfma_f32_16x16x32_bf16 v[20:23], v[162:165], v[200:203], v[20:23]
	v_mfma_f32_16x16x32_bf16 v[16:19], v[176:179], v[200:203], v[16:19]
	v_mfma_f32_16x16x32_bf16 v[4:7], v[162:165], v[208:211], v[4:7]
	v_mfma_f32_16x16x32_bf16 v[0:3], v[176:179], v[208:211], v[0:3]
	s_barrier
; #define PG8_STAGE(bufoff, gbase, voff) do { _Pragma("unroll") for (int _i = 0; _i < 2; ++_i) \
;     __builtin_amdgcn_global_load_lds((const unsigned*)((const char*)(gbase) + (voff)[_i]), (PG8_LAS unsigned*)(lds + (bufoff) + ldsw + _i * 8192), 16, 0, 0); } while (0)
; #define PG8_LDA(dst, b, h) do { _Pragma("unroll") for (int m = 0; m < 4; ++m) _Pragma("unroll") for (int k = 0; k < 2; ++k) dst[m][k] = *(const PG8_LAS bf16x8*)(lds + PG8_SA(b, h) + aoff + m * 2048 + k * 1024); } while (0)
; #define PG8_LDB(dst, b, h) do { _Pragma("unroll") for (int n = 0; n < 2; ++n) _Pragma("unroll") for (int k = 0; k < 2; ++k) dst[n][k] = *(const PG8_LAS bf16x8*)(lds + PG8_SB(b, h) + boff + n * 2048 + k * 1024); } while (0)
; #define PG8_MMA(ai, bj, At, Bt) do { __builtin_amdgcn_s_setprio(1); _Pragma("unroll") for (int m = 0; m < 4; ++m) _Pragma("unroll") for (int n = 0; n < 2; ++n) _Pragma("unroll") for (int k = 0; k < 2; ++k) \
;     acc[ai][bj][m][n] = __builtin_amdgcn_mfma_f32_16x16x32_bf16(Bt[n][k], At[m][k], acc[ai][bj][m][n], 0, 0, 0); __builtin_amdgcn_s_setprio(0); } while (0)
; #define PG8_WAIT_V(n) asm volatile("s_waitcnt vmcnt(" #n ")" ::: "memory")
; #define PG8_WAIT_L(n) asm volatile("s_waitcnt lgkmcnt(" #n ")" ::: "memory")
; #define PG8_BAR __builtin_amdgcn_s_barrier()
; #define PG8_SCHED __builtin_amdgcn_sched_barrier(0)
; template <class Epi, class Sched>
; DI void gemm_phase(PG8_LAS unsigned char* lds, const Gemm g, const Sched& S, const Epi& E) {
;     ...
;       PG8_LDB(B0, 1, 0); PG8_LDB(B1, 1, 1); PG8_SCHED; PG8_LDA(At, 1, 0); PG8_STAGE(PG8_SA(0, 1), a2 + hstepA, voffA);
;       PG8_WAIT_V(8); PG8_WAIT_L(0); PG8_BAR; PG8_MMA(0, 0, At, B0); PG8_MMA(0, 1, At, B1); PG8_BAR; PG8_SCHED;
;       PG8_LDA(At, 1, 1); PG8_STAGE(PG8_SB(1, 0), b3, voffB); PG8_STAGE(PG8_SB(1, 1), b3 + hstepB, voffB); PG8_STAGE(PG8_SA(1, 0), a3, voffA);
	s_add_i32 s33, s41, 0x110
	v_add_u32_e32 v140, s33, v166
	ds_read_b128 v[128:131], v140
	ds_read_b128 v[132:135], v140 offset:1024
	ds_read_b128 v[136:139], v140 offset:2048
	ds_read_b128 v[140:143], v140 offset:3072
	ds_read_b128 v[158:161], v171
	ds_read_b128 v[162:165], v171 offset:1024
	ds_read_b128 v[172:175], v171 offset:2048
	ds_read_b128 v[176:179], v171 offset:3072
	s_add_u32 s16, s34, 0x40000
	s_addc_u32 s17, s35, 0
	s_mov_b32 m0, s37
	v_lshl_add_u64 v[222:223], s[16:17], 0, v[144:145]
	ds_read_b128 v[180:183], v169 offset:32768
	ds_read_b128 v[184:187], v169 offset:33792
	ds_read_b128 v[188:191], v169 offset:34816
	ds_read_b128 v[192:195], v169 offset:35840
	ds_read_b128 v[196:199], v169 offset:36864
	ds_read_b128 v[200:203], v169 offset:37888
	ds_read_b128 v[204:207], v169 offset:38912
	ds_read_b128 v[208:211], v169 offset:39936
	global_load_lds_dwordx4 v[222:223], off
	v_lshl_add_u64 v[222:223], s[16:17], 0, v[148:149]
	s_mov_b32 m0, s38
	s_nop 0
	global_load_lds_dwordx4 v[222:223], off
	s_waitcnt vmcnt(8)
	s_waitcnt lgkmcnt(0)
	s_barrier
	s_waitcnt lgkmcnt(0)
	v_mfma_f32_16x16x32_bf16 v[124:127], v[128:131], v[180:183], v[124:127]
	v_mfma_f32_16x16x32_bf16 v[120:123], v[136:139], v[180:183], v[120:123]
	v_mfma_f32_16x16x32_bf16 v[108:111], v[128:131], v[188:191], v[108:111]
	v_mfma_f32_16x16x32_bf16 v[104:107], v[136:139], v[188:191], v[104:107]
	v_mfma_f32_16x16x32_bf16 v[92:95], v[128:131], v[196:199], v[92:95]
	v_mfma_f32_16x16x32_bf16 v[88:91], v[136:139], v[196:199], v[88:91]
	v_mfma_f32_16x16x32_bf16 v[76:79], v[128:131], v[204:207], v[76:79]
	v_mfma_f32_16x16x32_bf16 v[72:75], v[136:139], v[204:207], v[72:75]
	v_mfma_f32_16x16x32_bf16 v[124:127], v[132:135], v[184:187], v[124:127]
	v_mfma_f32_16x16x32_bf16 v[120:123], v[140:143], v[184:187], v[120:123]
	v_mfma_f32_16x16x32_bf16 v[108:111], v[132:135], v[192:195], v[108:111]
	v_mfma_f32_16x16x32_bf16 v[104:107], v[140:143], v[192:195], v[104:107]
	v_mfma_f32_16x16x32_bf16 v[92:95], v[132:135], v[200:203], v[92:95]
	v_mfma_f32_16x16x32_bf16 v[88:91], v[140:143], v[200:203], v[88:91]
	v_mfma_f32_16x16x32_bf16 v[76:79], v[132:135], v[208:211], v[76:79]
	v_mfma_f32_16x16x32_bf16 v[72:75], v[140:143], v[208:211], v[72:75]
	v_mfma_f32_16x16x32_bf16 v[116:119], v[158:161], v[180:183], v[116:119]
	v_mfma_f32_16x16x32_bf16 v[112:115], v[172:175], v[180:183], v[112:115]
	v_mfma_f32_16x16x32_bf16 v[100:103], v[158:161], v[188:191], v[100:103]
	v_mfma_f32_16x16x32_bf16 v[96:99], v[172:175], v[188:191], v[96:99]
	v_mfma_f32_16x16x32_bf16 v[84:87], v[158:161], v[196:199], v[84:87]
	v_mfma_f32_16x16x32_bf16 v[80:83], v[172:175], v[196:199], v[80:83]
	v_mfma_f32_16x16x32_bf16 v[68:71], v[158:161], v[204:207], v[68:71]
	v_mfma_f32_16x16x32_bf16 v[64:67], v[172:175], v[204:207], v[64:67]
	v_mfma_f32_16x16x32_bf16 v[116:119], v[162:165], v[184:187], v[116:119]
	v_mfma_f32_16x16x32_bf16 v[112:115], v[176:179], v[184:187], v[112:115]
	v_mfma_f32_16x16x32_bf16 v[100:103], v[162:165], v[192:195], v[100:103]
	v_mfma_f32_16x16x32_bf16 v[96:99], v[176:179], v[192:195], v[96:99]
	v_mfma_f32_16x16x32_bf16 v[84:87], v[162:165], v[200:203], v[84:87]
	v_mfma_f32_16x16x32_bf16 v[80:83], v[176:179], v[200:203], v[80:83]
	v_mfma_f32_16x16x32_bf16 v[68:71], v[162:165], v[208:211], v[68:71]
	v_mfma_f32_16x16x32_bf16 v[64:67], v[176:179], v[208:211], v[64:67]
	s_barrier
	s_add_i32 s16, s33, s2
	v_lshl_add_u64 v[214:215], v[214:215], 0, s[8:9]
	s_mov_b32 m0, s16
	ds_read_b128 v[180:183], v169 offset:49152
	ds_read_b128 v[184:187], v169 offset:50176
	ds_read_b128 v[188:191], v169 offset:51200
	ds_read_b128 v[192:195], v169 offset:52224
	ds_read_b128 v[196:199], v169 offset:53248
	ds_read_b128 v[200:203], v169 offset:54272
	ds_read_b128 v[204:207], v169 offset:55296
	ds_read_b128 v[208:211], v169 offset:56320
	global_load_lds_dwordx4 v[214:215], off
	s_add_i32 m0, s16, 0x2000
	s_add_u32 s16, s30, 0x40080
	v_lshl_add_u64 v[214:215], v[216:217], 0, s[8:9]
	s_addc_u32 s17, s31, 0
	s_add_i32 s30, s65, s2
	global_load_lds_dwordx4 v[214:215], off
	v_lshl_add_u64 v[214:215], s[16:17], 0, v[146:147]
	s_mov_b32 m0, s30
	s_nop 0
	global_load_lds_dwordx4 v[214:215], off
	v_lshl_add_u64 v[214:215], s[16:17], 0, v[150:151]
	s_add_i32 m0, s30, 0x2000
	s_nop 0
	global_load_lds_dwordx4 v[214:215], off
	v_lshl_add_u64 v[214:215], v[218:219], 0, s[8:9]
	s_mov_b32 m0, s4
	s_nop 0
	global_load_lds_dwordx4 v[214:215], off
	v_lshl_add_u64 v[214:215], v[220:221], 0, s[8:9]
	s_mov_b32 m0, s5
	s_nop 0
	global_load_lds_dwordx4 v[214:215], off
	s_waitcnt vmcnt(8)
	s_waitcnt lgkmcnt(0)
	s_barrier
; #define PG8_MMA(ai, bj, At, Bt) do { __builtin_amdgcn_s_setprio(1); _Pragma("unroll") for (int m = 0; m < 4; ++m) _Pragma("unroll") for (int n = 0; n < 2; ++n) _Pragma("unroll") for (int k = 0; k < 2; ++k) \
;     acc[ai][bj][m][n] = __builtin_amdgcn_mfma_f32_16x16x32_bf16(Bt[n][k], At[m][k], acc[ai][bj][m][n], 0, 0, 0); __builtin_amdgcn_s_setprio(0); } while (0)
; #define PG8_WAIT_V(n) asm volatile("s_waitcnt vmcnt(" #n ")" ::: "memory")
; #define PG8_WAIT_L(n) asm volatile("s_waitcnt lgkmcnt(" #n ")" ::: "memory")
; #define PG8_BAR __builtin_amdgcn_s_barrier()
; #define PG8_SCHED __builtin_amdgcn_sched_barrier(0)
;   DI void operator()(const f32x4 (&acc)[2][2][4][2], const Unit& u, int wr, int wc, int fr, int fq) const {
;     ...
;     RES_LD(0)
; template <class Epi, class Sched>
; DI void gemm_phase(PG8_LAS unsigned char* lds, const Gemm g, const Sched& S, const Epi& E) {
;     ...
;       PG8_WAIT_V(8); PG8_WAIT_L(0); PG8_BAR; PG8_MMA(1, 0, At, B0); PG8_MMA(1, 1, At, B1); PG8_BAR; PG8_SCHED;
;     }
;     if (wr == 0) PG8_BAR;
	s_waitcnt lgkmcnt(0)
	v_mfma_f32_16x16x32_bf16 v[60:63], v[128:131], v[180:183], v[60:63]
	v_mfma_f32_16x16x32_bf16 v[56:59], v[136:139], v[180:183], v[56:59]
	v_mfma_f32_16x16x32_bf16 v[44:47], v[128:131], v[188:191], v[44:47]
	v_mfma_f32_16x16x32_bf16 v[40:43], v[136:139], v[188:191], v[40:43]
	v_mfma_f32_16x16x32_bf16 v[28:31], v[128:131], v[196:199], v[28:31]
	v_mfma_f32_16x16x32_bf16 v[24:27], v[136:139], v[196:199], v[24:27]
	v_mfma_f32_16x16x32_bf16 v[12:15], v[128:131], v[204:207], v[12:15]
	v_mfma_f32_16x16x32_bf16 v[8:11], v[136:139], v[204:207], v[8:11]
	v_mfma_f32_16x16x32_bf16 v[60:63], v[132:135], v[184:187], v[60:63]
	v_mfma_f32_16x16x32_bf16 v[56:59], v[140:143], v[184:187], v[56:59]
	v_mfma_f32_16x16x32_bf16 v[44:47], v[132:135], v[192:195], v[44:47]
	v_mfma_f32_16x16x32_bf16 v[40:43], v[140:143], v[192:195], v[40:43]
	v_mfma_f32_16x16x32_bf16 v[28:31], v[132:135], v[200:203], v[28:31]
	v_mfma_f32_16x16x32_bf16 v[24:27], v[140:143], v[200:203], v[24:27]
	v_mfma_f32_16x16x32_bf16 v[12:15], v[132:135], v[208:211], v[12:15]
	v_mfma_f32_16x16x32_bf16 v[8:11], v[140:143], v[208:211], v[8:11]
	v_mfma_f32_16x16x32_bf16 v[52:55], v[158:161], v[180:183], v[52:55]
	v_mfma_f32_16x16x32_bf16 v[48:51], v[172:175], v[180:183], v[48:51]
	v_mfma_f32_16x16x32_bf16 v[36:39], v[158:161], v[188:191], v[36:39]
	v_mfma_f32_16x16x32_bf16 v[32:35], v[172:175], v[188:191], v[32:35]
	v_mfma_f32_16x16x32_bf16 v[20:23], v[158:161], v[196:199], v[20:23]
	v_mfma_f32_16x16x32_bf16 v[16:19], v[172:175], v[196:199], v[16:19]
	v_mfma_f32_16x16x32_bf16 v[4:7], v[158:161], v[204:207], v[4:7]
	v_mfma_f32_16x16x32_bf16 v[0:3], v[172:175], v[204:207], v[0:3]
	v_mfma_f32_16x16x32_bf16 v[52:55], v[162:165], v[184:187], v[52:55]
	v_mfma_f32_16x16x32_bf16 v[48:51], v[176:179], v[184:187], v[48:51]
	v_mfma_f32_16x16x32_bf16 v[36:39], v[162:165], v[192:195], v[36:39]
	v_mfma_f32_16x16x32_bf16 v[32:35], v[176:179], v[192:195], v[32:35]
	v_mfma_f32_16x16x32_bf16 v[20:23], v[162:165], v[200:203], v[20:23]
	v_mfma_f32_16x16x32_bf16 v[16:19], v[176:179], v[200:203], v[16:19]
	v_mfma_f32_16x16x32_bf16 v[4:7], v[162:165], v[208:211], v[4:7]
	v_mfma_f32_16x16x32_bf16 v[0:3], v[176:179], v[208:211], v[0:3]
	s_barrier
	s_add_i32 s70, s70, 2
	s_add_u32 s28, s28, 0x100
	s_addc_u32 s29, s29, 0
	s_add_u32 s68, s68, 0x100
	s_addc_u32 s69, s69, 0
	s_cmp_gt_u32 s70, 13
	s_cbranch_scc0 .LBB0_563
	v_lshl_add_u32 v164, s26, 8, v153
	v_ashrrev_i32_e32 v165, 31, v164
	s_lshl_b32 s16, s12, 8
	v_lshlrev_b64 v[128:129], 10, v[164:165]
	s_ashr_i32 s17, s16, 31
	v_lshl_add_u64 v[186:187], v[128:129], 0, s[16:17]
	v_or_b32_e32 v186, v186, v152
	v_lshl_add_u64 v[162:163], v[186:187], 2, s[44:45]
	s_mov_b64 s[16:17], 0x10000
	v_add_co_u32_e32 v130, vcc, s39, v162
	global_load_dwordx4 v[158:161], v[162:163], off offset:16
	global_load_dwordx4 v[174:177], v[162:163], off
	global_load_dwordx4 v[178:181], v[162:163], off offset:528
	global_load_dwordx4 v[182:185], v[162:163], off offset:512
	v_lshl_add_u64 v[128:129], v[162:163], 0, s[16:17]
	v_addc_co_u32_e32 v131, vcc, 0, v163, vcc
	s_mov_b64 s[16:17], 0x10200
	global_load_dwordx4 v[140:143], v[130:131], off
	global_load_dwordx4 v[136:139], v[128:129], off offset:16
	v_lshl_add_u64 v[128:129], v[162:163], 0, s[16:17]
	global_load_dwordx4 v[132:135], v[130:131], off offset:512
	s_nop 0
	global_load_dwordx4 v[128:131], v[128:129], off offset:16
	s_and_b64 vcc, exec, s[10:11]
	s_cbranch_vccz .LBB0_566
	s_barrier

; #define PG8_STAGE(bufoff, gbase, voff) do { _Pragma("unroll") for (int _i = 0; _i < 2; ++_i) \
;     __builtin_amdgcn_global_load_lds((const unsigned*)((const char*)(gbase) + (voff)[_i]), (PG8_LAS unsigned*)(lds + (bufoff) + ldsw + _i * 8192), 16, 0, 0); } while (0)
; #define PG8_LDA(dst, b, h) do { _Pragma("unroll") for (int m = 0; m < 4; ++m) _Pragma("unroll") for (int k = 0; k < 2; ++k) dst[m][k] = *(const PG8_LAS bf16x8*)(lds + PG8_SA(b, h) + aoff + m * 2048 + k * 1024); } while (0)
; #define PG8_LDB(dst, b, h) do { _Pragma("unroll") for (int n = 0; n < 2; ++n) _Pragma("unroll") for (int k = 0; k < 2; ++k) dst[n][k] = *(const PG8_LAS bf16x8*)(lds + PG8_SB(b, h) + boff + n * 2048 + k * 1024); } while (0)
; #define PG8_SCHED __builtin_amdgcn_sched_barrier(0)
; template <class Epi, class Sched>
; DI void gemm_phase(PG8_LAS unsigned char* lds, const Gemm g, const Sched& S, const Epi& E) {
;     ...
;   for (;;) {
;     const bool has_next = S.next(ui + 1, nxt);
;     const char* nA = has_next ? (const char*)g.A + (size_t)nxt.pm * tstepA : cA; const char* nB = has_next ? (const char*)g.Bt + (size_t)nxt.pn * tstepB : cB;
; #pragma unroll 1
;     for (int t = 0; t < nt; t += 2) {
;       const bool last = (t == nt - 2);
;       const char* a1 = cA + (size_t)(t + 1) * kstep;
;       const char* a2 = last ? nA : cA + (size_t)(t + 2) * kstep; const char* b2 = last ? nB : cB + (size_t)(t + 2) * kstep;
;       const char* a3 = a2 + kstep; const char* b3 = b2 + kstep;
;       PG8_LDB(B0, 0, 0); PG8_LDB(B1, 0, 1); PG8_SCHED; PG8_LDA(At, 0, 0); PG8_STAGE(PG8_SA(1, 1), a1 + hstepA, voffA);
;     ...
; #pragma unroll
;     for (int a = 0; a < 2; ++a)
; #pragma unroll
;       for (int b = 0; b < 2; ++b)
; #pragma unroll
;         for (int m = 0; m < 4; ++m)
; #pragma unroll
;           for (int n = 0; n < 2; ++n) acc[a][b][m][n] = (f32x4){0.f, 0.f, 0.f, 0.f};
.LBB0_646:
	s_ashr_i32 s25, s24, 31
	s_lshl_b64 s[16:17], s[24:25], 19
	s_add_u32 s28, s50, s16
	s_addc_u32 s29, s51, s17
	s_and_b64 s[16:17], s[26:27], exec
	s_cselect_b32 s1, s29, s7
	s_cselect_b32 s25, s28, s6
	s_ashr_i32 s23, s22, 31
	s_lshl_b64 s[16:17], s[22:23], 19
	s_add_u32 s30, s94, s16
	s_addc_u32 s31, s95, s17
	s_and_b64 s[16:17], s[26:27], exec
	s_cselect_b32 s23, s31, s35
	s_cselect_b32 s65, s30, s34
	s_add_u32 s6, s6, 0x40080
	s_addc_u32 s7, s7, 0
	s_add_u32 s66, s34, 0x100
	v_mov_b32_e32 v0, 0
	s_addc_u32 s67, s35, 0
	s_mov_b32 s68, -2
	v_mov_b32_e32 v1, v0
	v_mov_b32_e32 v2, v0
	v_mov_b32_e32 v3, v0
	v_mov_b32_e32 v4, v0
	v_mov_b32_e32 v5, v0
	v_mov_b32_e32 v6, v0
	v_mov_b32_e32 v7, v0
	v_mov_b32_e32 v16, v0
	v_mov_b32_e32 v17, v0
	v_mov_b32_e32 v18, v0
	v_mov_b32_e32 v19, v0
	v_mov_b32_e32 v20, v0
	v_mov_b32_e32 v21, v0
	v_mov_b32_e32 v22, v0
	v_mov_b32_e32 v23, v0
	v_mov_b32_e32 v32, v0
	v_mov_b32_e32 v33, v0
	v_mov_b32_e32 v34, v0
	v_mov_b32_e32 v35, v0
	v_mov_b32_e32 v36, v0
	v_mov_b32_e32 v37, v0
	v_mov_b32_e32 v38, v0
	v_mov_b32_e32 v39, v0
	v_mov_b32_e32 v48, v0
	v_mov_b32_e32 v49, v0
	v_mov_b32_e32 v50, v0
	v_mov_b32_e32 v51, v0
	v_mov_b32_e32 v52, v0
	v_mov_b32_e32 v53, v0
	v_mov_b32_e32 v54, v0
	v_mov_b32_e32 v55, v0
	v_mov_b32_e32 v8, v0
	v_mov_b32_e32 v9, v0
	v_mov_b32_e32 v10, v0
	v_mov_b32_e32 v11, v0
	v_mov_b32_e32 v12, v0
	v_mov_b32_e32 v13, v0
	v_mov_b32_e32 v14, v0
	v_mov_b32_e32 v15, v0
	v_mov_b32_e32 v24, v0
	v_mov_b32_e32 v25, v0
	v_mov_b32_e32 v26, v0
	v_mov_b32_e32 v27, v0
	v_mov_b32_e32 v28, v0
	v_mov_b32_e32 v29, v0
	v_mov_b32_e32 v30, v0
	v_mov_b32_e32 v31, v0
	v_mov_b32_e32 v40, v0
	v_mov_b32_e32 v41, v0
	v_mov_b32_e32 v42, v0
	v_mov_b32_e32 v43, v0
	v_mov_b32_e32 v44, v0
	v_mov_b32_e32 v45, v0
	v_mov_b32_e32 v46, v0
	v_mov_b32_e32 v47, v0
	v_mov_b32_e32 v56, v0
	v_mov_b32_e32 v57, v0
	v_mov_b32_e32 v58, v0
	v_mov_b32_e32 v59, v0
	v_mov_b32_e32 v60, v0
	v_mov_b32_e32 v61, v0
	v_mov_b32_e32 v62, v0
	v_mov_b32_e32 v63, v0
	v_mov_b32_e32 v64, v0
	v_mov_b32_e32 v65, v0
	v_mov_b32_e32 v66, v0
	v_mov_b32_e32 v67, v0
	v_mov_b32_e32 v68, v0
	v_mov_b32_e32 v69, v0
	v_mov_b32_e32 v70, v0
	v_mov_b32_e32 v71, v0
	v_mov_b32_e32 v80, v0
	v_mov_b32_e32 v81, v0
	v_mov_b32_e32 v82, v0
	v_mov_b32_e32 v83, v0
	v_mov_b32_e32 v84, v0
	v_mov_b32_e32 v85, v0
	v_mov_b32_e32 v86, v0
	v_mov_b32_e32 v87, v0
	v_mov_b32_e32 v96, v0
	v_mov_b32_e32 v97, v0
	v_mov_b32_e32 v98, v0
	v_mov_b32_e32 v99, v0
	v_mov_b32_e32 v100, v0
	v_mov_b32_e32 v101, v0
	v_mov_b32_e32 v102, v0
	v_mov_b32_e32 v103, v0
	s_waitcnt vmcnt(0)
	v_mov_b32_e32 v112, v0
	v_mov_b32_e32 v113, v0
	v_mov_b32_e32 v114, v0
	v_mov_b32_e32 v115, v0
	v_mov_b32_e32 v116, v0
	v_mov_b32_e32 v117, v0
	v_mov_b32_e32 v118, v0
	v_mov_b32_e32 v119, v0
	v_mov_b32_e32 v72, v0
	v_mov_b32_e32 v73, v0
	v_mov_b32_e32 v74, v0
	v_mov_b32_e32 v75, v0
	v_mov_b32_e32 v76, v0
	v_mov_b32_e32 v77, v0
	v_mov_b32_e32 v78, v0
	v_mov_b32_e32 v79, v0
	v_mov_b32_e32 v88, v0
	v_mov_b32_e32 v89, v0
	v_mov_b32_e32 v90, v0
	v_mov_b32_e32 v91, v0
	v_mov_b32_e32 v92, v0
	v_mov_b32_e32 v93, v0
	v_mov_b32_e32 v94, v0
	v_mov_b32_e32 v95, v0
	v_mov_b32_e32 v104, v0
	v_mov_b32_e32 v105, v0
	v_mov_b32_e32 v106, v0
	v_mov_b32_e32 v107, v0
	v_mov_b32_e32 v108, v0
	v_mov_b32_e32 v109, v0
	v_mov_b32_e32 v110, v0
	v_mov_b32_e32 v111, v0
	v_mov_b32_e32 v120, v0
	v_mov_b32_e32 v121, v0
	v_mov_b32_e32 v122, v0
	v_mov_b32_e32 v123, v0
	v_mov_b32_e32 v124, v0
	v_mov_b32_e32 v125, v0
	v_mov_b32_e32 v126, v0
	v_mov_b32_e32 v127, v0
	v_readfirstlane_b32 s100, v212
	s_nop 3
	s_lshr_b32 s100, s100, 8
	s_cmp_lg_u32 s100, 0
	s_cbranch_scc0 .Lgp_2
	s_setprio 1
.Lgp_2:
.LBB0_647:
	ds_read_b128 v[144:147], v157
	ds_read_b128 v[148:151], v157 offset:1024
	ds_read_b128 v[174:177], v157 offset:2048
	ds_read_b128 v[178:181], v157 offset:3072
	ds_read_b128 v[182:185], v161
	ds_read_b128 v[186:189], v161 offset:1024
	ds_read_b128 v[190:193], v161 offset:2048
	ds_read_b128 v[194:197], v161 offset:3072
	s_add_u32 s16, s6, 0xfffc0080
	s_addc_u32 s17, s7, -1
	s_cmp_eq_u32 s68, 12
	s_cselect_b32 s37, s1, s17
	s_cselect_b32 s36, s25, s16
	s_cselect_b32 s35, s23, s67
	s_cselect_b32 s34, s65, s66
	v_lshl_add_u64 v[154:155], s[6:7], 0, v[140:141]
	s_add_i32 m0, s21, 0xc000
	ds_read_b128 v[198:201], v165
	ds_read_b128 v[202:205], v165 offset:1024
	ds_read_b128 v[206:209], v165 offset:2048
	ds_read_b128 v[214:217], v165 offset:3072
	ds_read_b128 v[218:221], v165 offset:4096
	ds_read_b128 v[222:225], v165 offset:5120
	ds_read_b128 v[226:229], v165 offset:6144
	ds_read_b128 v[230:233], v165 offset:7168
	global_load_lds_dwordx4 v[154:155], off
	v_lshl_add_u64 v[154:155], s[6:7], 0, v[142:143]
	s_add_i32 m0, s21, 0xe000
	s_nop 0
	global_load_lds_dwordx4 v[154:155], off
	s_waitcnt vmcnt(8)
	s_waitcnt lgkmcnt(0)
	s_barrier
; #define PG8_STAGE(bufoff, gbase, voff) do { _Pragma("unroll") for (int _i = 0; _i < 2; ++_i) \
;     __builtin_amdgcn_global_load_lds((const unsigned*)((const char*)(gbase) + (voff)[_i]), (PG8_LAS unsigned*)(lds + (bufoff) + ldsw + _i * 8192), 16, 0, 0); } while (0)
; #define PG8_LDA(dst, b, h) do { _Pragma("unroll") for (int m = 0; m < 4; ++m) _Pragma("unroll") for (int k = 0; k < 2; ++k) dst[m][k] = *(const PG8_LAS bf16x8*)(lds + PG8_SA(b, h) + aoff + m * 2048 + k * 1024); } while (0)
; #define PG8_MMA(ai, bj, At, Bt) do { __builtin_amdgcn_s_setprio(1); _Pragma("unroll") for (int m = 0; m < 4; ++m) _Pragma("unroll") for (int n = 0; n < 2; ++n) _Pragma("unroll") for (int k = 0; k < 2; ++k) \
;     acc[ai][bj][m][n] = __builtin_amdgcn_mfma_f32_16x16x32_bf16(Bt[n][k], At[m][k], acc[ai][bj][m][n], 0, 0, 0); __builtin_amdgcn_s_setprio(0); } while (0)
; #define PG8_WAIT_V(n) asm volatile("s_waitcnt vmcnt(" #n ")" ::: "memory")
; #define PG8_WAIT_L(n) asm volatile("s_waitcnt lgkmcnt(" #n ")" ::: "memory")
; #define PG8_BAR __builtin_amdgcn_s_barrier()
; #define PG8_SCHED __builtin_amdgcn_sched_barrier(0)
; template <class Epi, class Sched>
; DI void gemm_phase(PG8_LAS unsigned char* lds, const Gemm g, const Sched& S, const Epi& E) {
;     ...
;       PG8_WAIT_V(8); PG8_WAIT_L(0); PG8_BAR; PG8_MMA(0, 0, At, B0); PG8_MMA(0, 1, At, B1); PG8_BAR; PG8_SCHED;
;       PG8_LDA(At, 0, 1); PG8_STAGE(PG8_SB(0, 0), b2, voffB); PG8_STAGE(PG8_SB(0, 1), b2 + hstepB, voffB); PG8_STAGE(PG8_SA(0, 0), a2, voffA);
;       PG8_WAIT_V(8); PG8_WAIT_L(0); PG8_BAR; PG8_MMA(1, 0, At, B0); PG8_MMA(1, 1, At, B1); PG8_BAR; PG8_SCHED;
	s_waitcnt lgkmcnt(0)
	v_mfma_f32_16x16x32_bf16 v[124:127], v[144:147], v[198:201], v[124:127]
	v_mfma_f32_16x16x32_bf16 v[120:123], v[174:177], v[198:201], v[120:123]
	v_mfma_f32_16x16x32_bf16 v[108:111], v[144:147], v[206:209], v[108:111]
	v_mfma_f32_16x16x32_bf16 v[104:107], v[174:177], v[206:209], v[104:107]
	v_mfma_f32_16x16x32_bf16 v[92:95], v[144:147], v[218:221], v[92:95]
	v_mfma_f32_16x16x32_bf16 v[88:91], v[174:177], v[218:221], v[88:91]
	v_mfma_f32_16x16x32_bf16 v[76:79], v[144:147], v[226:229], v[76:79]
	v_mfma_f32_16x16x32_bf16 v[72:75], v[174:177], v[226:229], v[72:75]
	v_mfma_f32_16x16x32_bf16 v[124:127], v[148:151], v[202:205], v[124:127]
	v_mfma_f32_16x16x32_bf16 v[120:123], v[178:181], v[202:205], v[120:123]
	v_mfma_f32_16x16x32_bf16 v[108:111], v[148:151], v[214:217], v[108:111]
	v_mfma_f32_16x16x32_bf16 v[104:107], v[178:181], v[214:217], v[104:107]
	v_mfma_f32_16x16x32_bf16 v[92:95], v[148:151], v[222:225], v[92:95]
	v_mfma_f32_16x16x32_bf16 v[88:91], v[178:181], v[222:225], v[88:91]
	v_mfma_f32_16x16x32_bf16 v[76:79], v[148:151], v[230:233], v[76:79]
	v_mfma_f32_16x16x32_bf16 v[72:75], v[178:181], v[230:233], v[72:75]
	v_mfma_f32_16x16x32_bf16 v[116:119], v[182:185], v[198:201], v[116:119]
	v_mfma_f32_16x16x32_bf16 v[112:115], v[190:193], v[198:201], v[112:115]
	v_mfma_f32_16x16x32_bf16 v[100:103], v[182:185], v[206:209], v[100:103]
	v_mfma_f32_16x16x32_bf16 v[96:99], v[190:193], v[206:209], v[96:99]
	v_mfma_f32_16x16x32_bf16 v[84:87], v[182:185], v[218:221], v[84:87]
	v_mfma_f32_16x16x32_bf16 v[80:83], v[190:193], v[218:221], v[80:83]
	v_mfma_f32_16x16x32_bf16 v[68:71], v[182:185], v[226:229], v[68:71]
	v_mfma_f32_16x16x32_bf16 v[64:67], v[190:193], v[226:229], v[64:67]
	v_mfma_f32_16x16x32_bf16 v[116:119], v[186:189], v[202:205], v[116:119]
	v_mfma_f32_16x16x32_bf16 v[112:115], v[194:197], v[202:205], v[112:115]
	v_mfma_f32_16x16x32_bf16 v[100:103], v[186:189], v[214:217], v[100:103]
	v_mfma_f32_16x16x32_bf16 v[96:99], v[194:197], v[214:217], v[96:99]
	v_mfma_f32_16x16x32_bf16 v[84:87], v[186:189], v[222:225], v[84:87]
	v_mfma_f32_16x16x32_bf16 v[80:83], v[194:197], v[222:225], v[80:83]
	v_mfma_f32_16x16x32_bf16 v[68:71], v[186:189], v[230:233], v[68:71]
	v_mfma_f32_16x16x32_bf16 v[64:67], v[194:197], v[230:233], v[64:67]
	s_barrier
	s_add_i32 s16, s39, s2
	v_lshl_add_u64 v[154:155], s[34:35], 0, v[132:133]
	s_mov_b32 m0, s16
	ds_read_b128 v[198:201], v165 offset:16384
	ds_read_b128 v[202:205], v165 offset:17408
	ds_read_b128 v[206:209], v165 offset:18432
	ds_read_b128 v[214:217], v165 offset:19456
	ds_read_b128 v[218:221], v165 offset:20480
	ds_read_b128 v[222:225], v165 offset:21504
	ds_read_b128 v[226:229], v165 offset:22528
	ds_read_b128 v[230:233], v165 offset:23552
	global_load_lds_dwordx4 v[154:155], off
	s_add_i32 m0, s16, 0x2000
	s_add_u32 s16, s34, 0x40000
	v_lshl_add_u64 v[158:159], s[34:35], 0, v[128:129]
	s_addc_u32 s17, s35, 0
	s_add_i32 s33, s40, s2
	global_load_lds_dwordx4 v[158:159], off
	v_lshl_add_u64 v[162:163], s[16:17], 0, v[132:133]
	s_mov_b32 m0, s33
	v_lshl_add_u64 v[166:167], s[36:37], 0, v[130:131]
	global_load_lds_dwordx4 v[162:163], off
	v_lshl_add_u64 v[162:163], s[16:17], 0, v[128:129]
	s_add_i32 m0, s33, 0x2000
	s_nop 0
	global_load_lds_dwordx4 v[162:163], off
	v_lshl_add_u64 v[162:163], s[36:37], 0, v[134:135]
	s_mov_b32 m0, s21
	s_nop 0
	global_load_lds_dwordx4 v[162:163], off
	s_mov_b32 m0, s4
	s_nop 0
	global_load_lds_dwordx4 v[166:167], off
	s_waitcnt vmcnt(8)
	s_waitcnt lgkmcnt(0)
	s_barrier
	s_waitcnt lgkmcnt(0)
	v_mfma_f32_16x16x32_bf16 v[60:63], v[144:147], v[198:201], v[60:63]
	v_mfma_f32_16x16x32_bf16 v[56:59], v[174:177], v[198:201], v[56:59]
	v_mfma_f32_16x16x32_bf16 v[44:47], v[144:147], v[206:209], v[44:47]
	v_mfma_f32_16x16x32_bf16 v[40:43], v[174:177], v[206:209], v[40:43]
	v_mfma_f32_16x16x32_bf16 v[28:31], v[144:147], v[218:221], v[28:31]
	v_mfma_f32_16x16x32_bf16 v[24:27], v[174:177], v[218:221], v[24:27]
	v_mfma_f32_16x16x32_bf16 v[12:15], v[144:147], v[226:229], v[12:15]
	v_mfma_f32_16x16x32_bf16 v[8:11], v[174:177], v[226:229], v[8:11]
	v_mfma_f32_16x16x32_bf16 v[60:63], v[148:151], v[202:205], v[60:63]
	v_mfma_f32_16x16x32_bf16 v[56:59], v[178:181], v[202:205], v[56:59]
	v_mfma_f32_16x16x32_bf16 v[44:47], v[148:151], v[214:217], v[44:47]
	v_mfma_f32_16x16x32_bf16 v[40:43], v[178:181], v[214:217], v[40:43]
	v_mfma_f32_16x16x32_bf16 v[28:31], v[148:151], v[222:225], v[28:31]
	v_mfma_f32_16x16x32_bf16 v[24:27], v[178:181], v[222:225], v[24:27]
	v_mfma_f32_16x16x32_bf16 v[12:15], v[148:151], v[230:233], v[12:15]
	v_mfma_f32_16x16x32_bf16 v[8:11], v[178:181], v[230:233], v[8:11]
	v_mfma_f32_16x16x32_bf16 v[52:55], v[182:185], v[198:201], v[52:55]
	v_mfma_f32_16x16x32_bf16 v[48:51], v[190:193], v[198:201], v[48:51]
	v_mfma_f32_16x16x32_bf16 v[36:39], v[182:185], v[206:209], v[36:39]
	v_mfma_f32_16x16x32_bf16 v[32:35], v[190:193], v[206:209], v[32:35]
	v_mfma_f32_16x16x32_bf16 v[20:23], v[182:185], v[218:221], v[20:23]
	v_mfma_f32_16x16x32_bf16 v[16:19], v[190:193], v[218:221], v[16:19]
	v_mfma_f32_16x16x32_bf16 v[4:7], v[182:185], v[226:229], v[4:7]
	v_mfma_f32_16x16x32_bf16 v[0:3], v[190:193], v[226:229], v[0:3]
	v_mfma_f32_16x16x32_bf16 v[52:55], v[186:189], v[202:205], v[52:55]
	v_mfma_f32_16x16x32_bf16 v[48:51], v[194:197], v[202:205], v[48:51]
	v_mfma_f32_16x16x32_bf16 v[36:39], v[186:189], v[214:217], v[36:39]
	v_mfma_f32_16x16x32_bf16 v[32:35], v[194:197], v[214:217], v[32:35]
	v_mfma_f32_16x16x32_bf16 v[20:23], v[186:189], v[222:225], v[20:23]
	v_mfma_f32_16x16x32_bf16 v[16:19], v[194:197], v[222:225], v[16:19]
	v_mfma_f32_16x16x32_bf16 v[4:7], v[186:189], v[230:233], v[4:7]
	v_mfma_f32_16x16x32_bf16 v[0:3], v[194:197], v[230:233], v[0:3]
	s_barrier
; #define PG8_STAGE(bufoff, gbase, voff) do { _Pragma("unroll") for (int _i = 0; _i < 2; ++_i) \
;     __builtin_amdgcn_global_load_lds((const unsigned*)((const char*)(gbase) + (voff)[_i]), (PG8_LAS unsigned*)(lds + (bufoff) + ldsw + _i * 8192), 16, 0, 0); } while (0)
; #define PG8_LDA(dst, b, h) do { _Pragma("unroll") for (int m = 0; m < 4; ++m) _Pragma("unroll") for (int k = 0; k < 2; ++k) dst[m][k] = *(const PG8_LAS bf16x8*)(lds + PG8_SA(b, h) + aoff + m * 2048 + k * 1024); } while (0)
; #define PG8_LDB(dst, b, h) do { _Pragma("unroll") for (int n = 0; n < 2; ++n) _Pragma("unroll") for (int k = 0; k < 2; ++k) dst[n][k] = *(const PG8_LAS bf16x8*)(lds + PG8_SB(b, h) + boff + n * 2048 + k * 1024); } while (0)
; #define PG8_MMA(ai, bj, At, Bt) do { __builtin_amdgcn_s_setprio(1); _Pragma("unroll") for (int m = 0; m < 4; ++m) _Pragma("unroll") for (int n = 0; n < 2; ++n) _Pragma("unroll") for (int k = 0; k < 2; ++k) \
;     acc[ai][bj][m][n] = __builtin_amdgcn_mfma_f32_16x16x32_bf16(Bt[n][k], At[m][k], acc[ai][bj][m][n], 0, 0, 0); __builtin_amdgcn_s_setprio(0); } while (0)
; #define PG8_WAIT_V(n) asm volatile("s_waitcnt vmcnt(" #n ")" ::: "memory")
; #define PG8_WAIT_L(n) asm volatile("s_waitcnt lgkmcnt(" #n ")" ::: "memory")
; #define PG8_BAR __builtin_amdgcn_s_barrier()
; #define PG8_SCHED __builtin_amdgcn_sched_barrier(0)
; template <class Epi, class Sched>
; DI void gemm_phase(PG8_LAS unsigned char* lds, const Gemm g, const Sched& S, const Epi& E) {
;     ...
;       PG8_LDB(B0, 1, 0); PG8_LDB(B1, 1, 1); PG8_SCHED; PG8_LDA(At, 1, 0); PG8_STAGE(PG8_SA(0, 1), a2 + hstepA, voffA);
;       PG8_WAIT_V(8); PG8_WAIT_L(0); PG8_BAR; PG8_MMA(0, 0, At, B0); PG8_MMA(0, 1, At, B1); PG8_BAR; PG8_SCHED;
;       PG8_LDA(At, 1, 1); PG8_STAGE(PG8_SB(1, 0), b3, voffB); PG8_STAGE(PG8_SB(1, 1), b3 + hstepB, voffB); PG8_STAGE(PG8_SA(1, 0), a3, voffA);
	ds_read_b128 v[144:147], v171
	ds_read_b128 v[148:151], v171 offset:1024
	ds_read_b128 v[174:177], v171 offset:2048
	ds_read_b128 v[178:181], v171 offset:3072
	ds_read_b128 v[182:185], v173
	ds_read_b128 v[186:189], v173 offset:1024
	ds_read_b128 v[190:193], v173 offset:2048
	ds_read_b128 v[194:197], v173 offset:3072
	s_add_u32 s16, s36, 0x40000
	s_addc_u32 s17, s37, 0
	s_mov_b32 m0, s5
	v_lshl_add_u64 v[210:211], s[16:17], 0, v[134:135]
	ds_read_b128 v[198:201], v165 offset:32768
	ds_read_b128 v[202:205], v165 offset:33792
	ds_read_b128 v[206:209], v165 offset:34816
	ds_read_b128 v[214:217], v165 offset:35840
	ds_read_b128 v[218:221], v165 offset:36864
	ds_read_b128 v[222:225], v165 offset:37888
	ds_read_b128 v[226:229], v165 offset:38912
	ds_read_b128 v[230:233], v165 offset:39936
	global_load_lds_dwordx4 v[210:211], off
	v_lshl_add_u64 v[210:211], s[16:17], 0, v[130:131]
	s_mov_b32 m0, s18
	s_nop 0
	global_load_lds_dwordx4 v[210:211], off
	s_waitcnt vmcnt(8)
	s_waitcnt lgkmcnt(0)
	s_barrier
	s_waitcnt lgkmcnt(0)
	v_mfma_f32_16x16x32_bf16 v[124:127], v[144:147], v[198:201], v[124:127]
	v_mfma_f32_16x16x32_bf16 v[120:123], v[174:177], v[198:201], v[120:123]
	v_mfma_f32_16x16x32_bf16 v[108:111], v[144:147], v[206:209], v[108:111]
	v_mfma_f32_16x16x32_bf16 v[104:107], v[174:177], v[206:209], v[104:107]
	v_mfma_f32_16x16x32_bf16 v[92:95], v[144:147], v[218:221], v[92:95]
	v_mfma_f32_16x16x32_bf16 v[88:91], v[174:177], v[218:221], v[88:91]
	v_mfma_f32_16x16x32_bf16 v[76:79], v[144:147], v[226:229], v[76:79]
	v_mfma_f32_16x16x32_bf16 v[72:75], v[174:177], v[226:229], v[72:75]
	v_mfma_f32_16x16x32_bf16 v[124:127], v[148:151], v[202:205], v[124:127]
	v_mfma_f32_16x16x32_bf16 v[120:123], v[178:181], v[202:205], v[120:123]
	v_mfma_f32_16x16x32_bf16 v[108:111], v[148:151], v[214:217], v[108:111]
	v_mfma_f32_16x16x32_bf16 v[104:107], v[178:181], v[214:217], v[104:107]
	v_mfma_f32_16x16x32_bf16 v[92:95], v[148:151], v[222:225], v[92:95]
	v_mfma_f32_16x16x32_bf16 v[88:91], v[178:181], v[222:225], v[88:91]
	v_mfma_f32_16x16x32_bf16 v[76:79], v[148:151], v[230:233], v[76:79]
	v_mfma_f32_16x16x32_bf16 v[72:75], v[178:181], v[230:233], v[72:75]
	v_mfma_f32_16x16x32_bf16 v[116:119], v[182:185], v[198:201], v[116:119]
	v_mfma_f32_16x16x32_bf16 v[112:115], v[190:193], v[198:201], v[112:115]
	v_mfma_f32_16x16x32_bf16 v[100:103], v[182:185], v[206:209], v[100:103]
	v_mfma_f32_16x16x32_bf16 v[96:99], v[190:193], v[206:209], v[96:99]
	v_mfma_f32_16x16x32_bf16 v[84:87], v[182:185], v[218:221], v[84:87]
	v_mfma_f32_16x16x32_bf16 v[80:83], v[190:193], v[218:221], v[80:83]
	v_mfma_f32_16x16x32_bf16 v[68:71], v[182:185], v[226:229], v[68:71]
	v_mfma_f32_16x16x32_bf16 v[64:67], v[190:193], v[226:229], v[64:67]
	v_mfma_f32_16x16x32_bf16 v[116:119], v[186:189], v[202:205], v[116:119]
	v_mfma_f32_16x16x32_bf16 v[112:115], v[194:197], v[202:205], v[112:115]
	v_mfma_f32_16x16x32_bf16 v[100:103], v[186:189], v[214:217], v[100:103]
	v_mfma_f32_16x16x32_bf16 v[96:99], v[194:197], v[214:217], v[96:99]
	v_mfma_f32_16x16x32_bf16 v[84:87], v[186:189], v[222:225], v[84:87]
	v_mfma_f32_16x16x32_bf16 v[80:83], v[194:197], v[222:225], v[80:83]
	v_mfma_f32_16x16x32_bf16 v[68:71], v[186:189], v[230:233], v[68:71]
	v_mfma_f32_16x16x32_bf16 v[64:67], v[194:197], v[230:233], v[64:67]
	s_barrier
	s_add_i32 s16, s45, s2
	v_lshl_add_u64 v[154:155], v[154:155], 0, s[10:11]
	s_mov_b32 m0, s16
	ds_read_b128 v[198:201], v165 offset:49152
	ds_read_b128 v[202:205], v165 offset:50176
	ds_read_b128 v[206:209], v165 offset:51200
	ds_read_b128 v[214:217], v165 offset:52224
	ds_read_b128 v[218:221], v165 offset:53248
	ds_read_b128 v[222:225], v165 offset:54272
	ds_read_b128 v[226:229], v165 offset:55296
	ds_read_b128 v[230:233], v165 offset:56320
	global_load_lds_dwordx4 v[154:155], off
	s_add_i32 m0, s16, 0x2000
	s_add_u32 s16, s34, 0x40080
	v_lshl_add_u64 v[154:155], v[158:159], 0, s[10:11]
	s_addc_u32 s17, s35, 0
	s_add_i32 s33, s53, s2
	global_load_lds_dwordx4 v[154:155], off
	v_lshl_add_u64 v[154:155], s[16:17], 0, v[132:133]
	s_mov_b32 m0, s33
	s_nop 0
	global_load_lds_dwordx4 v[154:155], off
	v_lshl_add_u64 v[154:155], s[16:17], 0, v[128:129]
	s_add_i32 m0, s33, 0x2000
	s_nop 0
	global_load_lds_dwordx4 v[154:155], off
	v_lshl_add_u64 v[154:155], v[162:163], 0, s[10:11]
	s_mov_b32 m0, s19
	s_nop 0
	global_load_lds_dwordx4 v[154:155], off
	v_lshl_add_u64 v[154:155], v[166:167], 0, s[10:11]
	s_mov_b32 m0, s38
	s_nop 0
	global_load_lds_dwordx4 v[154:155], off
	s_waitcnt vmcnt(8)
	s_waitcnt lgkmcnt(0)
	s_barrier
; #define PG8_MMA(ai, bj, At, Bt) do { __builtin_amdgcn_s_setprio(1); _Pragma("unroll") for (int m = 0; m < 4; ++m) _Pragma("unroll") for (int n = 0; n < 2; ++n) _Pragma("unroll") for (int k = 0; k < 2; ++k) \
;     acc[ai][bj][m][n] = __builtin_amdgcn_mfma_f32_16x16x32_bf16(Bt[n][k], At[m][k], acc[ai][bj][m][n], 0, 0, 0); __builtin_amdgcn_s_setprio(0); } while (0)
; #define PG8_WAIT_V(n) asm volatile("s_waitcnt vmcnt(" #n ")" ::: "memory")
; #define PG8_WAIT_L(n) asm volatile("s_waitcnt lgkmcnt(" #n ")" ::: "memory")
; #define PG8_BAR __builtin_amdgcn_s_barrier()
; #define PG8_SCHED __builtin_amdgcn_sched_barrier(0)
; DI void rows_rstd(float (&rs)[2][4], const float* ps, const Unit& u, int wr, int fr, int fq, int p_lo, int p_hi, float inv_dim) {
;   f32x4 pv[2][4];
; #pragma unroll
;   for (int ai = 0; ai < 2; ++ai)
; #pragma unroll
;     for (int m = 0; m < 4; ++m) pv[ai][m] = *(const f32x4*)(ps + (size_t)(u.pm * BM + ai * HALF + wr * 64 + m * 16 + fr) * 16 + 4 * fq);
; template <class Epi, class Sched>
; DI void gemm_phase(PG8_LAS unsigned char* lds, const Gemm g, const Sched& S, const Epi& E) {
;     ...
;       PG8_WAIT_V(8); PG8_WAIT_L(0); PG8_BAR; PG8_MMA(1, 0, At, B0); PG8_MMA(1, 1, At, B1); PG8_BAR; PG8_SCHED;
;     }
;     if (wr == 0) PG8_BAR;
	s_waitcnt lgkmcnt(0)
	v_mfma_f32_16x16x32_bf16 v[60:63], v[144:147], v[198:201], v[60:63]
	v_mfma_f32_16x16x32_bf16 v[56:59], v[174:177], v[198:201], v[56:59]
	v_mfma_f32_16x16x32_bf16 v[44:47], v[144:147], v[206:209], v[44:47]
	v_mfma_f32_16x16x32_bf16 v[40:43], v[174:177], v[206:209], v[40:43]
	v_mfma_f32_16x16x32_bf16 v[28:31], v[144:147], v[218:221], v[28:31]
	v_mfma_f32_16x16x32_bf16 v[24:27], v[174:177], v[218:221], v[24:27]
	v_mfma_f32_16x16x32_bf16 v[12:15], v[144:147], v[226:229], v[12:15]
	v_mfma_f32_16x16x32_bf16 v[8:11], v[174:177], v[226:229], v[8:11]
	v_mfma_f32_16x16x32_bf16 v[60:63], v[148:151], v[202:205], v[60:63]
	v_mfma_f32_16x16x32_bf16 v[56:59], v[178:181], v[202:205], v[56:59]
	v_mfma_f32_16x16x32_bf16 v[44:47], v[148:151], v[214:217], v[44:47]
	v_mfma_f32_16x16x32_bf16 v[40:43], v[178:181], v[214:217], v[40:43]
	v_mfma_f32_16x16x32_bf16 v[28:31], v[148:151], v[222:225], v[28:31]
	v_mfma_f32_16x16x32_bf16 v[24:27], v[178:181], v[222:225], v[24:27]
	v_mfma_f32_16x16x32_bf16 v[12:15], v[148:151], v[230:233], v[12:15]
	v_mfma_f32_16x16x32_bf16 v[8:11], v[178:181], v[230:233], v[8:11]
	v_mfma_f32_16x16x32_bf16 v[52:55], v[182:185], v[198:201], v[52:55]
	v_mfma_f32_16x16x32_bf16 v[48:51], v[190:193], v[198:201], v[48:51]
	v_mfma_f32_16x16x32_bf16 v[36:39], v[182:185], v[206:209], v[36:39]
	v_mfma_f32_16x16x32_bf16 v[32:35], v[190:193], v[206:209], v[32:35]
	v_mfma_f32_16x16x32_bf16 v[20:23], v[182:185], v[218:221], v[20:23]
	v_mfma_f32_16x16x32_bf16 v[16:19], v[190:193], v[218:221], v[16:19]
	v_mfma_f32_16x16x32_bf16 v[4:7], v[182:185], v[226:229], v[4:7]
	v_mfma_f32_16x16x32_bf16 v[0:3], v[190:193], v[226:229], v[0:3]
	v_mfma_f32_16x16x32_bf16 v[52:55], v[186:189], v[202:205], v[52:55]
	v_mfma_f32_16x16x32_bf16 v[48:51], v[194:197], v[202:205], v[48:51]
	v_mfma_f32_16x16x32_bf16 v[36:39], v[186:189], v[214:217], v[36:39]
	v_mfma_f32_16x16x32_bf16 v[32:35], v[194:197], v[214:217], v[32:35]
	v_mfma_f32_16x16x32_bf16 v[20:23], v[186:189], v[222:225], v[20:23]
	v_mfma_f32_16x16x32_bf16 v[16:19], v[194:197], v[222:225], v[16:19]
	v_mfma_f32_16x16x32_bf16 v[4:7], v[186:189], v[230:233], v[4:7]
	v_mfma_f32_16x16x32_bf16 v[0:3], v[194:197], v[230:233], v[0:3]
	s_barrier
	s_add_i32 s68, s68, 2
	s_add_u32 s6, s6, 0x100
	s_addc_u32 s7, s7, 0
	s_add_u32 s66, s66, 0x100
	s_addc_u32 s67, s67, 0
	s_cmp_gt_u32 s68, 13
	s_cbranch_scc0 .LBB0_647
	v_lshl_add_u32 v166, s0, 8, v153
	v_or_b32_e32 v162, 16, v166
	v_ashrrev_i32_e32 v167, 31, v166
	v_ashrrev_i32_e32 v163, 31, v162
	v_or_b32_e32 v158, 32, v166
	v_lshlrev_b64 v[146:147], 6, v[166:167]
	v_lshlrev_b64 v[144:145], 6, v[162:163]
	v_ashrrev_i32_e32 v159, 31, v158
	v_lshl_add_u64 v[146:147], v[138:139], 0, v[146:147]
	v_or_b32_e32 v154, 48, v166
	v_lshl_add_u64 v[144:145], v[138:139], 0, v[144:145]
	global_load_dwordx4 v[174:177], v[146:147], off
	v_lshlrev_b64 v[146:147], 6, v[158:159]
	v_ashrrev_i32_e32 v155, 31, v154
	v_lshl_add_u64 v[146:147], v[138:139], 0, v[146:147]
	global_load_dwordx4 v[178:181], v[144:145], off
	global_load_dwordx4 v[182:185], v[146:147], off
	v_lshlrev_b64 v[144:145], 6, v[154:155]
	v_lshl_add_u64 v[144:145], v[138:139], 0, v[144:145]
	global_load_dwordx4 v[186:189], v[144:145], off
	v_add_u32_e32 v150, 0x80, v166
	v_ashrrev_i32_e32 v151, 31, v150
	v_lshlrev_b64 v[144:145], 6, v[150:151]
	v_add_u32_e32 v148, 0x90, v166
	v_lshl_add_u64 v[144:145], v[138:139], 0, v[144:145]
	v_ashrrev_i32_e32 v149, 31, v148
	global_load_dwordx4 v[190:193], v[144:145], off
	v_lshlrev_b64 v[144:145], 6, v[148:149]
	v_lshl_add_u64 v[144:145], v[138:139], 0, v[144:145]
	global_load_dwordx4 v[194:197], v[144:145], off
	v_and_b32_e32 v145, 64, v169
	v_add_u32_e32 v144, 0xb0, v166
	v_add_u32_e32 v146, 0xa0, v166
	v_add_u32_e32 v152, 64, v145
	v_ashrrev_i32_e32 v145, 31, v144
	v_ashrrev_i32_e32 v147, 31, v146
	v_lshlrev_b64 v[198:199], 6, v[144:145]
	v_lshlrev_b64 v[200:201], 6, v[146:147]
	v_lshl_add_u64 v[198:199], v[138:139], 0, v[198:199]
	v_lshl_add_u64 v[202:203], v[138:139], 0, v[200:201]
	global_load_dwordx4 v[198:201], v[198:199], off
	s_nop 0
	global_load_dwordx4 v[202:205], v[202:203], off
	s_and_b64 vcc, exec, s[12:13]
	s_cbranch_vccz .LBB0_650
	s_barrier

; #define PG8_STAGE(bufoff, gbase, voff) do { _Pragma("unroll") for (int _i = 0; _i < 2; ++_i) \
;     __builtin_amdgcn_global_load_lds((const unsigned*)((const char*)(gbase) + (voff)[_i]), (PG8_LAS unsigned*)(lds + (bufoff) + ldsw + _i * 8192), 16, 0, 0); } while (0)
; #define PG8_LDA(dst, b, h) do { _Pragma("unroll") for (int m = 0; m < 4; ++m) _Pragma("unroll") for (int k = 0; k < 2; ++k) dst[m][k] = *(const PG8_LAS bf16x8*)(lds + PG8_SA(b, h) + aoff + m * 2048 + k * 1024); } while (0)
; #define PG8_LDB(dst, b, h) do { _Pragma("unroll") for (int n = 0; n < 2; ++n) _Pragma("unroll") for (int k = 0; k < 2; ++k) dst[n][k] = *(const PG8_LAS bf16x8*)(lds + PG8_SB(b, h) + boff + n * 2048 + k * 1024); } while (0)
; #define PG8_MMA(ai, bj, At, Bt) do { __builtin_amdgcn_s_setprio(1); _Pragma("unroll") for (int m = 0; m < 4; ++m) _Pragma("unroll") for (int n = 0; n < 2; ++n) _Pragma("unroll") for (int k = 0; k < 2; ++k) \
;     acc[ai][bj][m][n] = __builtin_amdgcn_mfma_f32_16x16x32_bf16(Bt[n][k], At[m][k], acc[ai][bj][m][n], 0, 0, 0); __builtin_amdgcn_s_setprio(0); } while (0)
; #define PG8_WAIT_V(n) asm volatile("s_waitcnt vmcnt(" #n ")" ::: "memory")
; template <class Epi, class Sched>
; DI void gemm_phase(PG8_LAS unsigned char* lds, const Gemm g, const Sched& S, const Epi& E) {
;     ...
;   for (;;) {
;     const bool has_next = S.next(ui + 1, nxt);
;     const char* nA = has_next ? (const char*)g.A + (size_t)nxt.pm * tstepA : cA; const char* nB = has_next ? (const char*)g.Bt + (size_t)nxt.pn * tstepB : cB;
; #pragma unroll 1
;     for (int t = 0; t < nt; t += 2) {
;       const bool last = (t == nt - 2);
;       const char* a1 = cA + (size_t)(t + 1) * kstep;
;       const char* a2 = last ? nA : cA + (size_t)(t + 2) * kstep; const char* b2 = last ? nB : cB + (size_t)(t + 2) * kstep;
;       const char* a3 = a2 + kstep; const char* b3 = b2 + kstep;
;       PG8_LDB(B0, 0, 0); PG8_LDB(B1, 0, 1); PG8_SCHED; PG8_LDA(At, 0, 0); PG8_STAGE(PG8_SA(1, 1), a1 + hstepA, voffA);
;       PG8_WAIT_V(8); PG8_WAIT_L(0); PG8_BAR; PG8_MMA(0, 0, At, B0); PG8_MMA(0, 1, At, B1); PG8_BAR; PG8_SCHED;
;     ...
; #pragma unroll
;     for (int a = 0; a < 2; ++a)
; #pragma unroll
;       for (int b = 0; b < 2; ++b)
; #pragma unroll
;         for (int m = 0; m < 4; ++m)
; #pragma unroll
;           for (int n = 0; n < 2; ++n) acc[a][b][m][n] = (f32x4){0.f, 0.f, 0.f, 0.f};
.LBB0_720:
	s_add_u32 s55, s26, 0x100
	v_mov_b32_e32 v0, 0
	s_addc_u32 s64, s27, 0
	s_mov_b32 s65, -2
	s_waitcnt lgkmcnt(0)
	v_mov_b32_e32 v1, v0
	v_mov_b32_e32 v2, v0
	v_mov_b32_e32 v3, v0
	v_mov_b32_e32 v4, v0
	v_mov_b32_e32 v5, v0
	v_mov_b32_e32 v6, v0
	v_mov_b32_e32 v7, v0
	v_mov_b32_e32 v16, v0
	v_mov_b32_e32 v17, v0
	v_mov_b32_e32 v18, v0
	v_mov_b32_e32 v19, v0
	v_mov_b32_e32 v20, v0
	v_mov_b32_e32 v21, v0
	v_mov_b32_e32 v22, v0
	v_mov_b32_e32 v23, v0
	v_mov_b32_e32 v32, v0
	v_mov_b32_e32 v33, v0
	v_mov_b32_e32 v34, v0
	v_mov_b32_e32 v35, v0
	v_mov_b32_e32 v36, v0
	v_mov_b32_e32 v37, v0
	v_mov_b32_e32 v38, v0
	v_mov_b32_e32 v39, v0
	v_mov_b32_e32 v48, v0
	v_mov_b32_e32 v49, v0
	v_mov_b32_e32 v50, v0
	v_mov_b32_e32 v51, v0
	v_mov_b32_e32 v52, v0
	v_mov_b32_e32 v53, v0
	v_mov_b32_e32 v54, v0
	v_mov_b32_e32 v55, v0
	v_mov_b32_e32 v8, v0
	v_mov_b32_e32 v9, v0
	v_mov_b32_e32 v10, v0
	v_mov_b32_e32 v11, v0
	v_mov_b32_e32 v12, v0
	v_mov_b32_e32 v13, v0
	v_mov_b32_e32 v14, v0
	v_mov_b32_e32 v15, v0
	v_mov_b32_e32 v24, v0
	v_mov_b32_e32 v25, v0
	v_mov_b32_e32 v26, v0
	v_mov_b32_e32 v27, v0
	v_mov_b32_e32 v28, v0
	v_mov_b32_e32 v29, v0
	v_mov_b32_e32 v30, v0
	v_mov_b32_e32 v31, v0
	v_mov_b32_e32 v40, v0
	v_mov_b32_e32 v41, v0
	v_mov_b32_e32 v42, v0
	v_mov_b32_e32 v43, v0
	v_mov_b32_e32 v44, v0
	v_mov_b32_e32 v45, v0
	v_mov_b32_e32 v46, v0
	v_mov_b32_e32 v47, v0
	v_mov_b32_e32 v56, v0
	v_mov_b32_e32 v57, v0
	v_mov_b32_e32 v58, v0
	v_mov_b32_e32 v59, v0
	v_mov_b32_e32 v60, v0
	v_mov_b32_e32 v61, v0
	v_mov_b32_e32 v62, v0
	v_mov_b32_e32 v63, v0
	v_mov_b32_e32 v64, v0
	v_mov_b32_e32 v65, v0
	v_mov_b32_e32 v66, v0
	v_mov_b32_e32 v67, v0
	v_mov_b32_e32 v68, v0
	v_mov_b32_e32 v69, v0
	v_mov_b32_e32 v70, v0
	v_mov_b32_e32 v71, v0
	v_mov_b32_e32 v80, v0
	v_mov_b32_e32 v81, v0
	v_mov_b32_e32 v82, v0
	v_mov_b32_e32 v83, v0
	v_mov_b32_e32 v84, v0
	v_mov_b32_e32 v85, v0
	v_mov_b32_e32 v86, v0
	v_mov_b32_e32 v87, v0
	v_mov_b32_e32 v96, v0
	v_mov_b32_e32 v97, v0
	v_mov_b32_e32 v98, v0
	v_mov_b32_e32 v99, v0
	v_mov_b32_e32 v100, v0
	v_mov_b32_e32 v101, v0
	v_mov_b32_e32 v102, v0
	v_mov_b32_e32 v103, v0
	s_waitcnt vmcnt(0)
	v_mov_b32_e32 v112, v0
	v_mov_b32_e32 v113, v0
	v_mov_b32_e32 v114, v0
	v_mov_b32_e32 v115, v0
	v_mov_b32_e32 v116, v0
	v_mov_b32_e32 v117, v0
	v_mov_b32_e32 v118, v0
	v_mov_b32_e32 v119, v0
	v_mov_b32_e32 v72, v0
	v_mov_b32_e32 v73, v0
	v_mov_b32_e32 v74, v0
	v_mov_b32_e32 v75, v0
	v_mov_b32_e32 v76, v0
	v_mov_b32_e32 v77, v0
	v_mov_b32_e32 v78, v0
	v_mov_b32_e32 v79, v0
	v_mov_b32_e32 v88, v0
	v_mov_b32_e32 v89, v0
	v_mov_b32_e32 v90, v0
	v_mov_b32_e32 v91, v0
	v_mov_b32_e32 v92, v0
	v_mov_b32_e32 v93, v0
	v_mov_b32_e32 v94, v0
	v_mov_b32_e32 v95, v0
	v_mov_b32_e32 v104, v0
	v_mov_b32_e32 v105, v0
	v_mov_b32_e32 v106, v0
	v_mov_b32_e32 v107, v0
	v_mov_b32_e32 v108, v0
	v_mov_b32_e32 v109, v0
	v_mov_b32_e32 v110, v0
	v_mov_b32_e32 v111, v0
	v_mov_b32_e32 v120, v0
	v_mov_b32_e32 v121, v0
	v_mov_b32_e32 v122, v0
	v_mov_b32_e32 v123, v0
	v_mov_b32_e32 v124, v0
	v_mov_b32_e32 v125, v0
	v_mov_b32_e32 v126, v0
	v_mov_b32_e32 v127, v0
	v_readfirstlane_b32 s100, v212
	s_nop 3
	s_lshr_b32 s100, s100, 8
	s_cmp_lg_u32 s100, 0
	s_cbranch_scc0 .Lgp_3
	s_setprio 1
.Lgp_3:
.LBB0_721:
	ds_read_b128 v[128:131], v156
	ds_read_b128 v[132:135], v156 offset:1024
	ds_read_b128 v[150:153], v156 offset:2048
	ds_read_b128 v[162:165], v156 offset:3072
	ds_read_b128 v[166:169], v157
	ds_read_b128 v[170:173], v157 offset:1024
	ds_read_b128 v[174:177], v157 offset:2048
	ds_read_b128 v[178:181], v157 offset:3072
	s_add_u32 s26, s24, 0x100
	s_addc_u32 s27, s25, 0
	s_cmp_eq_u32 s65, 40
	s_cselect_b32 s31, s21, s27
	s_cselect_b32 s30, s20, s26
	s_cselect_b32 s29, s23, s64
	s_cselect_b32 s28, s22, s55
	v_lshl_add_u64 v[210:211], s[24:25], 0, v[146:147]
	s_add_i32 m0, s3, 0xc000
	ds_read_b128 v[182:185], v158
	ds_read_b128 v[186:189], v158 offset:1024
	ds_read_b128 v[190:193], v158 offset:2048
	ds_read_b128 v[194:197], v158 offset:3072
	ds_read_b128 v[198:201], v158 offset:4096
	ds_read_b128 v[202:205], v158 offset:5120
	ds_read_b128 v[206:209], v158 offset:6144
	ds_read_b128 v[214:217], v158 offset:7168
	global_load_lds_dwordx4 v[210:211], off
	v_lshl_add_u64 v[210:211], s[24:25], 0, v[148:149]
	s_add_i32 m0, s3, 0xe000
	s_nop 0
	global_load_lds_dwordx4 v[210:211], off
	s_waitcnt vmcnt(8)
	s_waitcnt lgkmcnt(0)
	s_barrier
	s_waitcnt lgkmcnt(0)
	v_mfma_f32_16x16x32_bf16 v[124:127], v[128:131], v[182:185], v[124:127]
	v_mfma_f32_16x16x32_bf16 v[120:123], v[150:153], v[182:185], v[120:123]
	v_mfma_f32_16x16x32_bf16 v[108:111], v[128:131], v[190:193], v[108:111]
	v_mfma_f32_16x16x32_bf16 v[104:107], v[150:153], v[190:193], v[104:107]
	v_mfma_f32_16x16x32_bf16 v[92:95], v[128:131], v[198:201], v[92:95]
	v_mfma_f32_16x16x32_bf16 v[88:91], v[150:153], v[198:201], v[88:91]
	v_mfma_f32_16x16x32_bf16 v[76:79], v[128:131], v[206:209], v[76:79]
	v_mfma_f32_16x16x32_bf16 v[72:75], v[150:153], v[206:209], v[72:75]
	v_mfma_f32_16x16x32_bf16 v[124:127], v[132:135], v[186:189], v[124:127]
	v_mfma_f32_16x16x32_bf16 v[120:123], v[162:165], v[186:189], v[120:123]
	v_mfma_f32_16x16x32_bf16 v[108:111], v[132:135], v[194:197], v[108:111]
	v_mfma_f32_16x16x32_bf16 v[104:107], v[162:165], v[194:197], v[104:107]
	v_mfma_f32_16x16x32_bf16 v[92:95], v[132:135], v[202:205], v[92:95]
	v_mfma_f32_16x16x32_bf16 v[88:91], v[162:165], v[202:205], v[88:91]
	v_mfma_f32_16x16x32_bf16 v[76:79], v[132:135], v[214:217], v[76:79]
	v_mfma_f32_16x16x32_bf16 v[72:75], v[162:165], v[214:217], v[72:75]
	v_mfma_f32_16x16x32_bf16 v[116:119], v[166:169], v[182:185], v[116:119]
	v_mfma_f32_16x16x32_bf16 v[112:115], v[174:177], v[182:185], v[112:115]
	v_mfma_f32_16x16x32_bf16 v[100:103], v[166:169], v[190:193], v[100:103]
	v_mfma_f32_16x16x32_bf16 v[96:99], v[174:177], v[190:193], v[96:99]
	v_mfma_f32_16x16x32_bf16 v[84:87], v[166:169], v[198:201], v[84:87]
	v_mfma_f32_16x16x32_bf16 v[80:83], v[174:177], v[198:201], v[80:83]
	v_mfma_f32_16x16x32_bf16 v[68:71], v[166:169], v[206:209], v[68:71]
	v_mfma_f32_16x16x32_bf16 v[64:67], v[174:177], v[206:209], v[64:67]
	v_mfma_f32_16x16x32_bf16 v[116:119], v[170:173], v[186:189], v[116:119]
	v_mfma_f32_16x16x32_bf16 v[112:115], v[178:181], v[186:189], v[112:115]
	v_mfma_f32_16x16x32_bf16 v[100:103], v[170:173], v[194:197], v[100:103]
	v_mfma_f32_16x16x32_bf16 v[96:99], v[178:181], v[194:197], v[96:99]
	v_mfma_f32_16x16x32_bf16 v[84:87], v[170:173], v[202:205], v[84:87]
	v_mfma_f32_16x16x32_bf16 v[80:83], v[178:181], v[202:205], v[80:83]
	v_mfma_f32_16x16x32_bf16 v[68:71], v[170:173], v[214:217], v[68:71]
	v_mfma_f32_16x16x32_bf16 v[64:67], v[178:181], v[214:217], v[64:67]
	s_barrier
; #define PG8_STAGE(bufoff, gbase, voff) do { _Pragma("unroll") for (int _i = 0; _i < 2; ++_i) \
;     __builtin_amdgcn_global_load_lds((const unsigned*)((const char*)(gbase) + (voff)[_i]), (PG8_LAS unsigned*)(lds + (bufoff) + ldsw + _i * 8192), 16, 0, 0); } while (0)
; #define PG8_LDA(dst, b, h) do { _Pragma("unroll") for (int m = 0; m < 4; ++m) _Pragma("unroll") for (int k = 0; k < 2; ++k) dst[m][k] = *(const PG8_LAS bf16x8*)(lds + PG8_SA(b, h) + aoff + m * 2048 + k * 1024); } while (0)
; #define PG8_LDB(dst, b, h) do { _Pragma("unroll") for (int n = 0; n < 2; ++n) _Pragma("unroll") for (int k = 0; k < 2; ++k) dst[n][k] = *(const PG8_LAS bf16x8*)(lds + PG8_SB(b, h) + boff + n * 2048 + k * 1024); } while (0)
; #define PG8_MMA(ai, bj, At, Bt) do { __builtin_amdgcn_s_setprio(1); _Pragma("unroll") for (int m = 0; m < 4; ++m) _Pragma("unroll") for (int n = 0; n < 2; ++n) _Pragma("unroll") for (int k = 0; k < 2; ++k) \
;     acc[ai][bj][m][n] = __builtin_amdgcn_mfma_f32_16x16x32_bf16(Bt[n][k], At[m][k], acc[ai][bj][m][n], 0, 0, 0); __builtin_amdgcn_s_setprio(0); } while (0)
; #define PG8_WAIT_V(n) asm volatile("s_waitcnt vmcnt(" #n ")" ::: "memory")
; #define PG8_WAIT_L(n) asm volatile("s_waitcnt lgkmcnt(" #n ")" ::: "memory")
; #define PG8_BAR __builtin_amdgcn_s_barrier()
; #define PG8_SCHED __builtin_amdgcn_sched_barrier(0)
; template <class Epi, class Sched>
; DI void gemm_phase(PG8_LAS unsigned char* lds, const Gemm g, const Sched& S, const Epi& E) {
;     ...
;       PG8_LDA(At, 0, 1); PG8_STAGE(PG8_SB(0, 0), b2, voffB); PG8_STAGE(PG8_SB(0, 1), b2 + hstepB, voffB); PG8_STAGE(PG8_SA(0, 0), a2, voffA);
;       PG8_WAIT_V(8); PG8_WAIT_L(0); PG8_BAR; PG8_MMA(1, 0, At, B0); PG8_MMA(1, 1, At, B1); PG8_BAR; PG8_SCHED;
;       PG8_LDB(B0, 1, 0); PG8_LDB(B1, 1, 1); PG8_SCHED; PG8_LDA(At, 1, 0); PG8_STAGE(PG8_SA(0, 1), a2 + hstepA, voffA);
;       PG8_WAIT_V(8); PG8_WAIT_L(0); PG8_BAR; PG8_MMA(0, 0, At, B0); PG8_MMA(0, 1, At, B1); PG8_BAR; PG8_SCHED;
	s_add_i32 s16, s37, s2
	v_lshl_add_u64 v[210:211], s[28:29], 0, v[138:139]
	s_mov_b32 m0, s16
	ds_read_b128 v[182:185], v158 offset:16384
	ds_read_b128 v[186:189], v158 offset:17408
	ds_read_b128 v[190:193], v158 offset:18432
	ds_read_b128 v[194:197], v158 offset:19456
	ds_read_b128 v[198:201], v158 offset:20480
	ds_read_b128 v[202:205], v158 offset:21504
	ds_read_b128 v[206:209], v158 offset:22528
	ds_read_b128 v[214:217], v158 offset:23552
	global_load_lds_dwordx4 v[210:211], off
	s_add_i32 m0, s16, 0x2000
	s_add_u32 s16, s28, 0xb0000
	v_lshl_add_u64 v[218:219], s[28:29], 0, v[142:143]
	s_addc_u32 s17, s29, 0
	s_add_i32 s24, s38, s2
	global_load_lds_dwordx4 v[218:219], off
	v_lshl_add_u64 v[220:221], s[16:17], 0, v[138:139]
	s_mov_b32 m0, s24
	v_lshl_add_u64 v[222:223], s[30:31], 0, v[140:141]
	global_load_lds_dwordx4 v[220:221], off
	v_lshl_add_u64 v[220:221], s[16:17], 0, v[142:143]
	s_add_i32 m0, s24, 0x2000
	s_nop 0
	global_load_lds_dwordx4 v[220:221], off
	v_lshl_add_u64 v[220:221], s[30:31], 0, v[136:137]
	s_mov_b32 m0, s3
	s_nop 0
	global_load_lds_dwordx4 v[220:221], off
	s_mov_b32 m0, s34
	s_nop 0
	global_load_lds_dwordx4 v[222:223], off
	s_waitcnt vmcnt(8)
	s_waitcnt lgkmcnt(0)
	s_barrier
	s_waitcnt lgkmcnt(0)
	v_mfma_f32_16x16x32_bf16 v[60:63], v[128:131], v[182:185], v[60:63]
	v_mfma_f32_16x16x32_bf16 v[56:59], v[150:153], v[182:185], v[56:59]
	v_mfma_f32_16x16x32_bf16 v[44:47], v[128:131], v[190:193], v[44:47]
	v_mfma_f32_16x16x32_bf16 v[40:43], v[150:153], v[190:193], v[40:43]
	v_mfma_f32_16x16x32_bf16 v[28:31], v[128:131], v[198:201], v[28:31]
	v_mfma_f32_16x16x32_bf16 v[24:27], v[150:153], v[198:201], v[24:27]
	v_mfma_f32_16x16x32_bf16 v[12:15], v[128:131], v[206:209], v[12:15]
	v_mfma_f32_16x16x32_bf16 v[8:11], v[150:153], v[206:209], v[8:11]
	v_mfma_f32_16x16x32_bf16 v[60:63], v[132:135], v[186:189], v[60:63]
	v_mfma_f32_16x16x32_bf16 v[56:59], v[162:165], v[186:189], v[56:59]
	v_mfma_f32_16x16x32_bf16 v[44:47], v[132:135], v[194:197], v[44:47]
	v_mfma_f32_16x16x32_bf16 v[40:43], v[162:165], v[194:197], v[40:43]
	v_mfma_f32_16x16x32_bf16 v[28:31], v[132:135], v[202:205], v[28:31]
	v_mfma_f32_16x16x32_bf16 v[24:27], v[162:165], v[202:205], v[24:27]
	v_mfma_f32_16x16x32_bf16 v[12:15], v[132:135], v[214:217], v[12:15]
	v_mfma_f32_16x16x32_bf16 v[8:11], v[162:165], v[214:217], v[8:11]
	v_mfma_f32_16x16x32_bf16 v[52:55], v[166:169], v[182:185], v[52:55]
	v_mfma_f32_16x16x32_bf16 v[48:51], v[174:177], v[182:185], v[48:51]
	v_mfma_f32_16x16x32_bf16 v[36:39], v[166:169], v[190:193], v[36:39]
	v_mfma_f32_16x16x32_bf16 v[32:35], v[174:177], v[190:193], v[32:35]
	v_mfma_f32_16x16x32_bf16 v[20:23], v[166:169], v[198:201], v[20:23]
	v_mfma_f32_16x16x32_bf16 v[16:19], v[174:177], v[198:201], v[16:19]
	v_mfma_f32_16x16x32_bf16 v[4:7], v[166:169], v[206:209], v[4:7]
	v_mfma_f32_16x16x32_bf16 v[0:3], v[174:177], v[206:209], v[0:3]
	v_mfma_f32_16x16x32_bf16 v[52:55], v[170:173], v[186:189], v[52:55]
	v_mfma_f32_16x16x32_bf16 v[48:51], v[178:181], v[186:189], v[48:51]
	v_mfma_f32_16x16x32_bf16 v[36:39], v[170:173], v[194:197], v[36:39]
	v_mfma_f32_16x16x32_bf16 v[32:35], v[178:181], v[194:197], v[32:35]
	v_mfma_f32_16x16x32_bf16 v[20:23], v[170:173], v[202:205], v[20:23]
	v_mfma_f32_16x16x32_bf16 v[16:19], v[178:181], v[202:205], v[16:19]
	v_mfma_f32_16x16x32_bf16 v[4:7], v[170:173], v[214:217], v[4:7]
	v_mfma_f32_16x16x32_bf16 v[0:3], v[178:181], v[214:217], v[0:3]
	s_barrier
	s_mov_b32 s16, 0x18000
	s_add_i32 s24, s16, 0x110
	v_add_u32_e32 v161, s24, v155
	ds_read_b128 v[128:131], v161
	ds_read_b128 v[132:135], v161 offset:1024
	ds_read_b128 v[150:153], v161 offset:2048
	ds_read_b128 v[162:165], v161 offset:3072
	ds_read_b128 v[166:169], v160
	ds_read_b128 v[170:173], v160 offset:1024
	ds_read_b128 v[174:177], v160 offset:2048
	ds_read_b128 v[178:181], v160 offset:3072
	s_add_u32 s16, s30, 0xb0000
	s_addc_u32 s17, s31, 0
	s_mov_b32 m0, s18
	v_lshl_add_u64 v[224:225], s[16:17], 0, v[136:137]
	ds_read_b128 v[182:185], v158 offset:32768
	ds_read_b128 v[186:189], v158 offset:33792
	ds_read_b128 v[190:193], v158 offset:34816
	ds_read_b128 v[194:197], v158 offset:35840
	ds_read_b128 v[198:201], v158 offset:36864
	ds_read_b128 v[202:205], v158 offset:37888
	ds_read_b128 v[206:209], v158 offset:38912
	ds_read_b128 v[214:217], v158 offset:39936
	global_load_lds_dwordx4 v[224:225], off
	v_lshl_add_u64 v[224:225], s[16:17], 0, v[140:141]
	s_mov_b32 m0, s19
	s_nop 0
	global_load_lds_dwordx4 v[224:225], off
	s_waitcnt vmcnt(8)
	s_waitcnt lgkmcnt(0)
	s_barrier
; #define PG8_STAGE(bufoff, gbase, voff) do { _Pragma("unroll") for (int _i = 0; _i < 2; ++_i) \
;     __builtin_amdgcn_global_load_lds((const unsigned*)((const char*)(gbase) + (voff)[_i]), (PG8_LAS unsigned*)(lds + (bufoff) + ldsw + _i * 8192), 16, 0, 0); } while (0)
; #define PG8_LDA(dst, b, h) do { _Pragma("unroll") for (int m = 0; m < 4; ++m) _Pragma("unroll") for (int k = 0; k < 2; ++k) dst[m][k] = *(const PG8_LAS bf16x8*)(lds + PG8_SA(b, h) + aoff + m * 2048 + k * 1024); } while (0)
; #define PG8_MMA(ai, bj, At, Bt) do { __builtin_amdgcn_s_setprio(1); _Pragma("unroll") for (int m = 0; m < 4; ++m) _Pragma("unroll") for (int n = 0; n < 2; ++n) _Pragma("unroll") for (int k = 0; k < 2; ++k) \
;     acc[ai][bj][m][n] = __builtin_amdgcn_mfma_f32_16x16x32_bf16(Bt[n][k], At[m][k], acc[ai][bj][m][n], 0, 0, 0); __builtin_amdgcn_s_setprio(0); } while (0)
; #define PG8_WAIT_V(n) asm volatile("s_waitcnt vmcnt(" #n ")" ::: "memory")
; #define PG8_WAIT_L(n) asm volatile("s_waitcnt lgkmcnt(" #n ")" ::: "memory")
; #define PG8_BAR __builtin_amdgcn_s_barrier()
; #define PG8_SCHED __builtin_amdgcn_sched_barrier(0)
;   DI void operator()(const f32x4 (&acc)[2][2][4][2], const Unit& u, int wr, int wc, int fr, int fq) const {
;     ...
;     RES_LD(0)
; template <class Epi, class Sched>
; DI void gemm_phase(PG8_LAS unsigned char* lds, const Gemm g, const Sched& S, const Epi& E) {
;     ...
;       PG8_WAIT_V(8); PG8_WAIT_L(0); PG8_BAR; PG8_MMA(0, 0, At, B0); PG8_MMA(0, 1, At, B1); PG8_BAR; PG8_SCHED;
;       PG8_LDA(At, 1, 1); PG8_STAGE(PG8_SB(1, 0), b3, voffB); PG8_STAGE(PG8_SB(1, 1), b3 + hstepB, voffB); PG8_STAGE(PG8_SA(1, 0), a3, voffA);
;       PG8_WAIT_V(8); PG8_WAIT_L(0); PG8_BAR; PG8_MMA(1, 0, At, B0); PG8_MMA(1, 1, At, B1); PG8_BAR; PG8_SCHED;
;     }
;     if (wr == 0) PG8_BAR;
	s_waitcnt lgkmcnt(0)
	v_mfma_f32_16x16x32_bf16 v[124:127], v[128:131], v[182:185], v[124:127]
	v_mfma_f32_16x16x32_bf16 v[120:123], v[150:153], v[182:185], v[120:123]
	v_mfma_f32_16x16x32_bf16 v[108:111], v[128:131], v[190:193], v[108:111]
	v_mfma_f32_16x16x32_bf16 v[104:107], v[150:153], v[190:193], v[104:107]
	v_mfma_f32_16x16x32_bf16 v[92:95], v[128:131], v[198:201], v[92:95]
	v_mfma_f32_16x16x32_bf16 v[88:91], v[150:153], v[198:201], v[88:91]
	v_mfma_f32_16x16x32_bf16 v[76:79], v[128:131], v[206:209], v[76:79]
	v_mfma_f32_16x16x32_bf16 v[72:75], v[150:153], v[206:209], v[72:75]
	v_mfma_f32_16x16x32_bf16 v[124:127], v[132:135], v[186:189], v[124:127]
	v_mfma_f32_16x16x32_bf16 v[120:123], v[162:165], v[186:189], v[120:123]
	v_mfma_f32_16x16x32_bf16 v[108:111], v[132:135], v[194:197], v[108:111]
	v_mfma_f32_16x16x32_bf16 v[104:107], v[162:165], v[194:197], v[104:107]
	v_mfma_f32_16x16x32_bf16 v[92:95], v[132:135], v[202:205], v[92:95]
	v_mfma_f32_16x16x32_bf16 v[88:91], v[162:165], v[202:205], v[88:91]
	v_mfma_f32_16x16x32_bf16 v[76:79], v[132:135], v[214:217], v[76:79]
	v_mfma_f32_16x16x32_bf16 v[72:75], v[162:165], v[214:217], v[72:75]
	v_mfma_f32_16x16x32_bf16 v[116:119], v[166:169], v[182:185], v[116:119]
	v_mfma_f32_16x16x32_bf16 v[112:115], v[174:177], v[182:185], v[112:115]
	v_mfma_f32_16x16x32_bf16 v[100:103], v[166:169], v[190:193], v[100:103]
	v_mfma_f32_16x16x32_bf16 v[96:99], v[174:177], v[190:193], v[96:99]
	v_mfma_f32_16x16x32_bf16 v[84:87], v[166:169], v[198:201], v[84:87]
	v_mfma_f32_16x16x32_bf16 v[80:83], v[174:177], v[198:201], v[80:83]
	v_mfma_f32_16x16x32_bf16 v[68:71], v[166:169], v[206:209], v[68:71]
	v_mfma_f32_16x16x32_bf16 v[64:67], v[174:177], v[206:209], v[64:67]
	v_mfma_f32_16x16x32_bf16 v[116:119], v[170:173], v[186:189], v[116:119]
	v_mfma_f32_16x16x32_bf16 v[112:115], v[178:181], v[186:189], v[112:115]
	v_mfma_f32_16x16x32_bf16 v[100:103], v[170:173], v[194:197], v[100:103]
	v_mfma_f32_16x16x32_bf16 v[96:99], v[178:181], v[194:197], v[96:99]
	v_mfma_f32_16x16x32_bf16 v[84:87], v[170:173], v[202:205], v[84:87]
	v_mfma_f32_16x16x32_bf16 v[80:83], v[178:181], v[202:205], v[80:83]
	v_mfma_f32_16x16x32_bf16 v[68:71], v[170:173], v[214:217], v[68:71]
	v_mfma_f32_16x16x32_bf16 v[64:67], v[178:181], v[214:217], v[64:67]
	s_barrier
	s_add_i32 s16, s24, s2
	v_lshl_add_u64 v[210:211], v[210:211], 0, s[10:11]
	s_mov_b32 m0, s16
	ds_read_b128 v[182:185], v158 offset:49152
	ds_read_b128 v[186:189], v158 offset:50176
	ds_read_b128 v[190:193], v158 offset:51200
	ds_read_b128 v[194:197], v158 offset:52224
	ds_read_b128 v[198:201], v158 offset:53248
	ds_read_b128 v[202:205], v158 offset:54272
	ds_read_b128 v[206:209], v158 offset:55296
	ds_read_b128 v[214:217], v158 offset:56320
	global_load_lds_dwordx4 v[210:211], off
	s_add_i32 m0, s16, 0x2000
	s_add_u32 s16, s28, 0xb0080
	v_lshl_add_u64 v[210:211], v[218:219], 0, s[10:11]
	s_addc_u32 s17, s29, 0
	s_add_i32 s24, s39, s2
	global_load_lds_dwordx4 v[210:211], off
	v_lshl_add_u64 v[210:211], s[16:17], 0, v[138:139]
	s_mov_b32 m0, s24
	s_nop 0
	global_load_lds_dwordx4 v[210:211], off
	v_lshl_add_u64 v[210:211], s[16:17], 0, v[142:143]
	s_add_i32 m0, s24, 0x2000
	s_nop 0
	global_load_lds_dwordx4 v[210:211], off
	v_lshl_add_u64 v[210:211], v[220:221], 0, s[10:11]
	s_mov_b32 m0, s5
	s_nop 0
	global_load_lds_dwordx4 v[210:211], off
	v_lshl_add_u64 v[210:211], v[222:223], 0, s[10:11]
	s_mov_b32 m0, s35
	s_nop 0
	global_load_lds_dwordx4 v[210:211], off
	s_waitcnt vmcnt(8)
	s_waitcnt lgkmcnt(0)
	s_barrier
	s_waitcnt lgkmcnt(0)
	v_mfma_f32_16x16x32_bf16 v[60:63], v[128:131], v[182:185], v[60:63]
	v_mfma_f32_16x16x32_bf16 v[56:59], v[150:153], v[182:185], v[56:59]
	v_mfma_f32_16x16x32_bf16 v[44:47], v[128:131], v[190:193], v[44:47]
	v_mfma_f32_16x16x32_bf16 v[40:43], v[150:153], v[190:193], v[40:43]
	v_mfma_f32_16x16x32_bf16 v[28:31], v[128:131], v[198:201], v[28:31]
	v_mfma_f32_16x16x32_bf16 v[24:27], v[150:153], v[198:201], v[24:27]
	v_mfma_f32_16x16x32_bf16 v[12:15], v[128:131], v[206:209], v[12:15]
	v_mfma_f32_16x16x32_bf16 v[8:11], v[150:153], v[206:209], v[8:11]
	v_mfma_f32_16x16x32_bf16 v[60:63], v[132:135], v[186:189], v[60:63]
	v_mfma_f32_16x16x32_bf16 v[56:59], v[162:165], v[186:189], v[56:59]
	v_mfma_f32_16x16x32_bf16 v[44:47], v[132:135], v[194:197], v[44:47]
	v_mfma_f32_16x16x32_bf16 v[40:43], v[162:165], v[194:197], v[40:43]
	v_mfma_f32_16x16x32_bf16 v[28:31], v[132:135], v[202:205], v[28:31]
	v_mfma_f32_16x16x32_bf16 v[24:27], v[162:165], v[202:205], v[24:27]
	v_mfma_f32_16x16x32_bf16 v[12:15], v[132:135], v[214:217], v[12:15]
	v_mfma_f32_16x16x32_bf16 v[8:11], v[162:165], v[214:217], v[8:11]
	v_mfma_f32_16x16x32_bf16 v[52:55], v[166:169], v[182:185], v[52:55]
	v_mfma_f32_16x16x32_bf16 v[48:51], v[174:177], v[182:185], v[48:51]
	v_mfma_f32_16x16x32_bf16 v[36:39], v[166:169], v[190:193], v[36:39]
	v_mfma_f32_16x16x32_bf16 v[32:35], v[174:177], v[190:193], v[32:35]
	v_mfma_f32_16x16x32_bf16 v[20:23], v[166:169], v[198:201], v[20:23]
	v_mfma_f32_16x16x32_bf16 v[16:19], v[174:177], v[198:201], v[16:19]
	v_mfma_f32_16x16x32_bf16 v[4:7], v[166:169], v[206:209], v[4:7]
	v_mfma_f32_16x16x32_bf16 v[0:3], v[174:177], v[206:209], v[0:3]
	v_mfma_f32_16x16x32_bf16 v[52:55], v[170:173], v[186:189], v[52:55]
	v_mfma_f32_16x16x32_bf16 v[48:51], v[178:181], v[186:189], v[48:51]
	v_mfma_f32_16x16x32_bf16 v[36:39], v[170:173], v[194:197], v[36:39]
	v_mfma_f32_16x16x32_bf16 v[32:35], v[178:181], v[194:197], v[32:35]
	v_mfma_f32_16x16x32_bf16 v[20:23], v[170:173], v[202:205], v[20:23]
	v_mfma_f32_16x16x32_bf16 v[16:19], v[178:181], v[202:205], v[16:19]
	v_mfma_f32_16x16x32_bf16 v[4:7], v[170:173], v[214:217], v[4:7]
	v_mfma_f32_16x16x32_bf16 v[0:3], v[178:181], v[214:217], v[0:3]
	s_barrier
	s_add_i32 s65, s65, 2
	s_add_u32 s55, s55, 0x100
	s_addc_u32 s64, s64, 0
	s_cmp_gt_u32 s65, 41
	s_mov_b64 s[24:25], s[26:27]
	s_cbranch_scc0 .LBB0_721
	v_lshl_add_u32 v152, s53, 8, v154
	v_ashrrev_i32_e32 v153, 31, v152
	s_lshl_b32 s16, s45, 8
	v_lshlrev_b64 v[128:129], 11, v[152:153]
	s_ashr_i32 s17, s16, 31
	v_lshl_add_u64 v[128:129], s[50:51], 0, v[128:129]
	v_lshl_add_u64 v[128:129], s[16:17], 1, v[128:129]
	v_lshl_add_u64 v[128:129], v[128:129], 0, s[14:15]
	v_lshl_add_u64 v[150:151], v[128:129], 0, v[144:145]
	s_mov_b32 s16, 0x8000
	v_add_co_u32_e32 v128, vcc, s16, v150
	global_load_dwordx4 v[164:167], v[150:151], off
	global_load_dwordx4 v[168:171], v[150:151], off offset:256
	v_addc_co_u32_e32 v129, vcc, 0, v151, vcc
	global_load_dwordx4 v[132:135], v[128:129], off
	s_nop 0
	global_load_dwordx4 v[128:131], v[128:129], off offset:256
	s_and_b64 vcc, exec, s[12:13]
	s_cbranch_vccz .LBB0_724
	s_barrier

; #define PG8_STAGE(bufoff, gbase, voff) do { _Pragma("unroll") for (int _i = 0; _i < 2; ++_i) \
;     __builtin_amdgcn_global_load_lds((const unsigned*)((const char*)(gbase) + (voff)[_i]), (PG8_LAS unsigned*)(lds + (bufoff) + ldsw + _i * 8192), 16, 0, 0); } while (0)
; #define PG8_LDA(dst, b, h) do { _Pragma("unroll") for (int m = 0; m < 4; ++m) _Pragma("unroll") for (int k = 0; k < 2; ++k) dst[m][k] = *(const PG8_LAS bf16x8*)(lds + PG8_SA(b, h) + aoff + m * 2048 + k * 1024); } while (0)
; #define PG8_LDB(dst, b, h) do { _Pragma("unroll") for (int n = 0; n < 2; ++n) _Pragma("unroll") for (int k = 0; k < 2; ++k) dst[n][k] = *(const PG8_LAS bf16x8*)(lds + PG8_SB(b, h) + boff + n * 2048 + k * 1024); } while (0)
; #define PG8_SCHED __builtin_amdgcn_sched_barrier(0)
; template <class Epi, class Sched>
; DI void gemm_phase(PG8_LAS unsigned char* lds, const Gemm g, const Sched& S, const Epi& E) {
;     ...
;   for (;;) {
;     const bool has_next = S.next(ui + 1, nxt);
;     const char* nA = has_next ? (const char*)g.A + (size_t)nxt.pm * tstepA : cA; const char* nB = has_next ? (const char*)g.Bt + (size_t)nxt.pn * tstepB : cB;
; #pragma unroll 1
;     for (int t = 0; t < nt; t += 2) {
;       const bool last = (t == nt - 2);
;       const char* a1 = cA + (size_t)(t + 1) * kstep;
;       const char* a2 = last ? nA : cA + (size_t)(t + 2) * kstep; const char* b2 = last ? nB : cB + (size_t)(t + 2) * kstep;
;       const char* a3 = a2 + kstep; const char* b3 = b2 + kstep;
;       PG8_LDB(B0, 0, 0); PG8_LDB(B1, 0, 1); PG8_SCHED; PG8_LDA(At, 0, 0); PG8_STAGE(PG8_SA(1, 1), a1 + hstepA, voffA);
;     ...
; #pragma unroll
;     for (int a = 0; a < 2; ++a)
; #pragma unroll
;       for (int b = 0; b < 2; ++b)
; #pragma unroll
;         for (int m = 0; m < 4; ++m)
; #pragma unroll
;           for (int n = 0; n < 2; ++n) acc[a][b][m][n] = (f32x4){0.f, 0.f, 0.f, 0.f};
.LBB0_806:
	s_ashr_i32 s31, s30, 31
	s_lshl_b64 s[16:17], s[30:31], 19
	s_add_u32 s36, s50, s16
	s_addc_u32 s37, s51, s17
	s_and_b64 s[16:17], s[34:35], exec
	s_cselect_b32 s1, s37, s11
	s_cselect_b32 s9, s36, s10
	s_ashr_i32 s29, s28, 31
	s_lshl_b64 s[16:17], s[28:29], 19
	s_add_u32 s38, s90, s16
	s_addc_u32 s39, s91, s17
	s_and_b64 s[16:17], s[34:35], exec
	s_cselect_b32 s22, s39, s41
	s_cselect_b32 s29, s38, s40
	s_add_u32 s10, s10, 0x40080
	s_addc_u32 s11, s11, 0
	s_add_u32 s31, s40, 0x100
	v_mov_b32_e32 v0, 0
	s_addc_u32 s72, s41, 0
	s_mov_b32 s73, -2
	s_waitcnt lgkmcnt(0)
	v_mov_b32_e32 v1, v0
	v_mov_b32_e32 v2, v0
	v_mov_b32_e32 v3, v0
	v_mov_b32_e32 v4, v0
	v_mov_b32_e32 v5, v0
	v_mov_b32_e32 v6, v0
	v_mov_b32_e32 v7, v0
	v_mov_b32_e32 v16, v0
	v_mov_b32_e32 v17, v0
	v_mov_b32_e32 v18, v0
	v_mov_b32_e32 v19, v0
	v_mov_b32_e32 v20, v0
	v_mov_b32_e32 v21, v0
	v_mov_b32_e32 v22, v0
	v_mov_b32_e32 v23, v0
	v_mov_b32_e32 v32, v0
	v_mov_b32_e32 v33, v0
	v_mov_b32_e32 v34, v0
	v_mov_b32_e32 v35, v0
	v_mov_b32_e32 v36, v0
	v_mov_b32_e32 v37, v0
	v_mov_b32_e32 v38, v0
	v_mov_b32_e32 v39, v0
	v_mov_b32_e32 v48, v0
	v_mov_b32_e32 v49, v0
	v_mov_b32_e32 v50, v0
	v_mov_b32_e32 v51, v0
	v_mov_b32_e32 v52, v0
	v_mov_b32_e32 v53, v0
	v_mov_b32_e32 v54, v0
	v_mov_b32_e32 v55, v0
	v_mov_b32_e32 v8, v0
	v_mov_b32_e32 v9, v0
	v_mov_b32_e32 v10, v0
	v_mov_b32_e32 v11, v0
	v_mov_b32_e32 v12, v0
	v_mov_b32_e32 v13, v0
	v_mov_b32_e32 v14, v0
	v_mov_b32_e32 v15, v0
	v_mov_b32_e32 v24, v0
	v_mov_b32_e32 v25, v0
	v_mov_b32_e32 v26, v0
	v_mov_b32_e32 v27, v0
	v_mov_b32_e32 v28, v0
	v_mov_b32_e32 v29, v0
	v_mov_b32_e32 v30, v0
	v_mov_b32_e32 v31, v0
	v_mov_b32_e32 v40, v0
	v_mov_b32_e32 v41, v0
	v_mov_b32_e32 v42, v0
	v_mov_b32_e32 v43, v0
	v_mov_b32_e32 v44, v0
	v_mov_b32_e32 v45, v0
	v_mov_b32_e32 v46, v0
	v_mov_b32_e32 v47, v0
	v_mov_b32_e32 v56, v0
	v_mov_b32_e32 v57, v0
	v_mov_b32_e32 v58, v0
	v_mov_b32_e32 v59, v0
	v_mov_b32_e32 v60, v0
	v_mov_b32_e32 v61, v0
	v_mov_b32_e32 v62, v0
	v_mov_b32_e32 v63, v0
	v_mov_b32_e32 v64, v0
	v_mov_b32_e32 v65, v0
	v_mov_b32_e32 v66, v0
	v_mov_b32_e32 v67, v0
	v_mov_b32_e32 v68, v0
	v_mov_b32_e32 v69, v0
	v_mov_b32_e32 v70, v0
	v_mov_b32_e32 v71, v0
	v_mov_b32_e32 v80, v0
	v_mov_b32_e32 v81, v0
	v_mov_b32_e32 v82, v0
	v_mov_b32_e32 v83, v0
	v_mov_b32_e32 v84, v0
	v_mov_b32_e32 v85, v0
	v_mov_b32_e32 v86, v0
	v_mov_b32_e32 v87, v0
	v_mov_b32_e32 v96, v0
	v_mov_b32_e32 v97, v0
	v_mov_b32_e32 v98, v0
	v_mov_b32_e32 v99, v0
	v_mov_b32_e32 v100, v0
	v_mov_b32_e32 v101, v0
	v_mov_b32_e32 v102, v0
	v_mov_b32_e32 v103, v0
	s_waitcnt vmcnt(0)
	v_mov_b32_e32 v112, v0
	v_mov_b32_e32 v113, v0
	v_mov_b32_e32 v114, v0
	v_mov_b32_e32 v115, v0
	v_mov_b32_e32 v116, v0
	v_mov_b32_e32 v117, v0
	v_mov_b32_e32 v118, v0
	v_mov_b32_e32 v119, v0
	v_mov_b32_e32 v72, v0
	v_mov_b32_e32 v73, v0
	v_mov_b32_e32 v74, v0
	v_mov_b32_e32 v75, v0
	v_mov_b32_e32 v76, v0
	v_mov_b32_e32 v77, v0
	v_mov_b32_e32 v78, v0
	v_mov_b32_e32 v79, v0
	v_mov_b32_e32 v88, v0
	v_mov_b32_e32 v89, v0
	v_mov_b32_e32 v90, v0
	v_mov_b32_e32 v91, v0
	v_mov_b32_e32 v92, v0
	v_mov_b32_e32 v93, v0
	v_mov_b32_e32 v94, v0
	v_mov_b32_e32 v95, v0
	v_mov_b32_e32 v104, v0
	v_mov_b32_e32 v105, v0
	v_mov_b32_e32 v106, v0
	v_mov_b32_e32 v107, v0
	v_mov_b32_e32 v108, v0
	v_mov_b32_e32 v109, v0
	v_mov_b32_e32 v110, v0
	v_mov_b32_e32 v111, v0
	v_mov_b32_e32 v120, v0
	v_mov_b32_e32 v121, v0
	v_mov_b32_e32 v122, v0
	v_mov_b32_e32 v123, v0
	v_mov_b32_e32 v124, v0
	v_mov_b32_e32 v125, v0
	v_mov_b32_e32 v126, v0
	v_mov_b32_e32 v127, v0
	v_readfirstlane_b32 s100, v212
	s_nop 3
	s_lshr_b32 s100, s100, 8
	s_cmp_lg_u32 s100, 0
	s_cbranch_scc0 .Lgp_4
	s_setprio 1
.Lgp_4:
.LBB0_807:
	ds_read_b128 v[144:147], v195
	ds_read_b128 v[148:151], v195 offset:1024
	ds_read_b128 v[152:155], v195 offset:2048
	ds_read_b128 v[156:159], v195 offset:3072
	ds_read_b128 v[160:163], v196
	ds_read_b128 v[164:167], v196 offset:1024
	ds_read_b128 v[168:171], v196 offset:2048
	ds_read_b128 v[172:175], v196 offset:3072
	s_add_u32 s16, s10, 0xfffc0080
	s_addc_u32 s17, s11, -1
	s_cmp_eq_u32 s73, 12
	s_cselect_b32 s45, s1, s17
	s_cselect_b32 s44, s9, s16
	s_cselect_b32 s41, s22, s72
	s_cselect_b32 s40, s29, s31
	v_lshl_add_u64 v[192:193], s[10:11], 0, v[138:139]
	s_add_i32 m0, s3, 0xc000
	ds_read_b128 v[176:179], v197
	ds_read_b128 v[180:183], v197 offset:1024
	ds_read_b128 v[184:187], v197 offset:2048
	ds_read_b128 v[188:191], v197 offset:3072
	ds_read_b128 v[202:205], v197 offset:4096
	ds_read_b128 v[206:209], v197 offset:5120
	ds_read_b128 v[214:217], v197 offset:6144
	ds_read_b128 v[218:221], v197 offset:7168
	global_load_lds_dwordx4 v[192:193], off
	v_lshl_add_u64 v[192:193], s[10:11], 0, v[140:141]
	s_add_i32 m0, s3, 0xe000
	s_nop 0
	global_load_lds_dwordx4 v[192:193], off
	s_waitcnt vmcnt(8)
	s_waitcnt lgkmcnt(0)
	s_barrier
; #define PG8_STAGE(bufoff, gbase, voff) do { _Pragma("unroll") for (int _i = 0; _i < 2; ++_i) \
;     __builtin_amdgcn_global_load_lds((const unsigned*)((const char*)(gbase) + (voff)[_i]), (PG8_LAS unsigned*)(lds + (bufoff) + ldsw + _i * 8192), 16, 0, 0); } while (0)
; #define PG8_LDA(dst, b, h) do { _Pragma("unroll") for (int m = 0; m < 4; ++m) _Pragma("unroll") for (int k = 0; k < 2; ++k) dst[m][k] = *(const PG8_LAS bf16x8*)(lds + PG8_SA(b, h) + aoff + m * 2048 + k * 1024); } while (0)
; #define PG8_MMA(ai, bj, At, Bt) do { __builtin_amdgcn_s_setprio(1); _Pragma("unroll") for (int m = 0; m < 4; ++m) _Pragma("unroll") for (int n = 0; n < 2; ++n) _Pragma("unroll") for (int k = 0; k < 2; ++k) \
;     acc[ai][bj][m][n] = __builtin_amdgcn_mfma_f32_16x16x32_bf16(Bt[n][k], At[m][k], acc[ai][bj][m][n], 0, 0, 0); __builtin_amdgcn_s_setprio(0); } while (0)
; #define PG8_WAIT_V(n) asm volatile("s_waitcnt vmcnt(" #n ")" ::: "memory")
; #define PG8_WAIT_L(n) asm volatile("s_waitcnt lgkmcnt(" #n ")" ::: "memory")
; #define PG8_BAR __builtin_amdgcn_s_barrier()
; #define PG8_SCHED __builtin_amdgcn_sched_barrier(0)
; template <class Epi, class Sched>
; DI void gemm_phase(PG8_LAS unsigned char* lds, const Gemm g, const Sched& S, const Epi& E) {
;     ...
;       PG8_WAIT_V(8); PG8_WAIT_L(0); PG8_BAR; PG8_MMA(0, 0, At, B0); PG8_MMA(0, 1, At, B1); PG8_BAR; PG8_SCHED;
;       PG8_LDA(At, 0, 1); PG8_STAGE(PG8_SB(0, 0), b2, voffB); PG8_STAGE(PG8_SB(0, 1), b2 + hstepB, voffB); PG8_STAGE(PG8_SA(0, 0), a2, voffA);
;       PG8_WAIT_V(8); PG8_WAIT_L(0); PG8_BAR; PG8_MMA(1, 0, At, B0); PG8_MMA(1, 1, At, B1); PG8_BAR; PG8_SCHED;
	s_waitcnt lgkmcnt(0)
	v_mfma_f32_16x16x32_bf16 v[124:127], v[144:147], v[176:179], v[124:127]
	v_mfma_f32_16x16x32_bf16 v[120:123], v[152:155], v[176:179], v[120:123]
	v_mfma_f32_16x16x32_bf16 v[108:111], v[144:147], v[184:187], v[108:111]
	v_mfma_f32_16x16x32_bf16 v[104:107], v[152:155], v[184:187], v[104:107]
	v_mfma_f32_16x16x32_bf16 v[92:95], v[144:147], v[202:205], v[92:95]
	v_mfma_f32_16x16x32_bf16 v[88:91], v[152:155], v[202:205], v[88:91]
	v_mfma_f32_16x16x32_bf16 v[76:79], v[144:147], v[214:217], v[76:79]
	v_mfma_f32_16x16x32_bf16 v[72:75], v[152:155], v[214:217], v[72:75]
	v_mfma_f32_16x16x32_bf16 v[124:127], v[148:151], v[180:183], v[124:127]
	v_mfma_f32_16x16x32_bf16 v[120:123], v[156:159], v[180:183], v[120:123]
	v_mfma_f32_16x16x32_bf16 v[108:111], v[148:151], v[188:191], v[108:111]
	v_mfma_f32_16x16x32_bf16 v[104:107], v[156:159], v[188:191], v[104:107]
	v_mfma_f32_16x16x32_bf16 v[92:95], v[148:151], v[206:209], v[92:95]
	v_mfma_f32_16x16x32_bf16 v[88:91], v[156:159], v[206:209], v[88:91]
	v_mfma_f32_16x16x32_bf16 v[76:79], v[148:151], v[218:221], v[76:79]
	v_mfma_f32_16x16x32_bf16 v[72:75], v[156:159], v[218:221], v[72:75]
	v_mfma_f32_16x16x32_bf16 v[116:119], v[160:163], v[176:179], v[116:119]
	v_mfma_f32_16x16x32_bf16 v[112:115], v[168:171], v[176:179], v[112:115]
	v_mfma_f32_16x16x32_bf16 v[100:103], v[160:163], v[184:187], v[100:103]
	v_mfma_f32_16x16x32_bf16 v[96:99], v[168:171], v[184:187], v[96:99]
	v_mfma_f32_16x16x32_bf16 v[84:87], v[160:163], v[202:205], v[84:87]
	v_mfma_f32_16x16x32_bf16 v[80:83], v[168:171], v[202:205], v[80:83]
	v_mfma_f32_16x16x32_bf16 v[68:71], v[160:163], v[214:217], v[68:71]
	v_mfma_f32_16x16x32_bf16 v[64:67], v[168:171], v[214:217], v[64:67]
	v_mfma_f32_16x16x32_bf16 v[116:119], v[164:167], v[180:183], v[116:119]
	v_mfma_f32_16x16x32_bf16 v[112:115], v[172:175], v[180:183], v[112:115]
	v_mfma_f32_16x16x32_bf16 v[100:103], v[164:167], v[188:191], v[100:103]
	v_mfma_f32_16x16x32_bf16 v[96:99], v[172:175], v[188:191], v[96:99]
	v_mfma_f32_16x16x32_bf16 v[84:87], v[164:167], v[206:209], v[84:87]
	v_mfma_f32_16x16x32_bf16 v[80:83], v[172:175], v[206:209], v[80:83]
	v_mfma_f32_16x16x32_bf16 v[68:71], v[164:167], v[218:221], v[68:71]
	v_mfma_f32_16x16x32_bf16 v[64:67], v[172:175], v[218:221], v[64:67]
	s_barrier
	s_add_i32 s16, s4, s2
	v_lshl_add_u64 v[192:193], s[40:41], 0, v[130:131]
	s_mov_b32 m0, s16
	ds_read_b128 v[176:179], v197 offset:16384
	ds_read_b128 v[180:183], v197 offset:17408
	ds_read_b128 v[184:187], v197 offset:18432
	ds_read_b128 v[188:191], v197 offset:19456
	ds_read_b128 v[202:205], v197 offset:20480
	ds_read_b128 v[206:209], v197 offset:21504
	ds_read_b128 v[214:217], v197 offset:22528
	ds_read_b128 v[218:221], v197 offset:23552
	global_load_lds_dwordx4 v[192:193], off
	s_add_i32 m0, s16, 0x2000
	s_add_u32 s16, s40, 0x40000
	v_lshl_add_u64 v[210:211], s[40:41], 0, v[134:135]
	s_addc_u32 s17, s41, 0
	s_add_i32 s33, s5, s2
	global_load_lds_dwordx4 v[210:211], off
	v_lshl_add_u64 v[222:223], s[16:17], 0, v[130:131]
	s_mov_b32 m0, s33
	v_lshl_add_u64 v[224:225], s[44:45], 0, v[132:133]
	global_load_lds_dwordx4 v[222:223], off
	v_lshl_add_u64 v[222:223], s[16:17], 0, v[134:135]
	s_add_i32 m0, s33, 0x2000
	s_nop 0
	global_load_lds_dwordx4 v[222:223], off
	v_lshl_add_u64 v[222:223], s[44:45], 0, v[128:129]
	s_mov_b32 m0, s3
	s_nop 0
	global_load_lds_dwordx4 v[222:223], off
	s_mov_b32 m0, s27
	s_nop 0
	global_load_lds_dwordx4 v[224:225], off
	s_waitcnt vmcnt(8)
	s_waitcnt lgkmcnt(0)
	s_barrier
	s_waitcnt lgkmcnt(0)
	v_mfma_f32_16x16x32_bf16 v[60:63], v[144:147], v[176:179], v[60:63]
	v_mfma_f32_16x16x32_bf16 v[56:59], v[152:155], v[176:179], v[56:59]
	v_mfma_f32_16x16x32_bf16 v[44:47], v[144:147], v[184:187], v[44:47]
	v_mfma_f32_16x16x32_bf16 v[40:43], v[152:155], v[184:187], v[40:43]
	v_mfma_f32_16x16x32_bf16 v[28:31], v[144:147], v[202:205], v[28:31]
	v_mfma_f32_16x16x32_bf16 v[24:27], v[152:155], v[202:205], v[24:27]
	v_mfma_f32_16x16x32_bf16 v[12:15], v[144:147], v[214:217], v[12:15]
	v_mfma_f32_16x16x32_bf16 v[8:11], v[152:155], v[214:217], v[8:11]
	v_mfma_f32_16x16x32_bf16 v[60:63], v[148:151], v[180:183], v[60:63]
	v_mfma_f32_16x16x32_bf16 v[56:59], v[156:159], v[180:183], v[56:59]
	v_mfma_f32_16x16x32_bf16 v[44:47], v[148:151], v[188:191], v[44:47]
	v_mfma_f32_16x16x32_bf16 v[40:43], v[156:159], v[188:191], v[40:43]
	v_mfma_f32_16x16x32_bf16 v[28:31], v[148:151], v[206:209], v[28:31]
	v_mfma_f32_16x16x32_bf16 v[24:27], v[156:159], v[206:209], v[24:27]
	v_mfma_f32_16x16x32_bf16 v[12:15], v[148:151], v[218:221], v[12:15]
	v_mfma_f32_16x16x32_bf16 v[8:11], v[156:159], v[218:221], v[8:11]
	v_mfma_f32_16x16x32_bf16 v[52:55], v[160:163], v[176:179], v[52:55]
	v_mfma_f32_16x16x32_bf16 v[48:51], v[168:171], v[176:179], v[48:51]
	v_mfma_f32_16x16x32_bf16 v[36:39], v[160:163], v[184:187], v[36:39]
	v_mfma_f32_16x16x32_bf16 v[32:35], v[168:171], v[184:187], v[32:35]
	v_mfma_f32_16x16x32_bf16 v[20:23], v[160:163], v[202:205], v[20:23]
	v_mfma_f32_16x16x32_bf16 v[16:19], v[168:171], v[202:205], v[16:19]
	v_mfma_f32_16x16x32_bf16 v[4:7], v[160:163], v[214:217], v[4:7]
	v_mfma_f32_16x16x32_bf16 v[0:3], v[168:171], v[214:217], v[0:3]
	v_mfma_f32_16x16x32_bf16 v[52:55], v[164:167], v[180:183], v[52:55]
	v_mfma_f32_16x16x32_bf16 v[48:51], v[172:175], v[180:183], v[48:51]
	v_mfma_f32_16x16x32_bf16 v[36:39], v[164:167], v[188:191], v[36:39]
	v_mfma_f32_16x16x32_bf16 v[32:35], v[172:175], v[188:191], v[32:35]
	v_mfma_f32_16x16x32_bf16 v[20:23], v[164:167], v[206:209], v[20:23]
	v_mfma_f32_16x16x32_bf16 v[16:19], v[172:175], v[206:209], v[16:19]
	v_mfma_f32_16x16x32_bf16 v[4:7], v[164:167], v[218:221], v[4:7]
	v_mfma_f32_16x16x32_bf16 v[0:3], v[172:175], v[218:221], v[0:3]
	s_barrier
; #define PG8_STAGE(bufoff, gbase, voff) do { _Pragma("unroll") for (int _i = 0; _i < 2; ++_i) \
;     __builtin_amdgcn_global_load_lds((const unsigned*)((const char*)(gbase) + (voff)[_i]), (PG8_LAS unsigned*)(lds + (bufoff) + ldsw + _i * 8192), 16, 0, 0); } while (0)
; #define PG8_LDA(dst, b, h) do { _Pragma("unroll") for (int m = 0; m < 4; ++m) _Pragma("unroll") for (int k = 0; k < 2; ++k) dst[m][k] = *(const PG8_LAS bf16x8*)(lds + PG8_SA(b, h) + aoff + m * 2048 + k * 1024); } while (0)
; #define PG8_LDB(dst, b, h) do { _Pragma("unroll") for (int n = 0; n < 2; ++n) _Pragma("unroll") for (int k = 0; k < 2; ++k) dst[n][k] = *(const PG8_LAS bf16x8*)(lds + PG8_SB(b, h) + boff + n * 2048 + k * 1024); } while (0)
; #define PG8_MMA(ai, bj, At, Bt) do { __builtin_amdgcn_s_setprio(1); _Pragma("unroll") for (int m = 0; m < 4; ++m) _Pragma("unroll") for (int n = 0; n < 2; ++n) _Pragma("unroll") for (int k = 0; k < 2; ++k) \
;     acc[ai][bj][m][n] = __builtin_amdgcn_mfma_f32_16x16x32_bf16(Bt[n][k], At[m][k], acc[ai][bj][m][n], 0, 0, 0); __builtin_amdgcn_s_setprio(0); } while (0)
; #define PG8_WAIT_V(n) asm volatile("s_waitcnt vmcnt(" #n ")" ::: "memory")
; #define PG8_WAIT_L(n) asm volatile("s_waitcnt lgkmcnt(" #n ")" ::: "memory")
; #define PG8_BAR __builtin_amdgcn_s_barrier()
; #define PG8_SCHED __builtin_amdgcn_sched_barrier(0)
; template <class Epi, class Sched>
; DI void gemm_phase(PG8_LAS unsigned char* lds, const Gemm g, const Sched& S, const Epi& E) {
;     ...
;       PG8_LDB(B0, 1, 0); PG8_LDB(B1, 1, 1); PG8_SCHED; PG8_LDA(At, 1, 0); PG8_STAGE(PG8_SA(0, 1), a2 + hstepA, voffA);
;       PG8_WAIT_V(8); PG8_WAIT_L(0); PG8_BAR; PG8_MMA(0, 0, At, B0); PG8_MMA(0, 1, At, B1); PG8_BAR; PG8_SCHED;
;       PG8_LDA(At, 1, 1); PG8_STAGE(PG8_SB(1, 0), b3, voffB); PG8_STAGE(PG8_SB(1, 1), b3 + hstepB, voffB); PG8_STAGE(PG8_SA(1, 0), a3, voffA);
	ds_read_b128 v[144:147], v199
	ds_read_b128 v[148:151], v199 offset:1024
	ds_read_b128 v[152:155], v199 offset:2048
	ds_read_b128 v[156:159], v199 offset:3072
	ds_read_b128 v[160:163], v200
	ds_read_b128 v[164:167], v200 offset:1024
	ds_read_b128 v[168:171], v200 offset:2048
	ds_read_b128 v[172:175], v200 offset:3072
	s_add_u32 s16, s44, 0x40000
	s_addc_u32 s17, s45, 0
	s_mov_b32 m0, s53
	v_lshl_add_u64 v[226:227], s[16:17], 0, v[128:129]
	ds_read_b128 v[176:179], v197 offset:32768
	ds_read_b128 v[180:183], v197 offset:33792
	ds_read_b128 v[184:187], v197 offset:34816
	ds_read_b128 v[188:191], v197 offset:35840
	ds_read_b128 v[202:205], v197 offset:36864
	ds_read_b128 v[206:209], v197 offset:37888
	ds_read_b128 v[214:217], v197 offset:38912
	ds_read_b128 v[218:221], v197 offset:39936
	global_load_lds_dwordx4 v[226:227], off
	v_lshl_add_u64 v[226:227], s[16:17], 0, v[132:133]
	s_mov_b32 m0, s55
	s_nop 0
	global_load_lds_dwordx4 v[226:227], off
	s_waitcnt vmcnt(8)
	s_waitcnt lgkmcnt(0)
	s_barrier
	s_waitcnt lgkmcnt(0)
	v_mfma_f32_16x16x32_bf16 v[124:127], v[144:147], v[176:179], v[124:127]
	v_mfma_f32_16x16x32_bf16 v[120:123], v[152:155], v[176:179], v[120:123]
	v_mfma_f32_16x16x32_bf16 v[108:111], v[144:147], v[184:187], v[108:111]
	v_mfma_f32_16x16x32_bf16 v[104:107], v[152:155], v[184:187], v[104:107]
	v_mfma_f32_16x16x32_bf16 v[92:95], v[144:147], v[202:205], v[92:95]
	v_mfma_f32_16x16x32_bf16 v[88:91], v[152:155], v[202:205], v[88:91]
	v_mfma_f32_16x16x32_bf16 v[76:79], v[144:147], v[214:217], v[76:79]
	v_mfma_f32_16x16x32_bf16 v[72:75], v[152:155], v[214:217], v[72:75]
	v_mfma_f32_16x16x32_bf16 v[124:127], v[148:151], v[180:183], v[124:127]
	v_mfma_f32_16x16x32_bf16 v[120:123], v[156:159], v[180:183], v[120:123]
	v_mfma_f32_16x16x32_bf16 v[108:111], v[148:151], v[188:191], v[108:111]
	v_mfma_f32_16x16x32_bf16 v[104:107], v[156:159], v[188:191], v[104:107]
	v_mfma_f32_16x16x32_bf16 v[92:95], v[148:151], v[206:209], v[92:95]
	v_mfma_f32_16x16x32_bf16 v[88:91], v[156:159], v[206:209], v[88:91]
	v_mfma_f32_16x16x32_bf16 v[76:79], v[148:151], v[218:221], v[76:79]
	v_mfma_f32_16x16x32_bf16 v[72:75], v[156:159], v[218:221], v[72:75]
	v_mfma_f32_16x16x32_bf16 v[116:119], v[160:163], v[176:179], v[116:119]
	v_mfma_f32_16x16x32_bf16 v[112:115], v[168:171], v[176:179], v[112:115]
	v_mfma_f32_16x16x32_bf16 v[100:103], v[160:163], v[184:187], v[100:103]
	v_mfma_f32_16x16x32_bf16 v[96:99], v[168:171], v[184:187], v[96:99]
	v_mfma_f32_16x16x32_bf16 v[84:87], v[160:163], v[202:205], v[84:87]
	v_mfma_f32_16x16x32_bf16 v[80:83], v[168:171], v[202:205], v[80:83]
	v_mfma_f32_16x16x32_bf16 v[68:71], v[160:163], v[214:217], v[68:71]
	v_mfma_f32_16x16x32_bf16 v[64:67], v[168:171], v[214:217], v[64:67]
	v_mfma_f32_16x16x32_bf16 v[116:119], v[164:167], v[180:183], v[116:119]
	v_mfma_f32_16x16x32_bf16 v[112:115], v[172:175], v[180:183], v[112:115]
	v_mfma_f32_16x16x32_bf16 v[100:103], v[164:167], v[188:191], v[100:103]
	v_mfma_f32_16x16x32_bf16 v[96:99], v[172:175], v[188:191], v[96:99]
	v_mfma_f32_16x16x32_bf16 v[84:87], v[164:167], v[206:209], v[84:87]
	v_mfma_f32_16x16x32_bf16 v[80:83], v[172:175], v[206:209], v[80:83]
	v_mfma_f32_16x16x32_bf16 v[68:71], v[164:167], v[218:221], v[68:71]
	v_mfma_f32_16x16x32_bf16 v[64:67], v[172:175], v[218:221], v[64:67]
	s_barrier
	s_add_i32 s16, s69, s2
	v_lshl_add_u64 v[192:193], v[192:193], 0, s[14:15]
	s_mov_b32 m0, s16
	ds_read_b128 v[176:179], v197 offset:49152
	ds_read_b128 v[180:183], v197 offset:50176
	ds_read_b128 v[184:187], v197 offset:51200
	ds_read_b128 v[188:191], v197 offset:52224
	ds_read_b128 v[202:205], v197 offset:53248
	ds_read_b128 v[206:209], v197 offset:54272
	ds_read_b128 v[214:217], v197 offset:55296
	ds_read_b128 v[218:221], v197 offset:56320
	global_load_lds_dwordx4 v[192:193], off
	s_add_i32 m0, s16, 0x2000
	s_add_u32 s16, s40, 0x40080
	v_lshl_add_u64 v[192:193], v[210:211], 0, s[14:15]
	s_addc_u32 s17, s41, 0
	s_add_i32 s33, s70, s2
	global_load_lds_dwordx4 v[192:193], off
	v_lshl_add_u64 v[192:193], s[16:17], 0, v[130:131]
	s_mov_b32 m0, s33
	s_nop 0
	global_load_lds_dwordx4 v[192:193], off
	v_lshl_add_u64 v[192:193], s[16:17], 0, v[134:135]
	s_add_i32 m0, s33, 0x2000
	s_nop 0
	global_load_lds_dwordx4 v[192:193], off
	v_lshl_add_u64 v[192:193], v[222:223], 0, s[14:15]
	s_mov_b32 m0, s65
	s_nop 0
	global_load_lds_dwordx4 v[192:193], off
	v_lshl_add_u64 v[192:193], v[224:225], 0, s[14:15]
	s_mov_b32 m0, s66
	s_nop 0
	global_load_lds_dwordx4 v[192:193], off
	s_waitcnt vmcnt(8)
	s_waitcnt lgkmcnt(0)
	s_barrier
; #define PG8_MMA(ai, bj, At, Bt) do { __builtin_amdgcn_s_setprio(1); _Pragma("unroll") for (int m = 0; m < 4; ++m) _Pragma("unroll") for (int n = 0; n < 2; ++n) _Pragma("unroll") for (int k = 0; k < 2; ++k) \
;     acc[ai][bj][m][n] = __builtin_amdgcn_mfma_f32_16x16x32_bf16(Bt[n][k], At[m][k], acc[ai][bj][m][n], 0, 0, 0); __builtin_amdgcn_s_setprio(0); } while (0)
; #define PG8_WAIT_V(n) asm volatile("s_waitcnt vmcnt(" #n ")" ::: "memory")
; #define PG8_WAIT_L(n) asm volatile("s_waitcnt lgkmcnt(" #n ")" ::: "memory")
; #define PG8_BAR __builtin_amdgcn_s_barrier()
; #define PG8_SCHED __builtin_amdgcn_sched_barrier(0)
; DI void rows_rstd(float (&rs)[2][4], const float* ps, const Unit& u, int wr, int fr, int fq, int p_lo, int p_hi, float inv_dim) {
;   f32x4 pv[2][4];
; #pragma unroll
;   for (int ai = 0; ai < 2; ++ai)
; #pragma unroll
;     for (int m = 0; m < 4; ++m) pv[ai][m] = *(const f32x4*)(ps + (size_t)(u.pm * BM + ai * HALF + wr * 64 + m * 16 + fr) * 16 + 4 * fq);
; template <class Epi, class Sched>
; DI void gemm_phase(PG8_LAS unsigned char* lds, const Gemm g, const Sched& S, const Epi& E) {
;     ...
;       PG8_WAIT_V(8); PG8_WAIT_L(0); PG8_BAR; PG8_MMA(1, 0, At, B0); PG8_MMA(1, 1, At, B1); PG8_BAR; PG8_SCHED;
;     }
;     if (wr == 0) PG8_BAR;
	s_waitcnt lgkmcnt(0)
	v_mfma_f32_16x16x32_bf16 v[60:63], v[144:147], v[176:179], v[60:63]
	v_mfma_f32_16x16x32_bf16 v[56:59], v[152:155], v[176:179], v[56:59]
	v_mfma_f32_16x16x32_bf16 v[44:47], v[144:147], v[184:187], v[44:47]
	v_mfma_f32_16x16x32_bf16 v[40:43], v[152:155], v[184:187], v[40:43]
	v_mfma_f32_16x16x32_bf16 v[28:31], v[144:147], v[202:205], v[28:31]
	v_mfma_f32_16x16x32_bf16 v[24:27], v[152:155], v[202:205], v[24:27]
	v_mfma_f32_16x16x32_bf16 v[12:15], v[144:147], v[214:217], v[12:15]
	v_mfma_f32_16x16x32_bf16 v[8:11], v[152:155], v[214:217], v[8:11]
	v_mfma_f32_16x16x32_bf16 v[60:63], v[148:151], v[180:183], v[60:63]
	v_mfma_f32_16x16x32_bf16 v[56:59], v[156:159], v[180:183], v[56:59]
	v_mfma_f32_16x16x32_bf16 v[44:47], v[148:151], v[188:191], v[44:47]
	v_mfma_f32_16x16x32_bf16 v[40:43], v[156:159], v[188:191], v[40:43]
	v_mfma_f32_16x16x32_bf16 v[28:31], v[148:151], v[206:209], v[28:31]
	v_mfma_f32_16x16x32_bf16 v[24:27], v[156:159], v[206:209], v[24:27]
	v_mfma_f32_16x16x32_bf16 v[12:15], v[148:151], v[218:221], v[12:15]
	v_mfma_f32_16x16x32_bf16 v[8:11], v[156:159], v[218:221], v[8:11]
	v_mfma_f32_16x16x32_bf16 v[52:55], v[160:163], v[176:179], v[52:55]
	v_mfma_f32_16x16x32_bf16 v[48:51], v[168:171], v[176:179], v[48:51]
	v_mfma_f32_16x16x32_bf16 v[36:39], v[160:163], v[184:187], v[36:39]
	v_mfma_f32_16x16x32_bf16 v[32:35], v[168:171], v[184:187], v[32:35]
	v_mfma_f32_16x16x32_bf16 v[20:23], v[160:163], v[202:205], v[20:23]
	v_mfma_f32_16x16x32_bf16 v[16:19], v[168:171], v[202:205], v[16:19]
	v_mfma_f32_16x16x32_bf16 v[4:7], v[160:163], v[214:217], v[4:7]
	v_mfma_f32_16x16x32_bf16 v[0:3], v[168:171], v[214:217], v[0:3]
	v_mfma_f32_16x16x32_bf16 v[52:55], v[164:167], v[180:183], v[52:55]
	v_mfma_f32_16x16x32_bf16 v[48:51], v[172:175], v[180:183], v[48:51]
	v_mfma_f32_16x16x32_bf16 v[36:39], v[164:167], v[188:191], v[36:39]
	v_mfma_f32_16x16x32_bf16 v[32:35], v[172:175], v[188:191], v[32:35]
	v_mfma_f32_16x16x32_bf16 v[20:23], v[164:167], v[206:209], v[20:23]
	v_mfma_f32_16x16x32_bf16 v[16:19], v[172:175], v[206:209], v[16:19]
	v_mfma_f32_16x16x32_bf16 v[4:7], v[164:167], v[218:221], v[4:7]
	v_mfma_f32_16x16x32_bf16 v[0:3], v[172:175], v[218:221], v[0:3]
	s_barrier
	s_add_i32 s73, s73, 2
	s_add_u32 s10, s10, 0x100
	s_addc_u32 s11, s11, 0
	s_add_u32 s31, s31, 0x100
	s_addc_u32 s72, s72, 0
	s_cmp_gt_u32 s73, 13
	s_cbranch_scc0 .LBB0_807
	v_lshl_add_u32 v184, s8, 8, v143
	v_or_b32_e32 v180, 16, v184
	v_ashrrev_i32_e32 v181, 31, v180
	v_or_b32_e32 v172, 32, v184
	v_lshlrev_b64 v[178:179], 6, v[180:181]
	v_ashrrev_i32_e32 v173, 31, v172
	v_ashrrev_i32_e32 v185, 31, v184
	v_lshl_add_u64 v[144:145], v[136:137], 0, v[178:179]
	v_lshlrev_b64 v[170:171], 6, v[172:173]
	v_lshlrev_b64 v[182:183], 6, v[184:185]
	v_lshl_add_u64 v[146:147], v[136:137], 0, v[170:171]
	global_load_dwordx4 v[162:165], v[144:145], off
	global_load_dwordx4 v[174:177], v[146:147], off
	v_lshl_add_u64 v[144:145], v[136:137], 0, v[182:183]
	global_load_dwordx4 v[186:189], v[144:145], off
	v_or_b32_e32 v168, 48, v184
	v_ashrrev_i32_e32 v169, 31, v168
	v_add_u32_e32 v160, 0x80, v184
	v_add_u32_e32 v156, 0x90, v184
	v_lshlrev_b64 v[166:167], 6, v[168:169]
	v_ashrrev_i32_e32 v161, 31, v160
	v_ashrrev_i32_e32 v157, 31, v156
	v_lshl_add_u64 v[144:145], v[136:137], 0, v[166:167]
	v_lshlrev_b64 v[158:159], 6, v[160:161]
	v_lshlrev_b64 v[154:155], 6, v[156:157]
	v_lshl_add_u64 v[146:147], v[136:137], 0, v[158:159]
	global_load_dwordx4 v[190:193], v[144:145], off
	global_load_dwordx4 v[202:205], v[146:147], off
	v_lshl_add_u64 v[144:145], v[136:137], 0, v[154:155]
	global_load_dwordx4 v[206:209], v[144:145], off
	v_add_u32_e32 v150, 0xa0, v184
	v_ashrrev_i32_e32 v151, 31, v150
	v_lshlrev_b64 v[148:149], 6, v[150:151]
	v_add_u32_e32 v146, 0xb0, v184
	v_lshl_add_u64 v[144:145], v[136:137], 0, v[148:149]
	v_ashrrev_i32_e32 v147, 31, v146
	global_load_dwordx4 v[214:217], v[144:145], off
	v_lshlrev_b64 v[144:145], 6, v[146:147]
	v_lshl_add_u64 v[152:153], v[136:137], 0, v[144:145]
	global_load_dwordx4 v[218:221], v[152:153], off
	s_and_b64 vcc, exec, s[20:21]
	s_cbranch_vccz .LBB0_810
	s_barrier

; #define PG8_STAGE(bufoff, gbase, voff) do { _Pragma("unroll") for (int _i = 0; _i < 2; ++_i) \
;     __builtin_amdgcn_global_load_lds((const unsigned*)((const char*)(gbase) + (voff)[_i]), (PG8_LAS unsigned*)(lds + (bufoff) + ldsw + _i * 8192), 16, 0, 0); } while (0)
; #define PG8_LDA(dst, b, h) do { _Pragma("unroll") for (int m = 0; m < 4; ++m) _Pragma("unroll") for (int k = 0; k < 2; ++k) dst[m][k] = *(const PG8_LAS bf16x8*)(lds + PG8_SA(b, h) + aoff + m * 2048 + k * 1024); } while (0)
; #define PG8_LDB(dst, b, h) do { _Pragma("unroll") for (int n = 0; n < 2; ++n) _Pragma("unroll") for (int k = 0; k < 2; ++k) dst[n][k] = *(const PG8_LAS bf16x8*)(lds + PG8_SB(b, h) + boff + n * 2048 + k * 1024); } while (0)
; #define PG8_MMA(ai, bj, At, Bt) do { __builtin_amdgcn_s_setprio(1); _Pragma("unroll") for (int m = 0; m < 4; ++m) _Pragma("unroll") for (int n = 0; n < 2; ++n) _Pragma("unroll") for (int k = 0; k < 2; ++k) \
;     acc[ai][bj][m][n] = __builtin_amdgcn_mfma_f32_16x16x32_bf16(Bt[n][k], At[m][k], acc[ai][bj][m][n], 0, 0, 0); __builtin_amdgcn_s_setprio(0); } while (0)
; #define PG8_WAIT_V(n) asm volatile("s_waitcnt vmcnt(" #n ")" ::: "memory")
; template <class Epi, class Sched>
; DI void gemm_phase(PG8_LAS unsigned char* lds, const Gemm g, const Sched& S, const Epi& E) {
;     ...
;   for (;;) {
;     const bool has_next = S.next(ui + 1, nxt);
;     const char* nA = has_next ? (const char*)g.A + (size_t)nxt.pm * tstepA : cA; const char* nB = has_next ? (const char*)g.Bt + (size_t)nxt.pn * tstepB : cB;
; #pragma unroll 1
;     for (int t = 0; t < nt; t += 2) {
;       const bool last = (t == nt - 2);
;       const char* a1 = cA + (size_t)(t + 1) * kstep;
;       const char* a2 = last ? nA : cA + (size_t)(t + 2) * kstep; const char* b2 = last ? nB : cB + (size_t)(t + 2) * kstep;
;       const char* a3 = a2 + kstep; const char* b3 = b2 + kstep;
;       PG8_LDB(B0, 0, 0); PG8_LDB(B1, 0, 1); PG8_SCHED; PG8_LDA(At, 0, 0); PG8_STAGE(PG8_SA(1, 1), a1 + hstepA, voffA);
;       PG8_WAIT_V(8); PG8_WAIT_L(0); PG8_BAR; PG8_MMA(0, 0, At, B0); PG8_MMA(0, 1, At, B1); PG8_BAR; PG8_SCHED;
;     ...
; #pragma unroll
;     for (int a = 0; a < 2; ++a)
; #pragma unroll
;       for (int b = 0; b < 2; ++b)
; #pragma unroll
;         for (int m = 0; m < 4; ++m)
; #pragma unroll
;           for (int n = 0; n < 2; ++n) acc[a][b][m][n] = (f32x4){0.f, 0.f, 0.f, 0.f};
.LBB0_929:
	s_add_u32 s72, s12, 0x100
	v_mov_b32_e32 v0, 0
	s_addc_u32 s73, s13, 0
	s_mov_b32 s74, -2
	v_mov_b32_e32 v1, v0
	v_mov_b32_e32 v2, v0
	v_mov_b32_e32 v3, v0
	v_mov_b32_e32 v4, v0
	v_mov_b32_e32 v5, v0
	v_mov_b32_e32 v6, v0
	v_mov_b32_e32 v7, v0
	v_mov_b32_e32 v20, v0
	v_mov_b32_e32 v21, v0
	v_mov_b32_e32 v22, v0
	v_mov_b32_e32 v23, v0
	v_mov_b32_e32 v16, v0
	v_mov_b32_e32 v17, v0
	v_mov_b32_e32 v18, v0
	v_mov_b32_e32 v19, v0
	v_mov_b32_e32 v36, v0
	v_mov_b32_e32 v37, v0
	v_mov_b32_e32 v38, v0
	v_mov_b32_e32 v39, v0
	v_mov_b32_e32 v32, v0
	v_mov_b32_e32 v33, v0
	v_mov_b32_e32 v34, v0
	v_mov_b32_e32 v35, v0
	v_mov_b32_e32 v52, v0
	v_mov_b32_e32 v53, v0
	v_mov_b32_e32 v54, v0
	v_mov_b32_e32 v55, v0
	v_mov_b32_e32 v48, v0
	v_mov_b32_e32 v49, v0
	v_mov_b32_e32 v50, v0
	v_mov_b32_e32 v51, v0
	v_mov_b32_e32 v12, v0
	v_mov_b32_e32 v13, v0
	v_mov_b32_e32 v14, v0
	v_mov_b32_e32 v15, v0
	v_mov_b32_e32 v8, v0
	v_mov_b32_e32 v9, v0
	v_mov_b32_e32 v10, v0
	v_mov_b32_e32 v11, v0
	v_mov_b32_e32 v28, v0
	v_mov_b32_e32 v29, v0
	v_mov_b32_e32 v30, v0
	v_mov_b32_e32 v31, v0
	v_mov_b32_e32 v24, v0
	v_mov_b32_e32 v25, v0
	v_mov_b32_e32 v26, v0
	v_mov_b32_e32 v27, v0
	v_mov_b32_e32 v44, v0
	v_mov_b32_e32 v45, v0
	v_mov_b32_e32 v46, v0
	v_mov_b32_e32 v47, v0
	v_mov_b32_e32 v40, v0
	v_mov_b32_e32 v41, v0
	v_mov_b32_e32 v42, v0
	v_mov_b32_e32 v43, v0
	v_mov_b32_e32 v60, v0
	v_mov_b32_e32 v61, v0
	v_mov_b32_e32 v62, v0
	v_mov_b32_e32 v63, v0
	v_mov_b32_e32 v56, v0
	v_mov_b32_e32 v57, v0
	v_mov_b32_e32 v58, v0
	v_mov_b32_e32 v59, v0
	v_mov_b32_e32 v68, v0
	v_mov_b32_e32 v69, v0
	v_mov_b32_e32 v70, v0
	v_mov_b32_e32 v71, v0
	v_mov_b32_e32 v64, v0
	v_mov_b32_e32 v65, v0
	v_mov_b32_e32 v66, v0
	v_mov_b32_e32 v67, v0
	v_mov_b32_e32 v84, v0
	v_mov_b32_e32 v85, v0
	v_mov_b32_e32 v86, v0
	v_mov_b32_e32 v87, v0
	v_mov_b32_e32 v80, v0
	v_mov_b32_e32 v81, v0
	v_mov_b32_e32 v82, v0
	v_mov_b32_e32 v83, v0
	v_mov_b32_e32 v100, v0
	v_mov_b32_e32 v101, v0
	v_mov_b32_e32 v102, v0
	v_mov_b32_e32 v103, v0
	v_mov_b32_e32 v96, v0
	v_mov_b32_e32 v97, v0
	v_mov_b32_e32 v98, v0
	v_mov_b32_e32 v99, v0
	v_mov_b32_e32 v116, v0
	v_mov_b32_e32 v117, v0
	v_mov_b32_e32 v118, v0
	v_mov_b32_e32 v119, v0
	s_waitcnt vmcnt(0)
	v_mov_b32_e32 v112, v0
	v_mov_b32_e32 v113, v0
	v_mov_b32_e32 v114, v0
	v_mov_b32_e32 v115, v0
	v_mov_b32_e32 v76, v0
	v_mov_b32_e32 v77, v0
	v_mov_b32_e32 v78, v0
	v_mov_b32_e32 v79, v0
	v_mov_b32_e32 v72, v0
	v_mov_b32_e32 v73, v0
	v_mov_b32_e32 v74, v0
	v_mov_b32_e32 v75, v0
	v_mov_b32_e32 v92, v0
	v_mov_b32_e32 v93, v0
	v_mov_b32_e32 v94, v0
	v_mov_b32_e32 v95, v0
	v_mov_b32_e32 v88, v0
	v_mov_b32_e32 v89, v0
	v_mov_b32_e32 v90, v0
	v_mov_b32_e32 v91, v0
	v_mov_b32_e32 v108, v0
	v_mov_b32_e32 v109, v0
	v_mov_b32_e32 v110, v0
	v_mov_b32_e32 v111, v0
	v_mov_b32_e32 v104, v0
	v_mov_b32_e32 v105, v0
	v_mov_b32_e32 v106, v0
	v_mov_b32_e32 v107, v0
	v_mov_b32_e32 v124, v0
	v_mov_b32_e32 v125, v0
	v_mov_b32_e32 v126, v0
	v_mov_b32_e32 v127, v0
	v_mov_b32_e32 v120, v0
	v_mov_b32_e32 v121, v0
	v_mov_b32_e32 v122, v0
	v_mov_b32_e32 v123, v0
	v_readfirstlane_b32 s100, v212
	s_nop 3
	s_lshr_b32 s100, s100, 8
	s_cmp_lg_u32 s100, 0
	s_cbranch_scc0 .Lgp_5
	s_setprio 1
.Lgp_5:
.LBB0_930:
	ds_read_b128 v[128:131], v191
	ds_read_b128 v[132:135], v191 offset:1024
	ds_read_b128 v[136:139], v191 offset:2048
	ds_read_b128 v[140:143], v191 offset:3072
	ds_read_b128 v[144:147], v192
	ds_read_b128 v[148:151], v192 offset:1024
	ds_read_b128 v[152:155], v192 offset:2048
	ds_read_b128 v[172:175], v192 offset:3072
	s_add_u32 s12, s0, 0x100
	s_addc_u32 s13, s1, 0
	s_cmp_eq_u32 s74, 8
	s_cselect_b32 s39, s35, s13
	s_cselect_b32 s38, s34, s12
	s_cselect_b32 s15, s37, s73
	s_cselect_b32 s14, s36, s72
	s_mov_b32 m0, s65
	v_lshl_add_u64 v[188:189], s[0:1], 0, v[166:167]
	ds_read_b128 v[176:179], v193
	ds_read_b128 v[180:183], v193 offset:1024
	ds_read_b128 v[184:187], v193 offset:2048
	ds_read_b128 v[198:201], v193 offset:3072
	ds_read_b128 v[202:205], v193 offset:4096
	ds_read_b128 v[206:209], v193 offset:5120
	ds_read_b128 v[214:217], v193 offset:6144
	ds_read_b128 v[218:221], v193 offset:7168
	global_load_lds_dwordx4 v[188:189], off
	v_lshl_add_u64 v[188:189], s[0:1], 0, v[168:169]
	s_add_i32 m0, s3, 0xe000
	s_nop 0
	global_load_lds_dwordx4 v[188:189], off
	s_waitcnt vmcnt(8)
	s_waitcnt lgkmcnt(0)
	s_barrier
	s_waitcnt lgkmcnt(0)
	v_mfma_f32_16x16x32_bf16 v[120:123], v[128:131], v[176:179], v[120:123]
	v_mfma_f32_16x16x32_bf16 v[124:127], v[136:139], v[176:179], v[124:127]
	v_mfma_f32_16x16x32_bf16 v[104:107], v[128:131], v[184:187], v[104:107]
	v_mfma_f32_16x16x32_bf16 v[108:111], v[136:139], v[184:187], v[108:111]
	v_mfma_f32_16x16x32_bf16 v[88:91], v[128:131], v[202:205], v[88:91]
	v_mfma_f32_16x16x32_bf16 v[92:95], v[136:139], v[202:205], v[92:95]
	v_mfma_f32_16x16x32_bf16 v[72:75], v[128:131], v[214:217], v[72:75]
	v_mfma_f32_16x16x32_bf16 v[76:79], v[136:139], v[214:217], v[76:79]
	v_mfma_f32_16x16x32_bf16 v[120:123], v[132:135], v[180:183], v[120:123]
	v_mfma_f32_16x16x32_bf16 v[124:127], v[140:143], v[180:183], v[124:127]
	v_mfma_f32_16x16x32_bf16 v[104:107], v[132:135], v[198:201], v[104:107]
	v_mfma_f32_16x16x32_bf16 v[108:111], v[140:143], v[198:201], v[108:111]
	v_mfma_f32_16x16x32_bf16 v[88:91], v[132:135], v[206:209], v[88:91]
	v_mfma_f32_16x16x32_bf16 v[92:95], v[140:143], v[206:209], v[92:95]
	v_mfma_f32_16x16x32_bf16 v[72:75], v[132:135], v[218:221], v[72:75]
	v_mfma_f32_16x16x32_bf16 v[76:79], v[140:143], v[218:221], v[76:79]
	v_mfma_f32_16x16x32_bf16 v[112:115], v[144:147], v[176:179], v[112:115]
	v_mfma_f32_16x16x32_bf16 v[116:119], v[152:155], v[176:179], v[116:119]
	v_mfma_f32_16x16x32_bf16 v[96:99], v[144:147], v[184:187], v[96:99]
	v_mfma_f32_16x16x32_bf16 v[100:103], v[152:155], v[184:187], v[100:103]
	v_mfma_f32_16x16x32_bf16 v[80:83], v[144:147], v[202:205], v[80:83]
	v_mfma_f32_16x16x32_bf16 v[84:87], v[152:155], v[202:205], v[84:87]
	v_mfma_f32_16x16x32_bf16 v[64:67], v[144:147], v[214:217], v[64:67]
	v_mfma_f32_16x16x32_bf16 v[68:71], v[152:155], v[214:217], v[68:71]
	v_mfma_f32_16x16x32_bf16 v[112:115], v[148:151], v[180:183], v[112:115]
	v_mfma_f32_16x16x32_bf16 v[116:119], v[172:175], v[180:183], v[116:119]
	v_mfma_f32_16x16x32_bf16 v[96:99], v[148:151], v[198:201], v[96:99]
	v_mfma_f32_16x16x32_bf16 v[100:103], v[172:175], v[198:201], v[100:103]
	v_mfma_f32_16x16x32_bf16 v[80:83], v[148:151], v[206:209], v[80:83]
	v_mfma_f32_16x16x32_bf16 v[84:87], v[172:175], v[206:209], v[84:87]
	v_mfma_f32_16x16x32_bf16 v[64:67], v[148:151], v[218:221], v[64:67]
	v_mfma_f32_16x16x32_bf16 v[68:71], v[172:175], v[218:221], v[68:71]
	s_barrier
; #define PG8_STAGE(bufoff, gbase, voff) do { _Pragma("unroll") for (int _i = 0; _i < 2; ++_i) \
;     __builtin_amdgcn_global_load_lds((const unsigned*)((const char*)(gbase) + (voff)[_i]), (PG8_LAS unsigned*)(lds + (bufoff) + ldsw + _i * 8192), 16, 0, 0); } while (0)
; #define PG8_LDA(dst, b, h) do { _Pragma("unroll") for (int m = 0; m < 4; ++m) _Pragma("unroll") for (int k = 0; k < 2; ++k) dst[m][k] = *(const PG8_LAS bf16x8*)(lds + PG8_SA(b, h) + aoff + m * 2048 + k * 1024); } while (0)
; #define PG8_LDB(dst, b, h) do { _Pragma("unroll") for (int n = 0; n < 2; ++n) _Pragma("unroll") for (int k = 0; k < 2; ++k) dst[n][k] = *(const PG8_LAS bf16x8*)(lds + PG8_SB(b, h) + boff + n * 2048 + k * 1024); } while (0)
; #define PG8_MMA(ai, bj, At, Bt) do { __builtin_amdgcn_s_setprio(1); _Pragma("unroll") for (int m = 0; m < 4; ++m) _Pragma("unroll") for (int n = 0; n < 2; ++n) _Pragma("unroll") for (int k = 0; k < 2; ++k) \
;     acc[ai][bj][m][n] = __builtin_amdgcn_mfma_f32_16x16x32_bf16(Bt[n][k], At[m][k], acc[ai][bj][m][n], 0, 0, 0); __builtin_amdgcn_s_setprio(0); } while (0)
; #define PG8_WAIT_V(n) asm volatile("s_waitcnt vmcnt(" #n ")" ::: "memory")
; #define PG8_WAIT_L(n) asm volatile("s_waitcnt lgkmcnt(" #n ")" ::: "memory")
; #define PG8_BAR __builtin_amdgcn_s_barrier()
; #define PG8_SCHED __builtin_amdgcn_sched_barrier(0)
; template <class Epi, class Sched>
; DI void gemm_phase(PG8_LAS unsigned char* lds, const Gemm g, const Sched& S, const Epi& E) {
;     ...
;       PG8_LDA(At, 0, 1); PG8_STAGE(PG8_SB(0, 0), b2, voffB); PG8_STAGE(PG8_SB(0, 1), b2 + hstepB, voffB); PG8_STAGE(PG8_SA(0, 0), a2, voffA);
;       PG8_WAIT_V(8); PG8_WAIT_L(0); PG8_BAR; PG8_MMA(1, 0, At, B0); PG8_MMA(1, 1, At, B1); PG8_BAR; PG8_SCHED;
;       PG8_LDB(B0, 1, 0); PG8_LDB(B1, 1, 1); PG8_SCHED; PG8_LDA(At, 1, 0); PG8_STAGE(PG8_SA(0, 1), a2 + hstepA, voffA);
	s_add_i32 s0, s44, s2
	v_lshl_add_u64 v[188:189], s[14:15], 0, v[158:159]
	s_mov_b32 m0, s0
	ds_read_b128 v[176:179], v193 offset:16384
	ds_read_b128 v[180:183], v193 offset:17408
	ds_read_b128 v[184:187], v193 offset:18432
	ds_read_b128 v[198:201], v193 offset:19456
	ds_read_b128 v[202:205], v193 offset:20480
	ds_read_b128 v[206:209], v193 offset:21504
	ds_read_b128 v[214:217], v193 offset:22528
	ds_read_b128 v[218:221], v193 offset:23552
	global_load_lds_dwordx4 v[188:189], off
	s_add_i32 m0, s0, 0x2000
	s_add_u32 s0, s14, 0x30000
	v_lshl_add_u64 v[210:211], s[14:15], 0, v[162:163]
	s_addc_u32 s1, s15, 0
	s_add_i32 s16, s45, s2
	global_load_lds_dwordx4 v[210:211], off
	v_lshl_add_u64 v[222:223], s[0:1], 0, v[158:159]
	s_mov_b32 m0, s16
	v_lshl_add_u64 v[224:225], s[38:39], 0, v[160:161]
	global_load_lds_dwordx4 v[222:223], off
	v_lshl_add_u64 v[222:223], s[0:1], 0, v[162:163]
	s_add_i32 m0, s16, 0x2000
	s_nop 0
	global_load_lds_dwordx4 v[222:223], off
	v_lshl_add_u64 v[222:223], s[38:39], 0, v[156:157]
	s_mov_b32 m0, s3
	s_nop 0
	global_load_lds_dwordx4 v[222:223], off
	s_mov_b32 m0, s4
	s_nop 0
	global_load_lds_dwordx4 v[224:225], off
	s_waitcnt vmcnt(8)
	s_waitcnt lgkmcnt(0)
	s_barrier
	s_waitcnt lgkmcnt(0)
	v_mfma_f32_16x16x32_bf16 v[56:59], v[128:131], v[176:179], v[56:59]
	v_mfma_f32_16x16x32_bf16 v[60:63], v[136:139], v[176:179], v[60:63]
	v_mfma_f32_16x16x32_bf16 v[40:43], v[128:131], v[184:187], v[40:43]
	v_mfma_f32_16x16x32_bf16 v[44:47], v[136:139], v[184:187], v[44:47]
	v_mfma_f32_16x16x32_bf16 v[24:27], v[128:131], v[202:205], v[24:27]
	v_mfma_f32_16x16x32_bf16 v[28:31], v[136:139], v[202:205], v[28:31]
	v_mfma_f32_16x16x32_bf16 v[8:11], v[128:131], v[214:217], v[8:11]
	v_mfma_f32_16x16x32_bf16 v[12:15], v[136:139], v[214:217], v[12:15]
	v_mfma_f32_16x16x32_bf16 v[56:59], v[132:135], v[180:183], v[56:59]
	v_mfma_f32_16x16x32_bf16 v[60:63], v[140:143], v[180:183], v[60:63]
	v_mfma_f32_16x16x32_bf16 v[40:43], v[132:135], v[198:201], v[40:43]
	v_mfma_f32_16x16x32_bf16 v[44:47], v[140:143], v[198:201], v[44:47]
	v_mfma_f32_16x16x32_bf16 v[24:27], v[132:135], v[206:209], v[24:27]
	v_mfma_f32_16x16x32_bf16 v[28:31], v[140:143], v[206:209], v[28:31]
	v_mfma_f32_16x16x32_bf16 v[8:11], v[132:135], v[218:221], v[8:11]
	v_mfma_f32_16x16x32_bf16 v[12:15], v[140:143], v[218:221], v[12:15]
	v_mfma_f32_16x16x32_bf16 v[48:51], v[144:147], v[176:179], v[48:51]
	v_mfma_f32_16x16x32_bf16 v[52:55], v[152:155], v[176:179], v[52:55]
	v_mfma_f32_16x16x32_bf16 v[32:35], v[144:147], v[184:187], v[32:35]
	v_mfma_f32_16x16x32_bf16 v[36:39], v[152:155], v[184:187], v[36:39]
	v_mfma_f32_16x16x32_bf16 v[16:19], v[144:147], v[202:205], v[16:19]
	v_mfma_f32_16x16x32_bf16 v[20:23], v[152:155], v[202:205], v[20:23]
	v_mfma_f32_16x16x32_bf16 v[4:7], v[144:147], v[214:217], v[4:7]
	v_mfma_f32_16x16x32_bf16 v[0:3], v[152:155], v[214:217], v[0:3]
	v_mfma_f32_16x16x32_bf16 v[48:51], v[148:151], v[180:183], v[48:51]
	v_mfma_f32_16x16x32_bf16 v[52:55], v[172:175], v[180:183], v[52:55]
	v_mfma_f32_16x16x32_bf16 v[32:35], v[148:151], v[198:201], v[32:35]
	v_mfma_f32_16x16x32_bf16 v[36:39], v[172:175], v[198:201], v[36:39]
	v_mfma_f32_16x16x32_bf16 v[16:19], v[148:151], v[206:209], v[16:19]
	v_mfma_f32_16x16x32_bf16 v[20:23], v[172:175], v[206:209], v[20:23]
	v_mfma_f32_16x16x32_bf16 v[4:7], v[148:151], v[218:221], v[4:7]
	v_mfma_f32_16x16x32_bf16 v[0:3], v[172:175], v[218:221], v[0:3]
	s_barrier
	ds_read_b128 v[128:131], v195
	ds_read_b128 v[132:135], v195 offset:1024
	ds_read_b128 v[136:139], v195 offset:2048
	ds_read_b128 v[140:143], v195 offset:3072
	ds_read_b128 v[144:147], v196
	ds_read_b128 v[148:151], v196 offset:1024
	ds_read_b128 v[152:155], v196 offset:2048
	ds_read_b128 v[172:175], v196 offset:3072
	s_add_u32 s0, s38, 0x58000
	s_addc_u32 s1, s39, 0
	s_mov_b32 m0, s5
	v_lshl_add_u64 v[226:227], s[0:1], 0, v[156:157]
	ds_read_b128 v[176:179], v193 offset:32768
	ds_read_b128 v[180:183], v193 offset:33792
	ds_read_b128 v[184:187], v193 offset:34816
	ds_read_b128 v[198:201], v193 offset:35840
	ds_read_b128 v[202:205], v193 offset:36864
	ds_read_b128 v[206:209], v193 offset:37888
	ds_read_b128 v[214:217], v193 offset:38912
	ds_read_b128 v[218:221], v193 offset:39936
	global_load_lds_dwordx4 v[226:227], off
	v_lshl_add_u64 v[226:227], s[0:1], 0, v[160:161]
	s_mov_b32 m0, s18
	s_nop 0
	global_load_lds_dwordx4 v[226:227], off
	s_waitcnt vmcnt(8)
	s_waitcnt lgkmcnt(0)
	s_barrier
; #define PG8_STAGE(bufoff, gbase, voff) do { _Pragma("unroll") for (int _i = 0; _i < 2; ++_i) \
;     __builtin_amdgcn_global_load_lds((const unsigned*)((const char*)(gbase) + (voff)[_i]), (PG8_LAS unsigned*)(lds + (bufoff) + ldsw + _i * 8192), 16, 0, 0); } while (0)
; #define PG8_LDA(dst, b, h) do { _Pragma("unroll") for (int m = 0; m < 4; ++m) _Pragma("unroll") for (int k = 0; k < 2; ++k) dst[m][k] = *(const PG8_LAS bf16x8*)(lds + PG8_SA(b, h) + aoff + m * 2048 + k * 1024); } while (0)
; #define PG8_MMA(ai, bj, At, Bt) do { __builtin_amdgcn_s_setprio(1); _Pragma("unroll") for (int m = 0; m < 4; ++m) _Pragma("unroll") for (int n = 0; n < 2; ++n) _Pragma("unroll") for (int k = 0; k < 2; ++k) \
;     acc[ai][bj][m][n] = __builtin_amdgcn_mfma_f32_16x16x32_bf16(Bt[n][k], At[m][k], acc[ai][bj][m][n], 0, 0, 0); __builtin_amdgcn_s_setprio(0); } while (0)
; #define PG8_WAIT_V(n) asm volatile("s_waitcnt vmcnt(" #n ")" ::: "memory")
; #define PG8_WAIT_L(n) asm volatile("s_waitcnt lgkmcnt(" #n ")" ::: "memory")
; #define PG8_BAR __builtin_amdgcn_s_barrier()
; #define PG8_SCHED __builtin_amdgcn_sched_barrier(0)
; template <class Epi, class Sched>
; DI void gemm_phase(PG8_LAS unsigned char* lds, const Gemm g, const Sched& S, const Epi& E) {
;     ...
;       PG8_WAIT_V(8); PG8_WAIT_L(0); PG8_BAR; PG8_MMA(0, 0, At, B0); PG8_MMA(0, 1, At, B1); PG8_BAR; PG8_SCHED;
;       PG8_LDA(At, 1, 1); PG8_STAGE(PG8_SB(1, 0), b3, voffB); PG8_STAGE(PG8_SB(1, 1), b3 + hstepB, voffB); PG8_STAGE(PG8_SA(1, 0), a3, voffA);
;       PG8_WAIT_V(8); PG8_WAIT_L(0); PG8_BAR; PG8_MMA(1, 0, At, B0); PG8_MMA(1, 1, At, B1); PG8_BAR; PG8_SCHED;
;     }
;     if (wr == 0) PG8_BAR;
	s_waitcnt lgkmcnt(0)
	v_mfma_f32_16x16x32_bf16 v[120:123], v[128:131], v[176:179], v[120:123]
	v_mfma_f32_16x16x32_bf16 v[124:127], v[136:139], v[176:179], v[124:127]
	v_mfma_f32_16x16x32_bf16 v[104:107], v[128:131], v[184:187], v[104:107]
	v_mfma_f32_16x16x32_bf16 v[108:111], v[136:139], v[184:187], v[108:111]
	v_mfma_f32_16x16x32_bf16 v[88:91], v[128:131], v[202:205], v[88:91]
	v_mfma_f32_16x16x32_bf16 v[92:95], v[136:139], v[202:205], v[92:95]
	v_mfma_f32_16x16x32_bf16 v[72:75], v[128:131], v[214:217], v[72:75]
	v_mfma_f32_16x16x32_bf16 v[76:79], v[136:139], v[214:217], v[76:79]
	v_mfma_f32_16x16x32_bf16 v[120:123], v[132:135], v[180:183], v[120:123]
	v_mfma_f32_16x16x32_bf16 v[124:127], v[140:143], v[180:183], v[124:127]
	v_mfma_f32_16x16x32_bf16 v[104:107], v[132:135], v[198:201], v[104:107]
	v_mfma_f32_16x16x32_bf16 v[108:111], v[140:143], v[198:201], v[108:111]
	v_mfma_f32_16x16x32_bf16 v[88:91], v[132:135], v[206:209], v[88:91]
	v_mfma_f32_16x16x32_bf16 v[92:95], v[140:143], v[206:209], v[92:95]
	v_mfma_f32_16x16x32_bf16 v[72:75], v[132:135], v[218:221], v[72:75]
	v_mfma_f32_16x16x32_bf16 v[76:79], v[140:143], v[218:221], v[76:79]
	v_mfma_f32_16x16x32_bf16 v[112:115], v[144:147], v[176:179], v[112:115]
	v_mfma_f32_16x16x32_bf16 v[116:119], v[152:155], v[176:179], v[116:119]
	v_mfma_f32_16x16x32_bf16 v[96:99], v[144:147], v[184:187], v[96:99]
	v_mfma_f32_16x16x32_bf16 v[100:103], v[152:155], v[184:187], v[100:103]
	v_mfma_f32_16x16x32_bf16 v[80:83], v[144:147], v[202:205], v[80:83]
	v_mfma_f32_16x16x32_bf16 v[84:87], v[152:155], v[202:205], v[84:87]
	v_mfma_f32_16x16x32_bf16 v[64:67], v[144:147], v[214:217], v[64:67]
	v_mfma_f32_16x16x32_bf16 v[68:71], v[152:155], v[214:217], v[68:71]
	v_mfma_f32_16x16x32_bf16 v[112:115], v[148:151], v[180:183], v[112:115]
	v_mfma_f32_16x16x32_bf16 v[116:119], v[172:175], v[180:183], v[116:119]
	v_mfma_f32_16x16x32_bf16 v[96:99], v[148:151], v[198:201], v[96:99]
	v_mfma_f32_16x16x32_bf16 v[100:103], v[172:175], v[198:201], v[100:103]
	v_mfma_f32_16x16x32_bf16 v[80:83], v[148:151], v[206:209], v[80:83]
	v_mfma_f32_16x16x32_bf16 v[84:87], v[172:175], v[206:209], v[84:87]
	v_mfma_f32_16x16x32_bf16 v[64:67], v[148:151], v[218:221], v[64:67]
	v_mfma_f32_16x16x32_bf16 v[68:71], v[172:175], v[218:221], v[68:71]
	s_barrier
	s_add_i32 s0, s66, s2
	v_lshl_add_u64 v[188:189], v[188:189], 0, s[26:27]
	s_mov_b32 m0, s0
	ds_read_b128 v[176:179], v193 offset:49152
	ds_read_b128 v[180:183], v193 offset:50176
	ds_read_b128 v[184:187], v193 offset:51200
	ds_read_b128 v[198:201], v193 offset:52224
	ds_read_b128 v[202:205], v193 offset:53248
	ds_read_b128 v[206:209], v193 offset:54272
	ds_read_b128 v[214:217], v193 offset:55296
	ds_read_b128 v[218:221], v193 offset:56320
	global_load_lds_dwordx4 v[188:189], off
	s_add_i32 m0, s0, 0x2000
	s_add_u32 s0, s14, 0x30080
	v_lshl_add_u64 v[188:189], v[210:211], 0, s[26:27]
	s_addc_u32 s1, s15, 0
	s_add_i32 s14, s67, s2
	global_load_lds_dwordx4 v[188:189], off
	v_lshl_add_u64 v[188:189], s[0:1], 0, v[158:159]
	s_mov_b32 m0, s14
	s_nop 0
	global_load_lds_dwordx4 v[188:189], off
	v_lshl_add_u64 v[188:189], s[0:1], 0, v[162:163]
	s_add_i32 m0, s14, 0x2000
	s_nop 0
	global_load_lds_dwordx4 v[188:189], off
	v_lshl_add_u64 v[188:189], v[222:223], 0, s[26:27]
	s_mov_b32 m0, s19
	s_nop 0
	global_load_lds_dwordx4 v[188:189], off
	v_lshl_add_u64 v[188:189], v[224:225], 0, s[26:27]
	s_mov_b32 m0, s31
	s_nop 0
	global_load_lds_dwordx4 v[188:189], off
	s_waitcnt vmcnt(8)
	s_waitcnt lgkmcnt(0)
	s_barrier
	s_waitcnt lgkmcnt(0)
	v_mfma_f32_16x16x32_bf16 v[56:59], v[128:131], v[176:179], v[56:59]
	v_mfma_f32_16x16x32_bf16 v[60:63], v[136:139], v[176:179], v[60:63]
	v_mfma_f32_16x16x32_bf16 v[40:43], v[128:131], v[184:187], v[40:43]
	v_mfma_f32_16x16x32_bf16 v[44:47], v[136:139], v[184:187], v[44:47]
	v_mfma_f32_16x16x32_bf16 v[24:27], v[128:131], v[202:205], v[24:27]
	v_mfma_f32_16x16x32_bf16 v[28:31], v[136:139], v[202:205], v[28:31]
	v_mfma_f32_16x16x32_bf16 v[8:11], v[128:131], v[214:217], v[8:11]
	v_mfma_f32_16x16x32_bf16 v[12:15], v[136:139], v[214:217], v[12:15]
	v_mfma_f32_16x16x32_bf16 v[56:59], v[132:135], v[180:183], v[56:59]
	v_mfma_f32_16x16x32_bf16 v[60:63], v[140:143], v[180:183], v[60:63]
	v_mfma_f32_16x16x32_bf16 v[40:43], v[132:135], v[198:201], v[40:43]
	v_mfma_f32_16x16x32_bf16 v[44:47], v[140:143], v[198:201], v[44:47]
	v_mfma_f32_16x16x32_bf16 v[24:27], v[132:135], v[206:209], v[24:27]
	v_mfma_f32_16x16x32_bf16 v[28:31], v[140:143], v[206:209], v[28:31]
	v_mfma_f32_16x16x32_bf16 v[8:11], v[132:135], v[218:221], v[8:11]
	v_mfma_f32_16x16x32_bf16 v[12:15], v[140:143], v[218:221], v[12:15]
	v_mfma_f32_16x16x32_bf16 v[48:51], v[144:147], v[176:179], v[48:51]
	v_mfma_f32_16x16x32_bf16 v[52:55], v[152:155], v[176:179], v[52:55]
	v_mfma_f32_16x16x32_bf16 v[32:35], v[144:147], v[184:187], v[32:35]
	v_mfma_f32_16x16x32_bf16 v[36:39], v[152:155], v[184:187], v[36:39]
	v_mfma_f32_16x16x32_bf16 v[16:19], v[144:147], v[202:205], v[16:19]
	v_mfma_f32_16x16x32_bf16 v[20:23], v[152:155], v[202:205], v[20:23]
	v_mfma_f32_16x16x32_bf16 v[4:7], v[144:147], v[214:217], v[4:7]
	v_mfma_f32_16x16x32_bf16 v[0:3], v[152:155], v[214:217], v[0:3]
	v_mfma_f32_16x16x32_bf16 v[48:51], v[148:151], v[180:183], v[48:51]
	v_mfma_f32_16x16x32_bf16 v[52:55], v[172:175], v[180:183], v[52:55]
	v_mfma_f32_16x16x32_bf16 v[32:35], v[148:151], v[198:201], v[32:35]
	v_mfma_f32_16x16x32_bf16 v[36:39], v[172:175], v[198:201], v[36:39]
	v_mfma_f32_16x16x32_bf16 v[16:19], v[148:151], v[206:209], v[16:19]
	v_mfma_f32_16x16x32_bf16 v[20:23], v[172:175], v[206:209], v[20:23]
	v_mfma_f32_16x16x32_bf16 v[4:7], v[148:151], v[218:221], v[4:7]
	v_mfma_f32_16x16x32_bf16 v[0:3], v[172:175], v[218:221], v[0:3]
	s_barrier
	s_add_i32 s74, s74, 2
	s_add_u32 s72, s72, 0x100
	s_addc_u32 s73, s73, 0
	s_cmp_gt_u32 s74, 9
	s_mov_b64 s[0:1], s[12:13]
	s_cbranch_scc0 .LBB0_930
	s_and_b64 vcc, exec, s[28:29]
	s_cbranch_vccz .LBB0_933
	s_barrier

; #define PG8_STAGE(bufoff, gbase, voff) do { _Pragma("unroll") for (int _i = 0; _i < 2; ++_i) \
;     __builtin_amdgcn_global_load_lds((const unsigned*)((const char*)(gbase) + (voff)[_i]), (PG8_LAS unsigned*)(lds + (bufoff) + ldsw + _i * 8192), 16, 0, 0); } while (0)
; #define PG8_LDA(dst, b, h) do { _Pragma("unroll") for (int m = 0; m < 4; ++m) _Pragma("unroll") for (int k = 0; k < 2; ++k) dst[m][k] = *(const PG8_LAS bf16x8*)(lds + PG8_SA(b, h) + aoff + m * 2048 + k * 1024); } while (0)
; #define PG8_LDB(dst, b, h) do { _Pragma("unroll") for (int n = 0; n < 2; ++n) _Pragma("unroll") for (int k = 0; k < 2; ++k) dst[n][k] = *(const PG8_LAS bf16x8*)(lds + PG8_SB(b, h) + boff + n * 2048 + k * 1024); } while (0)
; #define PG8_MMA(ai, bj, At, Bt) do { __builtin_amdgcn_s_setprio(1); _Pragma("unroll") for (int m = 0; m < 4; ++m) _Pragma("unroll") for (int n = 0; n < 2; ++n) _Pragma("unroll") for (int k = 0; k < 2; ++k) \
;     acc[ai][bj][m][n] = __builtin_amdgcn_mfma_f32_16x16x32_bf16(Bt[n][k], At[m][k], acc[ai][bj][m][n], 0, 0, 0); __builtin_amdgcn_s_setprio(0); } while (0)
; #define PG8_BAR __builtin_amdgcn_s_barrier()
; template <class Epi, class Sched>
; DI void gemm_phase(PG8_LAS unsigned char* lds, const Gemm g, const Sched& S, const Epi& E) {
;     ...
;   for (;;) {
;     const bool has_next = S.next(ui + 1, nxt);
;     const char* nA = has_next ? (const char*)g.A + (size_t)nxt.pm * tstepA : cA; const char* nB = has_next ? (const char*)g.Bt + (size_t)nxt.pn * tstepB : cB;
; #pragma unroll 1
;     for (int t = 0; t < nt; t += 2) {
;       const bool last = (t == nt - 2);
;       const char* a1 = cA + (size_t)(t + 1) * kstep;
;       const char* a2 = last ? nA : cA + (size_t)(t + 2) * kstep; const char* b2 = last ? nB : cB + (size_t)(t + 2) * kstep;
;       const char* a3 = a2 + kstep; const char* b3 = b2 + kstep;
;       PG8_LDB(B0, 0, 0); PG8_LDB(B1, 0, 1); PG8_SCHED; PG8_LDA(At, 0, 0); PG8_STAGE(PG8_SA(1, 1), a1 + hstepA, voffA);
;       PG8_WAIT_V(8); PG8_WAIT_L(0); PG8_BAR; PG8_MMA(0, 0, At, B0); PG8_MMA(0, 1, At, B1); PG8_BAR; PG8_SCHED;
;     ...
; #pragma unroll
;     for (int a = 0; a < 2; ++a)
; #pragma unroll
;       for (int b = 0; b < 2; ++b)
; #pragma unroll
;         for (int m = 0; m < 4; ++m)
; #pragma unroll
;           for (int n = 0; n < 2; ++n) acc[a][b][m][n] = (f32x4){0.f, 0.f, 0.f, 0.f};
;     cur = nxt; cA = nA; cB = nB; ++ui;
.LBB0_1299:
	s_ashr_i32 s39, s38, 31
	s_lshl_b64 s[40:41], s[38:39], 19
	v_readlane_b32 s17, v254, 23
	s_add_u32 s40, s17, s40
	v_readlane_b32 s17, v254, 24
	s_addc_u32 s41, s17, s41
	s_and_b64 s[48:49], s[44:45], exec
	s_cselect_b32 s39, s41, s63
	s_cselect_b32 s59, s40, s62
	s_ashr_i32 s37, s36, 31
	s_lshl_b64 s[48:49], s[36:37], 19
	v_readlane_b32 s56, v254, 6
	v_readlane_b32 s57, v254, 7
	s_add_u32 s48, s56, s48
	s_addc_u32 s49, s57, s49
	s_and_b64 s[56:57], s[44:45], exec
	s_cselect_b32 s37, s49, s65
	s_cselect_b32 s61, s48, s64
	s_add_u32 s62, s62, 0x40080
	s_addc_u32 s63, s63, 0
	s_add_u32 s73, s64, 0x100
	v_mov_b32_e32 v0, 0
	s_addc_u32 s74, s65, 0
	s_mov_b32 s75, -2
	s_waitcnt lgkmcnt(0)
	v_mov_b32_e32 v1, v0
	v_mov_b32_e32 v2, v0
	v_mov_b32_e32 v3, v0
	v_mov_b32_e32 v4, v0
	v_mov_b32_e32 v5, v0
	v_mov_b32_e32 v6, v0
	v_mov_b32_e32 v7, v0
	v_mov_b32_e32 v16, v0
	v_mov_b32_e32 v17, v0
	v_mov_b32_e32 v18, v0
	v_mov_b32_e32 v19, v0
	v_mov_b32_e32 v20, v0
	v_mov_b32_e32 v21, v0
	v_mov_b32_e32 v22, v0
	v_mov_b32_e32 v23, v0
	v_mov_b32_e32 v32, v0
	v_mov_b32_e32 v33, v0
	v_mov_b32_e32 v34, v0
	v_mov_b32_e32 v35, v0
	v_mov_b32_e32 v36, v0
	v_mov_b32_e32 v37, v0
	v_mov_b32_e32 v38, v0
	v_mov_b32_e32 v39, v0
	v_mov_b32_e32 v48, v0
	v_mov_b32_e32 v49, v0
	v_mov_b32_e32 v50, v0
	v_mov_b32_e32 v51, v0
	v_mov_b32_e32 v52, v0
	v_mov_b32_e32 v53, v0
	v_mov_b32_e32 v54, v0
	v_mov_b32_e32 v55, v0
	v_mov_b32_e32 v8, v0
	v_mov_b32_e32 v9, v0
	v_mov_b32_e32 v10, v0
	v_mov_b32_e32 v11, v0
	v_mov_b32_e32 v12, v0
	v_mov_b32_e32 v13, v0
	v_mov_b32_e32 v14, v0
	v_mov_b32_e32 v15, v0
	v_mov_b32_e32 v24, v0
	v_mov_b32_e32 v25, v0
	v_mov_b32_e32 v26, v0
	v_mov_b32_e32 v27, v0
	v_mov_b32_e32 v28, v0
	v_mov_b32_e32 v29, v0
	v_mov_b32_e32 v30, v0
	v_mov_b32_e32 v31, v0
	v_mov_b32_e32 v40, v0
	v_mov_b32_e32 v41, v0
	v_mov_b32_e32 v42, v0
	v_mov_b32_e32 v43, v0
	v_mov_b32_e32 v44, v0
	v_mov_b32_e32 v45, v0
	v_mov_b32_e32 v46, v0
	v_mov_b32_e32 v47, v0
	v_mov_b32_e32 v56, v0
	v_mov_b32_e32 v57, v0
	v_mov_b32_e32 v58, v0
	v_mov_b32_e32 v59, v0
	v_mov_b32_e32 v60, v0
	v_mov_b32_e32 v61, v0
	v_mov_b32_e32 v62, v0
	v_mov_b32_e32 v63, v0
	v_mov_b32_e32 v64, v0
	v_mov_b32_e32 v65, v0
	v_mov_b32_e32 v66, v0
	v_mov_b32_e32 v67, v0
	v_mov_b32_e32 v68, v0
	v_mov_b32_e32 v69, v0
	v_mov_b32_e32 v70, v0
	v_mov_b32_e32 v71, v0
	v_mov_b32_e32 v80, v0
	v_mov_b32_e32 v81, v0
	v_mov_b32_e32 v82, v0
	v_mov_b32_e32 v83, v0
	v_mov_b32_e32 v84, v0
	v_mov_b32_e32 v85, v0
	v_mov_b32_e32 v86, v0
	v_mov_b32_e32 v87, v0
	v_mov_b32_e32 v96, v0
	v_mov_b32_e32 v97, v0
	v_mov_b32_e32 v98, v0
	v_mov_b32_e32 v99, v0
	v_mov_b32_e32 v100, v0
	v_mov_b32_e32 v101, v0
	v_mov_b32_e32 v102, v0
	v_mov_b32_e32 v103, v0
	s_waitcnt vmcnt(0)
	v_mov_b32_e32 v112, v0
	v_mov_b32_e32 v113, v0
	v_mov_b32_e32 v114, v0
	v_mov_b32_e32 v115, v0
	v_mov_b32_e32 v116, v0
	v_mov_b32_e32 v117, v0
	v_mov_b32_e32 v118, v0
	v_mov_b32_e32 v119, v0
	v_mov_b32_e32 v72, v0
	v_mov_b32_e32 v73, v0
	v_mov_b32_e32 v74, v0
	v_mov_b32_e32 v75, v0
	v_mov_b32_e32 v76, v0
	v_mov_b32_e32 v77, v0
	v_mov_b32_e32 v78, v0
	v_mov_b32_e32 v79, v0
	v_mov_b32_e32 v88, v0
	v_mov_b32_e32 v89, v0
	v_mov_b32_e32 v90, v0
	v_mov_b32_e32 v91, v0
	v_mov_b32_e32 v92, v0
	v_mov_b32_e32 v93, v0
	v_mov_b32_e32 v94, v0
	v_mov_b32_e32 v95, v0
	v_mov_b32_e32 v104, v0
	v_mov_b32_e32 v105, v0
	v_mov_b32_e32 v106, v0
	v_mov_b32_e32 v107, v0
	v_mov_b32_e32 v108, v0
	v_mov_b32_e32 v109, v0
	v_mov_b32_e32 v110, v0
	v_mov_b32_e32 v111, v0
	v_mov_b32_e32 v120, v0
	v_mov_b32_e32 v121, v0
	v_mov_b32_e32 v122, v0
	v_mov_b32_e32 v123, v0
	v_mov_b32_e32 v124, v0
	v_mov_b32_e32 v125, v0
	v_mov_b32_e32 v126, v0
	v_mov_b32_e32 v127, v0
	v_readfirstlane_b32 s100, v212
	s_nop 3
	s_lshr_b32 s100, s100, 8
	s_cmp_lg_u32 s100, 0
	s_cbranch_scc0 .Lgp_6
	s_setprio 1
.Lgp_6:
.LBB0_1300:
	ds_read_b128 v[128:131], v156
	ds_read_b128 v[132:135], v156 offset:1024
	ds_read_b128 v[150:153], v156 offset:2048
	ds_read_b128 v[162:165], v156 offset:3072
	ds_read_b128 v[166:169], v157
	ds_read_b128 v[170:173], v157 offset:1024
	ds_read_b128 v[174:177], v157 offset:2048
	ds_read_b128 v[178:181], v157 offset:3072
	s_add_u32 s17, s62, 0xfffc0080
	s_addc_u32 s33, s63, -1
	s_cmp_eq_u32 s75, 12
	s_cselect_b32 s67, s39, s33
	s_cselect_b32 s66, s59, s17
	s_cselect_b32 s65, s37, s74
	s_cselect_b32 s64, s61, s73
	v_lshl_add_u64 v[210:211], s[62:63], 0, v[146:147]
	s_add_i32 m0, s53, 0xc000
	ds_read_b128 v[182:185], v158
	ds_read_b128 v[186:189], v158 offset:1024
	ds_read_b128 v[190:193], v158 offset:2048
	ds_read_b128 v[194:197], v158 offset:3072
	ds_read_b128 v[198:201], v158 offset:4096
	ds_read_b128 v[202:205], v158 offset:5120
	ds_read_b128 v[206:209], v158 offset:6144
	ds_read_b128 v[214:217], v158 offset:7168
	global_load_lds_dwordx4 v[210:211], off
	v_lshl_add_u64 v[210:211], s[62:63], 0, v[148:149]
	s_add_i32 m0, s53, 0xe000
	s_nop 0
	global_load_lds_dwordx4 v[210:211], off
	s_waitcnt vmcnt(8)
	s_waitcnt lgkmcnt(0)
	s_barrier
; #define PG8_STAGE(bufoff, gbase, voff) do { _Pragma("unroll") for (int _i = 0; _i < 2; ++_i) \
;     __builtin_amdgcn_global_load_lds((const unsigned*)((const char*)(gbase) + (voff)[_i]), (PG8_LAS unsigned*)(lds + (bufoff) + ldsw + _i * 8192), 16, 0, 0); } while (0)
; #define PG8_LDA(dst, b, h) do { _Pragma("unroll") for (int m = 0; m < 4; ++m) _Pragma("unroll") for (int k = 0; k < 2; ++k) dst[m][k] = *(const PG8_LAS bf16x8*)(lds + PG8_SA(b, h) + aoff + m * 2048 + k * 1024); } while (0)
; #define PG8_MMA(ai, bj, At, Bt) do { __builtin_amdgcn_s_setprio(1); _Pragma("unroll") for (int m = 0; m < 4; ++m) _Pragma("unroll") for (int n = 0; n < 2; ++n) _Pragma("unroll") for (int k = 0; k < 2; ++k) \
;     acc[ai][bj][m][n] = __builtin_amdgcn_mfma_f32_16x16x32_bf16(Bt[n][k], At[m][k], acc[ai][bj][m][n], 0, 0, 0); __builtin_amdgcn_s_setprio(0); } while (0)
; #define PG8_WAIT_V(n) asm volatile("s_waitcnt vmcnt(" #n ")" ::: "memory")
; #define PG8_WAIT_L(n) asm volatile("s_waitcnt lgkmcnt(" #n ")" ::: "memory")
; #define PG8_BAR __builtin_amdgcn_s_barrier()
; #define PG8_SCHED __builtin_amdgcn_sched_barrier(0)
; template <class Epi, class Sched>
; DI void gemm_phase(PG8_LAS unsigned char* lds, const Gemm g, const Sched& S, const Epi& E) {
;     ...
;       PG8_WAIT_V(8); PG8_WAIT_L(0); PG8_BAR; PG8_MMA(0, 0, At, B0); PG8_MMA(0, 1, At, B1); PG8_BAR; PG8_SCHED;
;       PG8_LDA(At, 0, 1); PG8_STAGE(PG8_SB(0, 0), b2, voffB); PG8_STAGE(PG8_SB(0, 1), b2 + hstepB, voffB); PG8_STAGE(PG8_SA(0, 0), a2, voffA);
;       PG8_WAIT_V(8); PG8_WAIT_L(0); PG8_BAR; PG8_MMA(1, 0, At, B0); PG8_MMA(1, 1, At, B1); PG8_BAR; PG8_SCHED;
	s_waitcnt lgkmcnt(0)
	v_mfma_f32_16x16x32_bf16 v[124:127], v[128:131], v[182:185], v[124:127]
	v_mfma_f32_16x16x32_bf16 v[120:123], v[150:153], v[182:185], v[120:123]
	v_mfma_f32_16x16x32_bf16 v[108:111], v[128:131], v[190:193], v[108:111]
	v_mfma_f32_16x16x32_bf16 v[104:107], v[150:153], v[190:193], v[104:107]
	v_mfma_f32_16x16x32_bf16 v[92:95], v[128:131], v[198:201], v[92:95]
	v_mfma_f32_16x16x32_bf16 v[88:91], v[150:153], v[198:201], v[88:91]
	v_mfma_f32_16x16x32_bf16 v[76:79], v[128:131], v[206:209], v[76:79]
	v_mfma_f32_16x16x32_bf16 v[72:75], v[150:153], v[206:209], v[72:75]
	v_mfma_f32_16x16x32_bf16 v[124:127], v[132:135], v[186:189], v[124:127]
	v_mfma_f32_16x16x32_bf16 v[120:123], v[162:165], v[186:189], v[120:123]
	v_mfma_f32_16x16x32_bf16 v[108:111], v[132:135], v[194:197], v[108:111]
	v_mfma_f32_16x16x32_bf16 v[104:107], v[162:165], v[194:197], v[104:107]
	v_mfma_f32_16x16x32_bf16 v[92:95], v[132:135], v[202:205], v[92:95]
	v_mfma_f32_16x16x32_bf16 v[88:91], v[162:165], v[202:205], v[88:91]
	v_mfma_f32_16x16x32_bf16 v[76:79], v[132:135], v[214:217], v[76:79]
	v_mfma_f32_16x16x32_bf16 v[72:75], v[162:165], v[214:217], v[72:75]
	v_mfma_f32_16x16x32_bf16 v[116:119], v[166:169], v[182:185], v[116:119]
	v_mfma_f32_16x16x32_bf16 v[112:115], v[174:177], v[182:185], v[112:115]
	v_mfma_f32_16x16x32_bf16 v[100:103], v[166:169], v[190:193], v[100:103]
	v_mfma_f32_16x16x32_bf16 v[96:99], v[174:177], v[190:193], v[96:99]
	v_mfma_f32_16x16x32_bf16 v[84:87], v[166:169], v[198:201], v[84:87]
	v_mfma_f32_16x16x32_bf16 v[80:83], v[174:177], v[198:201], v[80:83]
	v_mfma_f32_16x16x32_bf16 v[68:71], v[166:169], v[206:209], v[68:71]
	v_mfma_f32_16x16x32_bf16 v[64:67], v[174:177], v[206:209], v[64:67]
	v_mfma_f32_16x16x32_bf16 v[116:119], v[170:173], v[186:189], v[116:119]
	v_mfma_f32_16x16x32_bf16 v[112:115], v[178:181], v[186:189], v[112:115]
	v_mfma_f32_16x16x32_bf16 v[100:103], v[170:173], v[194:197], v[100:103]
	v_mfma_f32_16x16x32_bf16 v[96:99], v[178:181], v[194:197], v[96:99]
	v_mfma_f32_16x16x32_bf16 v[84:87], v[170:173], v[202:205], v[84:87]
	v_mfma_f32_16x16x32_bf16 v[80:83], v[178:181], v[202:205], v[80:83]
	v_mfma_f32_16x16x32_bf16 v[68:71], v[170:173], v[214:217], v[68:71]
	v_mfma_f32_16x16x32_bf16 v[64:67], v[178:181], v[214:217], v[64:67]
	s_barrier
	s_add_i32 s17, s69, s16
	v_lshl_add_u64 v[210:211], s[64:65], 0, v[138:139]
	s_mov_b32 m0, s17
	ds_read_b128 v[182:185], v158 offset:16384
	ds_read_b128 v[186:189], v158 offset:17408
	ds_read_b128 v[190:193], v158 offset:18432
	ds_read_b128 v[194:197], v158 offset:19456
	ds_read_b128 v[198:201], v158 offset:20480
	ds_read_b128 v[202:205], v158 offset:21504
	ds_read_b128 v[206:209], v158 offset:22528
	ds_read_b128 v[214:217], v158 offset:23552
	global_load_lds_dwordx4 v[210:211], off
	s_add_i32 m0, s17, 0x2000
	s_add_u32 s56, s64, 0x40000
	v_lshl_add_u64 v[218:219], s[64:65], 0, v[142:143]
	s_addc_u32 s57, s65, 0
	s_add_i32 s17, s70, s16
	global_load_lds_dwordx4 v[218:219], off
	v_lshl_add_u64 v[220:221], s[56:57], 0, v[138:139]
	s_mov_b32 m0, s17
	v_lshl_add_u64 v[222:223], s[66:67], 0, v[140:141]
	global_load_lds_dwordx4 v[220:221], off
	v_lshl_add_u64 v[220:221], s[56:57], 0, v[142:143]
	s_add_i32 m0, s17, 0x2000
	s_nop 0
	global_load_lds_dwordx4 v[220:221], off
	v_lshl_add_u64 v[220:221], s[66:67], 0, v[136:137]
	s_mov_b32 m0, s53
	s_nop 0
	global_load_lds_dwordx4 v[220:221], off
	s_mov_b32 m0, s18
	s_nop 0
	global_load_lds_dwordx4 v[222:223], off
	s_waitcnt vmcnt(8)
	s_waitcnt lgkmcnt(0)
	s_barrier
	s_waitcnt lgkmcnt(0)
	v_mfma_f32_16x16x32_bf16 v[60:63], v[128:131], v[182:185], v[60:63]
	v_mfma_f32_16x16x32_bf16 v[56:59], v[150:153], v[182:185], v[56:59]
	v_mfma_f32_16x16x32_bf16 v[44:47], v[128:131], v[190:193], v[44:47]
	v_mfma_f32_16x16x32_bf16 v[40:43], v[150:153], v[190:193], v[40:43]
	v_mfma_f32_16x16x32_bf16 v[28:31], v[128:131], v[198:201], v[28:31]
	v_mfma_f32_16x16x32_bf16 v[24:27], v[150:153], v[198:201], v[24:27]
	v_mfma_f32_16x16x32_bf16 v[12:15], v[128:131], v[206:209], v[12:15]
	v_mfma_f32_16x16x32_bf16 v[8:11], v[150:153], v[206:209], v[8:11]
	v_mfma_f32_16x16x32_bf16 v[60:63], v[132:135], v[186:189], v[60:63]
	v_mfma_f32_16x16x32_bf16 v[56:59], v[162:165], v[186:189], v[56:59]
	v_mfma_f32_16x16x32_bf16 v[44:47], v[132:135], v[194:197], v[44:47]
	v_mfma_f32_16x16x32_bf16 v[40:43], v[162:165], v[194:197], v[40:43]
	v_mfma_f32_16x16x32_bf16 v[28:31], v[132:135], v[202:205], v[28:31]
	v_mfma_f32_16x16x32_bf16 v[24:27], v[162:165], v[202:205], v[24:27]
	v_mfma_f32_16x16x32_bf16 v[12:15], v[132:135], v[214:217], v[12:15]
	v_mfma_f32_16x16x32_bf16 v[8:11], v[162:165], v[214:217], v[8:11]
	v_mfma_f32_16x16x32_bf16 v[52:55], v[166:169], v[182:185], v[52:55]
	v_mfma_f32_16x16x32_bf16 v[48:51], v[174:177], v[182:185], v[48:51]
	v_mfma_f32_16x16x32_bf16 v[36:39], v[166:169], v[190:193], v[36:39]
	v_mfma_f32_16x16x32_bf16 v[32:35], v[174:177], v[190:193], v[32:35]
	v_mfma_f32_16x16x32_bf16 v[20:23], v[166:169], v[198:201], v[20:23]
	v_mfma_f32_16x16x32_bf16 v[16:19], v[174:177], v[198:201], v[16:19]
	v_mfma_f32_16x16x32_bf16 v[4:7], v[166:169], v[206:209], v[4:7]
	v_mfma_f32_16x16x32_bf16 v[0:3], v[174:177], v[206:209], v[0:3]
	v_mfma_f32_16x16x32_bf16 v[52:55], v[170:173], v[186:189], v[52:55]
	v_mfma_f32_16x16x32_bf16 v[48:51], v[178:181], v[186:189], v[48:51]
	v_mfma_f32_16x16x32_bf16 v[36:39], v[170:173], v[194:197], v[36:39]
	v_mfma_f32_16x16x32_bf16 v[32:35], v[178:181], v[194:197], v[32:35]
	v_mfma_f32_16x16x32_bf16 v[20:23], v[170:173], v[202:205], v[20:23]
	v_mfma_f32_16x16x32_bf16 v[16:19], v[178:181], v[202:205], v[16:19]
	v_mfma_f32_16x16x32_bf16 v[4:7], v[170:173], v[214:217], v[4:7]
	v_mfma_f32_16x16x32_bf16 v[0:3], v[178:181], v[214:217], v[0:3]
	s_barrier
; #define PG8_STAGE(bufoff, gbase, voff) do { _Pragma("unroll") for (int _i = 0; _i < 2; ++_i) \
;     __builtin_amdgcn_global_load_lds((const unsigned*)((const char*)(gbase) + (voff)[_i]), (PG8_LAS unsigned*)(lds + (bufoff) + ldsw + _i * 8192), 16, 0, 0); } while (0)
; #define PG8_LDA(dst, b, h) do { _Pragma("unroll") for (int m = 0; m < 4; ++m) _Pragma("unroll") for (int k = 0; k < 2; ++k) dst[m][k] = *(const PG8_LAS bf16x8*)(lds + PG8_SA(b, h) + aoff + m * 2048 + k * 1024); } while (0)
; #define PG8_LDB(dst, b, h) do { _Pragma("unroll") for (int n = 0; n < 2; ++n) _Pragma("unroll") for (int k = 0; k < 2; ++k) dst[n][k] = *(const PG8_LAS bf16x8*)(lds + PG8_SB(b, h) + boff + n * 2048 + k * 1024); } while (0)
; #define PG8_MMA(ai, bj, At, Bt) do { __builtin_amdgcn_s_setprio(1); _Pragma("unroll") for (int m = 0; m < 4; ++m) _Pragma("unroll") for (int n = 0; n < 2; ++n) _Pragma("unroll") for (int k = 0; k < 2; ++k) \
;     acc[ai][bj][m][n] = __builtin_amdgcn_mfma_f32_16x16x32_bf16(Bt[n][k], At[m][k], acc[ai][bj][m][n], 0, 0, 0); __builtin_amdgcn_s_setprio(0); } while (0)
; #define PG8_WAIT_V(n) asm volatile("s_waitcnt vmcnt(" #n ")" ::: "memory")
; #define PG8_WAIT_L(n) asm volatile("s_waitcnt lgkmcnt(" #n ")" ::: "memory")
; #define PG8_BAR __builtin_amdgcn_s_barrier()
; #define PG8_SCHED __builtin_amdgcn_sched_barrier(0)
; template <class Epi, class Sched>
; DI void gemm_phase(PG8_LAS unsigned char* lds, const Gemm g, const Sched& S, const Epi& E) {
;     ...
;       PG8_LDB(B0, 1, 0); PG8_LDB(B1, 1, 1); PG8_SCHED; PG8_LDA(At, 1, 0); PG8_STAGE(PG8_SA(0, 1), a2 + hstepA, voffA);
;       PG8_WAIT_V(8); PG8_WAIT_L(0); PG8_BAR; PG8_MMA(0, 0, At, B0); PG8_MMA(0, 1, At, B1); PG8_BAR; PG8_SCHED;
	s_mov_b32 s17, 0x18000
	s_addk_i32 s17, 0x110
	v_add_u32_e32 v161, s17, v155
	ds_read_b128 v[128:131], v161
	ds_read_b128 v[132:135], v161 offset:1024
	ds_read_b128 v[150:153], v161 offset:2048
	ds_read_b128 v[162:165], v161 offset:3072
	ds_read_b128 v[166:169], v160
	ds_read_b128 v[170:173], v160 offset:1024
	ds_read_b128 v[174:177], v160 offset:2048
	ds_read_b128 v[178:181], v160 offset:3072
	s_add_u32 s56, s66, 0x40000
	s_addc_u32 s57, s67, 0
	s_mov_b32 m0, s19
	v_lshl_add_u64 v[224:225], s[56:57], 0, v[136:137]
	ds_read_b128 v[182:185], v158 offset:32768
	ds_read_b128 v[186:189], v158 offset:33792
	ds_read_b128 v[190:193], v158 offset:34816
	ds_read_b128 v[194:197], v158 offset:35840
	ds_read_b128 v[198:201], v158 offset:36864
	ds_read_b128 v[202:205], v158 offset:37888
	ds_read_b128 v[206:209], v158 offset:38912
	ds_read_b128 v[214:217], v158 offset:39936
	global_load_lds_dwordx4 v[224:225], off
	v_lshl_add_u64 v[224:225], s[56:57], 0, v[140:141]
	s_mov_b32 m0, s54
	s_nop 0
	global_load_lds_dwordx4 v[224:225], off
	s_waitcnt vmcnt(8)
	s_waitcnt lgkmcnt(0)
	s_barrier
	s_waitcnt lgkmcnt(0)
	v_mfma_f32_16x16x32_bf16 v[124:127], v[128:131], v[182:185], v[124:127]
	v_mfma_f32_16x16x32_bf16 v[120:123], v[150:153], v[182:185], v[120:123]
	v_mfma_f32_16x16x32_bf16 v[108:111], v[128:131], v[190:193], v[108:111]
	v_mfma_f32_16x16x32_bf16 v[104:107], v[150:153], v[190:193], v[104:107]
	v_mfma_f32_16x16x32_bf16 v[92:95], v[128:131], v[198:201], v[92:95]
	v_mfma_f32_16x16x32_bf16 v[88:91], v[150:153], v[198:201], v[88:91]
	v_mfma_f32_16x16x32_bf16 v[76:79], v[128:131], v[206:209], v[76:79]
	v_mfma_f32_16x16x32_bf16 v[72:75], v[150:153], v[206:209], v[72:75]
	v_mfma_f32_16x16x32_bf16 v[124:127], v[132:135], v[186:189], v[124:127]
	v_mfma_f32_16x16x32_bf16 v[120:123], v[162:165], v[186:189], v[120:123]
	v_mfma_f32_16x16x32_bf16 v[108:111], v[132:135], v[194:197], v[108:111]
	v_mfma_f32_16x16x32_bf16 v[104:107], v[162:165], v[194:197], v[104:107]
	v_mfma_f32_16x16x32_bf16 v[92:95], v[132:135], v[202:205], v[92:95]
	v_mfma_f32_16x16x32_bf16 v[88:91], v[162:165], v[202:205], v[88:91]
	v_mfma_f32_16x16x32_bf16 v[76:79], v[132:135], v[214:217], v[76:79]
	v_mfma_f32_16x16x32_bf16 v[72:75], v[162:165], v[214:217], v[72:75]
	v_mfma_f32_16x16x32_bf16 v[116:119], v[166:169], v[182:185], v[116:119]
	v_mfma_f32_16x16x32_bf16 v[112:115], v[174:177], v[182:185], v[112:115]
	v_mfma_f32_16x16x32_bf16 v[100:103], v[166:169], v[190:193], v[100:103]
	v_mfma_f32_16x16x32_bf16 v[96:99], v[174:177], v[190:193], v[96:99]
	v_mfma_f32_16x16x32_bf16 v[84:87], v[166:169], v[198:201], v[84:87]
	v_mfma_f32_16x16x32_bf16 v[80:83], v[174:177], v[198:201], v[80:83]
	v_mfma_f32_16x16x32_bf16 v[68:71], v[166:169], v[206:209], v[68:71]
	v_mfma_f32_16x16x32_bf16 v[64:67], v[174:177], v[206:209], v[64:67]
	v_mfma_f32_16x16x32_bf16 v[116:119], v[170:173], v[186:189], v[116:119]
	v_mfma_f32_16x16x32_bf16 v[112:115], v[178:181], v[186:189], v[112:115]
	v_mfma_f32_16x16x32_bf16 v[100:103], v[170:173], v[194:197], v[100:103]
	v_mfma_f32_16x16x32_bf16 v[96:99], v[178:181], v[194:197], v[96:99]
	v_mfma_f32_16x16x32_bf16 v[84:87], v[170:173], v[202:205], v[84:87]
	v_mfma_f32_16x16x32_bf16 v[80:83], v[178:181], v[202:205], v[80:83]
	v_mfma_f32_16x16x32_bf16 v[68:71], v[170:173], v[214:217], v[68:71]
	v_mfma_f32_16x16x32_bf16 v[64:67], v[178:181], v[214:217], v[64:67]
	s_barrier
; #define PG8_STAGE(bufoff, gbase, voff) do { _Pragma("unroll") for (int _i = 0; _i < 2; ++_i) \
;     __builtin_amdgcn_global_load_lds((const unsigned*)((const char*)(gbase) + (voff)[_i]), (PG8_LAS unsigned*)(lds + (bufoff) + ldsw + _i * 8192), 16, 0, 0); } while (0)
; #define PG8_LDA(dst, b, h) do { _Pragma("unroll") for (int m = 0; m < 4; ++m) _Pragma("unroll") for (int k = 0; k < 2; ++k) dst[m][k] = *(const PG8_LAS bf16x8*)(lds + PG8_SA(b, h) + aoff + m * 2048 + k * 1024); } while (0)
; #define PG8_MMA(ai, bj, At, Bt) do { __builtin_amdgcn_s_setprio(1); _Pragma("unroll") for (int m = 0; m < 4; ++m) _Pragma("unroll") for (int n = 0; n < 2; ++n) _Pragma("unroll") for (int k = 0; k < 2; ++k) \
;     acc[ai][bj][m][n] = __builtin_amdgcn_mfma_f32_16x16x32_bf16(Bt[n][k], At[m][k], acc[ai][bj][m][n], 0, 0, 0); __builtin_amdgcn_s_setprio(0); } while (0)
; #define PG8_WAIT_V(n) asm volatile("s_waitcnt vmcnt(" #n ")" ::: "memory")
; #define PG8_WAIT_L(n) asm volatile("s_waitcnt lgkmcnt(" #n ")" ::: "memory")
; #define PG8_BAR __builtin_amdgcn_s_barrier()
; #define PG8_SCHED __builtin_amdgcn_sched_barrier(0)
;   DI void operator()(const f32x4 (&acc)[2][2][4][2], const Unit& u, int wr, int wc, int fr, int fq) const {
;     ...
;     RES_LD(0)
; template <class Epi, class Sched>
; DI void gemm_phase(PG8_LAS unsigned char* lds, const Gemm g, const Sched& S, const Epi& E) {
;     ...
;       PG8_LDA(At, 1, 1); PG8_STAGE(PG8_SB(1, 0), b3, voffB); PG8_STAGE(PG8_SB(1, 1), b3 + hstepB, voffB); PG8_STAGE(PG8_SA(1, 0), a3, voffA);
;       PG8_WAIT_V(8); PG8_WAIT_L(0); PG8_BAR; PG8_MMA(1, 0, At, B0); PG8_MMA(1, 1, At, B1); PG8_BAR; PG8_SCHED;
;     }
	s_add_i32 s17, s17, s16
	v_lshl_add_u64 v[210:211], v[210:211], 0, s[6:7]
	s_mov_b32 m0, s17
	ds_read_b128 v[182:185], v158 offset:49152
	ds_read_b128 v[186:189], v158 offset:50176
	ds_read_b128 v[190:193], v158 offset:51200
	ds_read_b128 v[194:197], v158 offset:52224
	ds_read_b128 v[198:201], v158 offset:53248
	ds_read_b128 v[202:205], v158 offset:54272
	ds_read_b128 v[206:209], v158 offset:55296
	ds_read_b128 v[214:217], v158 offset:56320
	global_load_lds_dwordx4 v[210:211], off
	s_add_i32 m0, s17, 0x2000
	s_add_u32 s56, s64, 0x40080
	v_lshl_add_u64 v[210:211], v[218:219], 0, s[6:7]
	s_addc_u32 s57, s65, 0
	s_add_i32 s17, s71, s16
	global_load_lds_dwordx4 v[210:211], off
	v_lshl_add_u64 v[210:211], s[56:57], 0, v[138:139]
	s_mov_b32 m0, s17
	s_nop 0
	global_load_lds_dwordx4 v[210:211], off
	v_lshl_add_u64 v[210:211], s[56:57], 0, v[142:143]
	s_add_i32 m0, s17, 0x2000
	s_nop 0
	global_load_lds_dwordx4 v[210:211], off
	v_lshl_add_u64 v[210:211], v[220:221], 0, s[6:7]
	s_mov_b32 m0, s5
	s_nop 0
	global_load_lds_dwordx4 v[210:211], off
	v_lshl_add_u64 v[210:211], v[222:223], 0, s[6:7]
	s_mov_b32 m0, s55
	s_nop 0
	global_load_lds_dwordx4 v[210:211], off
	s_waitcnt vmcnt(8)
	s_waitcnt lgkmcnt(0)
	s_barrier
	s_waitcnt lgkmcnt(0)
	v_mfma_f32_16x16x32_bf16 v[60:63], v[128:131], v[182:185], v[60:63]
	v_mfma_f32_16x16x32_bf16 v[56:59], v[150:153], v[182:185], v[56:59]
	v_mfma_f32_16x16x32_bf16 v[44:47], v[128:131], v[190:193], v[44:47]
	v_mfma_f32_16x16x32_bf16 v[40:43], v[150:153], v[190:193], v[40:43]
	v_mfma_f32_16x16x32_bf16 v[28:31], v[128:131], v[198:201], v[28:31]
	v_mfma_f32_16x16x32_bf16 v[24:27], v[150:153], v[198:201], v[24:27]
	v_mfma_f32_16x16x32_bf16 v[12:15], v[128:131], v[206:209], v[12:15]
	v_mfma_f32_16x16x32_bf16 v[8:11], v[150:153], v[206:209], v[8:11]
	v_mfma_f32_16x16x32_bf16 v[60:63], v[132:135], v[186:189], v[60:63]
	v_mfma_f32_16x16x32_bf16 v[56:59], v[162:165], v[186:189], v[56:59]
	v_mfma_f32_16x16x32_bf16 v[44:47], v[132:135], v[194:197], v[44:47]
	v_mfma_f32_16x16x32_bf16 v[40:43], v[162:165], v[194:197], v[40:43]
	v_mfma_f32_16x16x32_bf16 v[28:31], v[132:135], v[202:205], v[28:31]
	v_mfma_f32_16x16x32_bf16 v[24:27], v[162:165], v[202:205], v[24:27]
	v_mfma_f32_16x16x32_bf16 v[12:15], v[132:135], v[214:217], v[12:15]
	v_mfma_f32_16x16x32_bf16 v[8:11], v[162:165], v[214:217], v[8:11]
	v_mfma_f32_16x16x32_bf16 v[52:55], v[166:169], v[182:185], v[52:55]
	v_mfma_f32_16x16x32_bf16 v[48:51], v[174:177], v[182:185], v[48:51]
	v_mfma_f32_16x16x32_bf16 v[36:39], v[166:169], v[190:193], v[36:39]
	v_mfma_f32_16x16x32_bf16 v[32:35], v[174:177], v[190:193], v[32:35]
	v_mfma_f32_16x16x32_bf16 v[20:23], v[166:169], v[198:201], v[20:23]
	v_mfma_f32_16x16x32_bf16 v[16:19], v[174:177], v[198:201], v[16:19]
	v_mfma_f32_16x16x32_bf16 v[4:7], v[166:169], v[206:209], v[4:7]
	v_mfma_f32_16x16x32_bf16 v[0:3], v[174:177], v[206:209], v[0:3]
	v_mfma_f32_16x16x32_bf16 v[52:55], v[170:173], v[186:189], v[52:55]
	v_mfma_f32_16x16x32_bf16 v[48:51], v[178:181], v[186:189], v[48:51]
	v_mfma_f32_16x16x32_bf16 v[36:39], v[170:173], v[194:197], v[36:39]
	v_mfma_f32_16x16x32_bf16 v[32:35], v[178:181], v[194:197], v[32:35]
	v_mfma_f32_16x16x32_bf16 v[20:23], v[170:173], v[202:205], v[20:23]
	v_mfma_f32_16x16x32_bf16 v[16:19], v[178:181], v[202:205], v[16:19]
	v_mfma_f32_16x16x32_bf16 v[4:7], v[170:173], v[214:217], v[4:7]
	v_mfma_f32_16x16x32_bf16 v[0:3], v[178:181], v[214:217], v[0:3]
	s_barrier
	s_add_i32 s75, s75, 2
	s_add_u32 s62, s62, 0x100
	s_addc_u32 s63, s63, 0
	s_add_u32 s73, s73, 0x100
	s_addc_u32 s74, s74, 0
	s_cmp_gt_u32 s75, 13
	s_cbranch_scc0 .LBB0_1300
	v_lshl_add_u32 v152, s60, 8, v154
	v_ashrrev_i32_e32 v153, 31, v152
	s_lshl_b32 s56, s58, 8
	v_lshlrev_b64 v[128:129], 11, v[152:153]
	s_ashr_i32 s57, s56, 31
	v_lshl_add_u64 v[128:129], s[50:51], 0, v[128:129]
	v_lshl_add_u64 v[128:129], s[56:57], 1, v[128:129]
	v_lshl_add_u64 v[128:129], v[128:129], 0, s[10:11]
	v_lshl_add_u64 v[150:151], v[128:129], 0, v[144:145]
	s_mov_b32 s17, 0x8000
	v_add_co_u32_e32 v128, vcc, s17, v150
	global_load_dwordx4 v[164:167], v[150:151], off
	global_load_dwordx4 v[168:171], v[150:151], off offset:256
	v_addc_co_u32_e32 v129, vcc, 0, v151, vcc
	global_load_dwordx4 v[132:135], v[128:129], off
	s_nop 0
	global_load_dwordx4 v[128:131], v[128:129], off offset:256
	s_and_b64 vcc, exec, s[8:9]
	s_cbranch_vccz .LBB0_1303
	s_barrier

; #define PG8_STAGE(bufoff, gbase, voff) do { _Pragma("unroll") for (int _i = 0; _i < 2; ++_i) \
;     __builtin_amdgcn_global_load_lds((const unsigned*)((const char*)(gbase) + (voff)[_i]), (PG8_LAS unsigned*)(lds + (bufoff) + ldsw + _i * 8192), 16, 0, 0); } while (0)
; #define PG8_LDA(dst, b, h) do { _Pragma("unroll") for (int m = 0; m < 4; ++m) _Pragma("unroll") for (int k = 0; k < 2; ++k) dst[m][k] = *(const PG8_LAS bf16x8*)(lds + PG8_SA(b, h) + aoff + m * 2048 + k * 1024); } while (0)
; #define PG8_LDB(dst, b, h) do { _Pragma("unroll") for (int n = 0; n < 2; ++n) _Pragma("unroll") for (int k = 0; k < 2; ++k) dst[n][k] = *(const PG8_LAS bf16x8*)(lds + PG8_SB(b, h) + boff + n * 2048 + k * 1024); } while (0)
; #define PG8_MMA(ai, bj, At, Bt) do { __builtin_amdgcn_s_setprio(1); _Pragma("unroll") for (int m = 0; m < 4; ++m) _Pragma("unroll") for (int n = 0; n < 2; ++n) _Pragma("unroll") for (int k = 0; k < 2; ++k) \
;     acc[ai][bj][m][n] = __builtin_amdgcn_mfma_f32_16x16x32_bf16(Bt[n][k], At[m][k], acc[ai][bj][m][n], 0, 0, 0); __builtin_amdgcn_s_setprio(0); } while (0)
; #define PG8_BAR __builtin_amdgcn_s_barrier()
; template <class Epi, class Sched>
; DI void gemm_phase(PG8_LAS unsigned char* lds, const Gemm g, const Sched& S, const Epi& E) {
;     ...
;   for (;;) {
;     const bool has_next = S.next(ui + 1, nxt);
;     const char* nA = has_next ? (const char*)g.A + (size_t)nxt.pm * tstepA : cA; const char* nB = has_next ? (const char*)g.Bt + (size_t)nxt.pn * tstepB : cB;
; #pragma unroll 1
;     for (int t = 0; t < nt; t += 2) {
;       const bool last = (t == nt - 2);
;       const char* a1 = cA + (size_t)(t + 1) * kstep;
;       const char* a2 = last ? nA : cA + (size_t)(t + 2) * kstep; const char* b2 = last ? nB : cB + (size_t)(t + 2) * kstep;
;       const char* a3 = a2 + kstep; const char* b3 = b2 + kstep;
;       PG8_LDB(B0, 0, 0); PG8_LDB(B1, 0, 1); PG8_SCHED; PG8_LDA(At, 0, 0); PG8_STAGE(PG8_SA(1, 1), a1 + hstepA, voffA);
;       PG8_WAIT_V(8); PG8_WAIT_L(0); PG8_BAR; PG8_MMA(0, 0, At, B0); PG8_MMA(0, 1, At, B1); PG8_BAR; PG8_SCHED;
;     ...
; #pragma unroll
;     for (int a = 0; a < 2; ++a)
; #pragma unroll
;       for (int b = 0; b < 2; ++b)
; #pragma unroll
;         for (int m = 0; m < 4; ++m)
; #pragma unroll
;           for (int n = 0; n < 2; ++n) acc[a][b][m][n] = (f32x4){0.f, 0.f, 0.f, 0.f};
;     cur = nxt; cA = nA; cB = nB; ++ui;
.LBB0_1383:
	s_ashr_i32 s23, s22, 31
	s_lshl_b64 s[26:27], s[22:23], 19
	s_add_u32 s26, s50, s26
	s_addc_u32 s27, s51, s27
	s_and_b64 s[28:29], s[24:25], exec
	s_cselect_b32 s1, s27, s3
	s_cselect_b32 s23, s26, s2
	s_ashr_i32 s21, s20, 31
	s_lshl_b64 s[28:29], s[20:21], 19
	v_readlane_b32 s34, v254, 10
	v_readlane_b32 s35, v254, 11
	s_add_u32 s28, s34, s28
	s_addc_u32 s29, s35, s29
	s_and_b64 s[34:35], s[24:25], exec
	s_cselect_b32 s21, s29, s31
	s_cselect_b32 s49, s28, s30
	s_add_u32 s2, s2, 0x40080
	s_addc_u32 s3, s3, 0
	s_add_u32 s53, s30, 0x100
	v_mov_b32_e32 v0, 0
	s_addc_u32 s54, s31, 0
	s_mov_b32 s55, -2
	v_mov_b32_e32 v1, v0
	v_mov_b32_e32 v2, v0
	v_mov_b32_e32 v3, v0
	v_mov_b32_e32 v4, v0
	v_mov_b32_e32 v5, v0
	v_mov_b32_e32 v6, v0
	v_mov_b32_e32 v7, v0
	v_mov_b32_e32 v16, v0
	v_mov_b32_e32 v17, v0
	v_mov_b32_e32 v18, v0
	v_mov_b32_e32 v19, v0
	v_mov_b32_e32 v20, v0
	v_mov_b32_e32 v21, v0
	v_mov_b32_e32 v22, v0
	v_mov_b32_e32 v23, v0
	v_mov_b32_e32 v32, v0
	v_mov_b32_e32 v33, v0
	v_mov_b32_e32 v34, v0
	v_mov_b32_e32 v35, v0
	v_mov_b32_e32 v36, v0
	v_mov_b32_e32 v37, v0
	v_mov_b32_e32 v38, v0
	v_mov_b32_e32 v39, v0
	v_mov_b32_e32 v48, v0
	v_mov_b32_e32 v49, v0
	v_mov_b32_e32 v50, v0
	v_mov_b32_e32 v51, v0
	v_mov_b32_e32 v52, v0
	v_mov_b32_e32 v53, v0
	v_mov_b32_e32 v54, v0
	v_mov_b32_e32 v55, v0
	v_mov_b32_e32 v8, v0
	v_mov_b32_e32 v9, v0
	v_mov_b32_e32 v10, v0
	v_mov_b32_e32 v11, v0
	v_mov_b32_e32 v12, v0
	v_mov_b32_e32 v13, v0
	v_mov_b32_e32 v14, v0
	v_mov_b32_e32 v15, v0
	v_mov_b32_e32 v24, v0
	v_mov_b32_e32 v25, v0
	v_mov_b32_e32 v26, v0
	v_mov_b32_e32 v27, v0
	v_mov_b32_e32 v28, v0
	v_mov_b32_e32 v29, v0
	v_mov_b32_e32 v30, v0
	v_mov_b32_e32 v31, v0
	v_mov_b32_e32 v40, v0
	v_mov_b32_e32 v41, v0
	v_mov_b32_e32 v42, v0
	v_mov_b32_e32 v43, v0
	v_mov_b32_e32 v44, v0
	v_mov_b32_e32 v45, v0
	v_mov_b32_e32 v46, v0
	v_mov_b32_e32 v47, v0
	v_mov_b32_e32 v56, v0
	v_mov_b32_e32 v57, v0
	v_mov_b32_e32 v58, v0
	v_mov_b32_e32 v59, v0
	v_mov_b32_e32 v60, v0
	v_mov_b32_e32 v61, v0
	v_mov_b32_e32 v62, v0
	v_mov_b32_e32 v63, v0
	v_mov_b32_e32 v64, v0
	v_mov_b32_e32 v65, v0
	v_mov_b32_e32 v66, v0
	v_mov_b32_e32 v67, v0
	v_mov_b32_e32 v68, v0
	v_mov_b32_e32 v69, v0
	v_mov_b32_e32 v70, v0
	v_mov_b32_e32 v71, v0
	v_mov_b32_e32 v80, v0
	v_mov_b32_e32 v81, v0
	v_mov_b32_e32 v82, v0
	v_mov_b32_e32 v83, v0
	v_mov_b32_e32 v84, v0
	v_mov_b32_e32 v85, v0
	v_mov_b32_e32 v86, v0
	v_mov_b32_e32 v87, v0
	v_mov_b32_e32 v96, v0
	v_mov_b32_e32 v97, v0
	v_mov_b32_e32 v98, v0
	v_mov_b32_e32 v99, v0
	v_mov_b32_e32 v100, v0
	v_mov_b32_e32 v101, v0
	v_mov_b32_e32 v102, v0
	v_mov_b32_e32 v103, v0
	s_waitcnt vmcnt(0)
	v_mov_b32_e32 v112, v0
	v_mov_b32_e32 v113, v0
	v_mov_b32_e32 v114, v0
	v_mov_b32_e32 v115, v0
	v_mov_b32_e32 v116, v0
	v_mov_b32_e32 v117, v0
	v_mov_b32_e32 v118, v0
	v_mov_b32_e32 v119, v0
	v_mov_b32_e32 v72, v0
	v_mov_b32_e32 v73, v0
	v_mov_b32_e32 v74, v0
	v_mov_b32_e32 v75, v0
	v_mov_b32_e32 v76, v0
	v_mov_b32_e32 v77, v0
	v_mov_b32_e32 v78, v0
	v_mov_b32_e32 v79, v0
	v_mov_b32_e32 v88, v0
	v_mov_b32_e32 v89, v0
	v_mov_b32_e32 v90, v0
	v_mov_b32_e32 v91, v0
	v_mov_b32_e32 v92, v0
	v_mov_b32_e32 v93, v0
	v_mov_b32_e32 v94, v0
	v_mov_b32_e32 v95, v0
	v_mov_b32_e32 v104, v0
	v_mov_b32_e32 v105, v0
	v_mov_b32_e32 v106, v0
	v_mov_b32_e32 v107, v0
	v_mov_b32_e32 v108, v0
	v_mov_b32_e32 v109, v0
	v_mov_b32_e32 v110, v0
	v_mov_b32_e32 v111, v0
	v_mov_b32_e32 v120, v0
	v_mov_b32_e32 v121, v0
	v_mov_b32_e32 v122, v0
	v_mov_b32_e32 v123, v0
	v_mov_b32_e32 v124, v0
	v_mov_b32_e32 v125, v0
	v_mov_b32_e32 v126, v0
	v_mov_b32_e32 v127, v0
	v_readfirstlane_b32 s100, v212
	s_nop 3
	s_lshr_b32 s100, s100, 8
	s_cmp_lg_u32 s100, 0
	s_cbranch_scc0 .Lgp_7
	s_setprio 1
.Lgp_7:
.LBB0_1384:
	ds_read_b128 v[144:147], v155
	ds_read_b128 v[156:159], v155 offset:1024
	ds_read_b128 v[174:177], v155 offset:2048
	ds_read_b128 v[178:181], v155 offset:3072
	ds_read_b128 v[182:185], v161
	ds_read_b128 v[186:189], v161 offset:1024
	ds_read_b128 v[190:193], v161 offset:2048
	ds_read_b128 v[194:197], v161 offset:3072
	s_add_u32 s30, s2, 0xfffc0080
	s_addc_u32 s31, s3, -1
	s_cmp_eq_u32 s55, 12
	s_cselect_b32 s35, s1, s31
	s_cselect_b32 s34, s23, s30
	s_cselect_b32 s31, s21, s54
	s_cselect_b32 s30, s49, s53
	v_lshl_add_u64 v[148:149], s[2:3], 0, v[140:141]
	s_add_i32 m0, s17, 0xc000
	ds_read_b128 v[198:201], v165
	ds_read_b128 v[202:205], v165 offset:1024
	ds_read_b128 v[206:209], v165 offset:2048
	ds_read_b128 v[214:217], v165 offset:3072
	ds_read_b128 v[218:221], v165 offset:4096
	ds_read_b128 v[222:225], v165 offset:5120
	ds_read_b128 v[226:229], v165 offset:6144
	ds_read_b128 v[230:233], v165 offset:7168
	global_load_lds_dwordx4 v[148:149], off
	v_lshl_add_u64 v[148:149], s[2:3], 0, v[142:143]
	s_add_i32 m0, s17, 0xe000
	s_nop 0
	global_load_lds_dwordx4 v[148:149], off
	s_waitcnt vmcnt(8)
	s_waitcnt lgkmcnt(0)
	s_barrier
; #define PG8_STAGE(bufoff, gbase, voff) do { _Pragma("unroll") for (int _i = 0; _i < 2; ++_i) \
;     __builtin_amdgcn_global_load_lds((const unsigned*)((const char*)(gbase) + (voff)[_i]), (PG8_LAS unsigned*)(lds + (bufoff) + ldsw + _i * 8192), 16, 0, 0); } while (0)
; #define PG8_LDA(dst, b, h) do { _Pragma("unroll") for (int m = 0; m < 4; ++m) _Pragma("unroll") for (int k = 0; k < 2; ++k) dst[m][k] = *(const PG8_LAS bf16x8*)(lds + PG8_SA(b, h) + aoff + m * 2048 + k * 1024); } while (0)
; #define PG8_MMA(ai, bj, At, Bt) do { __builtin_amdgcn_s_setprio(1); _Pragma("unroll") for (int m = 0; m < 4; ++m) _Pragma("unroll") for (int n = 0; n < 2; ++n) _Pragma("unroll") for (int k = 0; k < 2; ++k) \
;     acc[ai][bj][m][n] = __builtin_amdgcn_mfma_f32_16x16x32_bf16(Bt[n][k], At[m][k], acc[ai][bj][m][n], 0, 0, 0); __builtin_amdgcn_s_setprio(0); } while (0)
; #define PG8_WAIT_V(n) asm volatile("s_waitcnt vmcnt(" #n ")" ::: "memory")
; #define PG8_WAIT_L(n) asm volatile("s_waitcnt lgkmcnt(" #n ")" ::: "memory")
; #define PG8_BAR __builtin_amdgcn_s_barrier()
; #define PG8_SCHED __builtin_amdgcn_sched_barrier(0)
; template <class Epi, class Sched>
; DI void gemm_phase(PG8_LAS unsigned char* lds, const Gemm g, const Sched& S, const Epi& E) {
;     ...
;       PG8_WAIT_V(8); PG8_WAIT_L(0); PG8_BAR; PG8_MMA(0, 0, At, B0); PG8_MMA(0, 1, At, B1); PG8_BAR; PG8_SCHED;
;       PG8_LDA(At, 0, 1); PG8_STAGE(PG8_SB(0, 0), b2, voffB); PG8_STAGE(PG8_SB(0, 1), b2 + hstepB, voffB); PG8_STAGE(PG8_SA(0, 0), a2, voffA);
;       PG8_WAIT_V(8); PG8_WAIT_L(0); PG8_BAR; PG8_MMA(1, 0, At, B0); PG8_MMA(1, 1, At, B1); PG8_BAR; PG8_SCHED;
	s_waitcnt lgkmcnt(0)
	v_mfma_f32_16x16x32_bf16 v[124:127], v[144:147], v[198:201], v[124:127]
	v_mfma_f32_16x16x32_bf16 v[120:123], v[174:177], v[198:201], v[120:123]
	v_mfma_f32_16x16x32_bf16 v[108:111], v[144:147], v[206:209], v[108:111]
	v_mfma_f32_16x16x32_bf16 v[104:107], v[174:177], v[206:209], v[104:107]
	v_mfma_f32_16x16x32_bf16 v[92:95], v[144:147], v[218:221], v[92:95]
	v_mfma_f32_16x16x32_bf16 v[88:91], v[174:177], v[218:221], v[88:91]
	v_mfma_f32_16x16x32_bf16 v[76:79], v[144:147], v[226:229], v[76:79]
	v_mfma_f32_16x16x32_bf16 v[72:75], v[174:177], v[226:229], v[72:75]
	v_mfma_f32_16x16x32_bf16 v[124:127], v[156:159], v[202:205], v[124:127]
	v_mfma_f32_16x16x32_bf16 v[120:123], v[178:181], v[202:205], v[120:123]
	v_mfma_f32_16x16x32_bf16 v[108:111], v[156:159], v[214:217], v[108:111]
	v_mfma_f32_16x16x32_bf16 v[104:107], v[178:181], v[214:217], v[104:107]
	v_mfma_f32_16x16x32_bf16 v[92:95], v[156:159], v[222:225], v[92:95]
	v_mfma_f32_16x16x32_bf16 v[88:91], v[178:181], v[222:225], v[88:91]
	v_mfma_f32_16x16x32_bf16 v[76:79], v[156:159], v[230:233], v[76:79]
	v_mfma_f32_16x16x32_bf16 v[72:75], v[178:181], v[230:233], v[72:75]
	v_mfma_f32_16x16x32_bf16 v[116:119], v[182:185], v[198:201], v[116:119]
	v_mfma_f32_16x16x32_bf16 v[112:115], v[190:193], v[198:201], v[112:115]
	v_mfma_f32_16x16x32_bf16 v[100:103], v[182:185], v[206:209], v[100:103]
	v_mfma_f32_16x16x32_bf16 v[96:99], v[190:193], v[206:209], v[96:99]
	v_mfma_f32_16x16x32_bf16 v[84:87], v[182:185], v[218:221], v[84:87]
	v_mfma_f32_16x16x32_bf16 v[80:83], v[190:193], v[218:221], v[80:83]
	v_mfma_f32_16x16x32_bf16 v[68:71], v[182:185], v[226:229], v[68:71]
	v_mfma_f32_16x16x32_bf16 v[64:67], v[190:193], v[226:229], v[64:67]
	v_mfma_f32_16x16x32_bf16 v[116:119], v[186:189], v[202:205], v[116:119]
	v_mfma_f32_16x16x32_bf16 v[112:115], v[194:197], v[202:205], v[112:115]
	v_mfma_f32_16x16x32_bf16 v[100:103], v[186:189], v[214:217], v[100:103]
	v_mfma_f32_16x16x32_bf16 v[96:99], v[194:197], v[214:217], v[96:99]
	v_mfma_f32_16x16x32_bf16 v[84:87], v[186:189], v[222:225], v[84:87]
	v_mfma_f32_16x16x32_bf16 v[80:83], v[194:197], v[222:225], v[80:83]
	v_mfma_f32_16x16x32_bf16 v[68:71], v[186:189], v[230:233], v[68:71]
	v_mfma_f32_16x16x32_bf16 v[64:67], v[194:197], v[230:233], v[64:67]
	s_barrier
	s_add_i32 s56, s37, s15
	v_lshl_add_u64 v[148:149], s[30:31], 0, v[132:133]
	s_mov_b32 m0, s56
	ds_read_b128 v[198:201], v165 offset:16384
	ds_read_b128 v[202:205], v165 offset:17408
	ds_read_b128 v[206:209], v165 offset:18432
	ds_read_b128 v[214:217], v165 offset:19456
	ds_read_b128 v[218:221], v165 offset:20480
	ds_read_b128 v[222:225], v165 offset:21504
	ds_read_b128 v[226:229], v165 offset:22528
	ds_read_b128 v[230:233], v165 offset:23552
	global_load_lds_dwordx4 v[148:149], off
	s_add_i32 m0, s56, 0x2000
	s_add_u32 s56, s30, 0x40000
	v_lshl_add_u64 v[152:153], s[30:31], 0, v[128:129]
	s_addc_u32 s57, s31, 0
	s_add_i32 s58, s38, s15
	global_load_lds_dwordx4 v[152:153], off
	v_lshl_add_u64 v[162:163], s[56:57], 0, v[132:133]
	s_mov_b32 m0, s58
	v_lshl_add_u64 v[166:167], s[34:35], 0, v[130:131]
	global_load_lds_dwordx4 v[162:163], off
	v_lshl_add_u64 v[162:163], s[56:57], 0, v[128:129]
	s_add_i32 m0, s58, 0x2000
	s_nop 0
	global_load_lds_dwordx4 v[162:163], off
	v_lshl_add_u64 v[162:163], s[34:35], 0, v[134:135]
	s_mov_b32 m0, s17
	s_nop 0
	global_load_lds_dwordx4 v[162:163], off
	s_mov_b32 m0, s4
	s_nop 0
	global_load_lds_dwordx4 v[166:167], off
	s_waitcnt vmcnt(8)
	s_waitcnt lgkmcnt(0)
	s_barrier
	s_waitcnt lgkmcnt(0)
	v_mfma_f32_16x16x32_bf16 v[60:63], v[144:147], v[198:201], v[60:63]
	v_mfma_f32_16x16x32_bf16 v[56:59], v[174:177], v[198:201], v[56:59]
	v_mfma_f32_16x16x32_bf16 v[44:47], v[144:147], v[206:209], v[44:47]
	v_mfma_f32_16x16x32_bf16 v[40:43], v[174:177], v[206:209], v[40:43]
	v_mfma_f32_16x16x32_bf16 v[28:31], v[144:147], v[218:221], v[28:31]
	v_mfma_f32_16x16x32_bf16 v[24:27], v[174:177], v[218:221], v[24:27]
	v_mfma_f32_16x16x32_bf16 v[12:15], v[144:147], v[226:229], v[12:15]
	v_mfma_f32_16x16x32_bf16 v[8:11], v[174:177], v[226:229], v[8:11]
	v_mfma_f32_16x16x32_bf16 v[60:63], v[156:159], v[202:205], v[60:63]
	v_mfma_f32_16x16x32_bf16 v[56:59], v[178:181], v[202:205], v[56:59]
	v_mfma_f32_16x16x32_bf16 v[44:47], v[156:159], v[214:217], v[44:47]
	v_mfma_f32_16x16x32_bf16 v[40:43], v[178:181], v[214:217], v[40:43]
	v_mfma_f32_16x16x32_bf16 v[28:31], v[156:159], v[222:225], v[28:31]
	v_mfma_f32_16x16x32_bf16 v[24:27], v[178:181], v[222:225], v[24:27]
	v_mfma_f32_16x16x32_bf16 v[12:15], v[156:159], v[230:233], v[12:15]
	v_mfma_f32_16x16x32_bf16 v[8:11], v[178:181], v[230:233], v[8:11]
	v_mfma_f32_16x16x32_bf16 v[52:55], v[182:185], v[198:201], v[52:55]
	v_mfma_f32_16x16x32_bf16 v[48:51], v[190:193], v[198:201], v[48:51]
	v_mfma_f32_16x16x32_bf16 v[36:39], v[182:185], v[206:209], v[36:39]
	v_mfma_f32_16x16x32_bf16 v[32:35], v[190:193], v[206:209], v[32:35]
	v_mfma_f32_16x16x32_bf16 v[20:23], v[182:185], v[218:221], v[20:23]
	v_mfma_f32_16x16x32_bf16 v[16:19], v[190:193], v[218:221], v[16:19]
	v_mfma_f32_16x16x32_bf16 v[4:7], v[182:185], v[226:229], v[4:7]
	v_mfma_f32_16x16x32_bf16 v[0:3], v[190:193], v[226:229], v[0:3]
	v_mfma_f32_16x16x32_bf16 v[52:55], v[186:189], v[202:205], v[52:55]
	v_mfma_f32_16x16x32_bf16 v[48:51], v[194:197], v[202:205], v[48:51]
	v_mfma_f32_16x16x32_bf16 v[36:39], v[186:189], v[214:217], v[36:39]
	v_mfma_f32_16x16x32_bf16 v[32:35], v[194:197], v[214:217], v[32:35]
	v_mfma_f32_16x16x32_bf16 v[20:23], v[186:189], v[222:225], v[20:23]
	v_mfma_f32_16x16x32_bf16 v[16:19], v[194:197], v[222:225], v[16:19]
	v_mfma_f32_16x16x32_bf16 v[4:7], v[186:189], v[230:233], v[4:7]
	v_mfma_f32_16x16x32_bf16 v[0:3], v[194:197], v[230:233], v[0:3]
	s_barrier
; #define PG8_STAGE(bufoff, gbase, voff) do { _Pragma("unroll") for (int _i = 0; _i < 2; ++_i) \
;     __builtin_amdgcn_global_load_lds((const unsigned*)((const char*)(gbase) + (voff)[_i]), (PG8_LAS unsigned*)(lds + (bufoff) + ldsw + _i * 8192), 16, 0, 0); } while (0)
; #define PG8_LDA(dst, b, h) do { _Pragma("unroll") for (int m = 0; m < 4; ++m) _Pragma("unroll") for (int k = 0; k < 2; ++k) dst[m][k] = *(const PG8_LAS bf16x8*)(lds + PG8_SA(b, h) + aoff + m * 2048 + k * 1024); } while (0)
; #define PG8_LDB(dst, b, h) do { _Pragma("unroll") for (int n = 0; n < 2; ++n) _Pragma("unroll") for (int k = 0; k < 2; ++k) dst[n][k] = *(const PG8_LAS bf16x8*)(lds + PG8_SB(b, h) + boff + n * 2048 + k * 1024); } while (0)
; #define PG8_MMA(ai, bj, At, Bt) do { __builtin_amdgcn_s_setprio(1); _Pragma("unroll") for (int m = 0; m < 4; ++m) _Pragma("unroll") for (int n = 0; n < 2; ++n) _Pragma("unroll") for (int k = 0; k < 2; ++k) \
;     acc[ai][bj][m][n] = __builtin_amdgcn_mfma_f32_16x16x32_bf16(Bt[n][k], At[m][k], acc[ai][bj][m][n], 0, 0, 0); __builtin_amdgcn_s_setprio(0); } while (0)
; #define PG8_WAIT_V(n) asm volatile("s_waitcnt vmcnt(" #n ")" ::: "memory")
; #define PG8_WAIT_L(n) asm volatile("s_waitcnt lgkmcnt(" #n ")" ::: "memory")
; #define PG8_BAR __builtin_amdgcn_s_barrier()
; #define PG8_SCHED __builtin_amdgcn_sched_barrier(0)
; template <class Epi, class Sched>
; DI void gemm_phase(PG8_LAS unsigned char* lds, const Gemm g, const Sched& S, const Epi& E) {
;     ...
;       PG8_LDB(B0, 1, 0); PG8_LDB(B1, 1, 1); PG8_SCHED; PG8_LDA(At, 1, 0); PG8_STAGE(PG8_SA(0, 1), a2 + hstepA, voffA);
;       PG8_WAIT_V(8); PG8_WAIT_L(0); PG8_BAR; PG8_MMA(0, 0, At, B0); PG8_MMA(0, 1, At, B1); PG8_BAR; PG8_SCHED;
;       PG8_LDA(At, 1, 1); PG8_STAGE(PG8_SB(1, 0), b3, voffB); PG8_STAGE(PG8_SB(1, 1), b3 + hstepB, voffB); PG8_STAGE(PG8_SA(1, 0), a3, voffA);
	ds_read_b128 v[144:147], v171
	ds_read_b128 v[156:159], v171 offset:1024
	ds_read_b128 v[174:177], v171 offset:2048
	ds_read_b128 v[178:181], v171 offset:3072
	ds_read_b128 v[182:185], v173
	ds_read_b128 v[186:189], v173 offset:1024
	ds_read_b128 v[190:193], v173 offset:2048
	ds_read_b128 v[194:197], v173 offset:3072
	s_add_u32 s34, s34, 0x40000
	s_addc_u32 s35, s35, 0
	s_mov_b32 m0, s5
	v_lshl_add_u64 v[210:211], s[34:35], 0, v[134:135]
	ds_read_b128 v[198:201], v165 offset:32768
	ds_read_b128 v[202:205], v165 offset:33792
	ds_read_b128 v[206:209], v165 offset:34816
	ds_read_b128 v[214:217], v165 offset:35840
	ds_read_b128 v[218:221], v165 offset:36864
	ds_read_b128 v[222:225], v165 offset:37888
	ds_read_b128 v[226:229], v165 offset:38912
	ds_read_b128 v[230:233], v165 offset:39936
	global_load_lds_dwordx4 v[210:211], off
	v_lshl_add_u64 v[210:211], s[34:35], 0, v[130:131]
	s_mov_b32 m0, s19
	s_nop 0
	global_load_lds_dwordx4 v[210:211], off
	s_waitcnt vmcnt(8)
	s_waitcnt lgkmcnt(0)
	s_barrier
	s_waitcnt lgkmcnt(0)
	v_mfma_f32_16x16x32_bf16 v[124:127], v[144:147], v[198:201], v[124:127]
	v_mfma_f32_16x16x32_bf16 v[120:123], v[174:177], v[198:201], v[120:123]
	v_mfma_f32_16x16x32_bf16 v[108:111], v[144:147], v[206:209], v[108:111]
	v_mfma_f32_16x16x32_bf16 v[104:107], v[174:177], v[206:209], v[104:107]
	v_mfma_f32_16x16x32_bf16 v[92:95], v[144:147], v[218:221], v[92:95]
	v_mfma_f32_16x16x32_bf16 v[88:91], v[174:177], v[218:221], v[88:91]
	v_mfma_f32_16x16x32_bf16 v[76:79], v[144:147], v[226:229], v[76:79]
	v_mfma_f32_16x16x32_bf16 v[72:75], v[174:177], v[226:229], v[72:75]
	v_mfma_f32_16x16x32_bf16 v[124:127], v[156:159], v[202:205], v[124:127]
	v_mfma_f32_16x16x32_bf16 v[120:123], v[178:181], v[202:205], v[120:123]
	v_mfma_f32_16x16x32_bf16 v[108:111], v[156:159], v[214:217], v[108:111]
	v_mfma_f32_16x16x32_bf16 v[104:107], v[178:181], v[214:217], v[104:107]
	v_mfma_f32_16x16x32_bf16 v[92:95], v[156:159], v[222:225], v[92:95]
	v_mfma_f32_16x16x32_bf16 v[88:91], v[178:181], v[222:225], v[88:91]
	v_mfma_f32_16x16x32_bf16 v[76:79], v[156:159], v[230:233], v[76:79]
	v_mfma_f32_16x16x32_bf16 v[72:75], v[178:181], v[230:233], v[72:75]
	v_mfma_f32_16x16x32_bf16 v[116:119], v[182:185], v[198:201], v[116:119]
	v_mfma_f32_16x16x32_bf16 v[112:115], v[190:193], v[198:201], v[112:115]
	v_mfma_f32_16x16x32_bf16 v[100:103], v[182:185], v[206:209], v[100:103]
	v_mfma_f32_16x16x32_bf16 v[96:99], v[190:193], v[206:209], v[96:99]
	v_mfma_f32_16x16x32_bf16 v[84:87], v[182:185], v[218:221], v[84:87]
	v_mfma_f32_16x16x32_bf16 v[80:83], v[190:193], v[218:221], v[80:83]
	v_mfma_f32_16x16x32_bf16 v[68:71], v[182:185], v[226:229], v[68:71]
	v_mfma_f32_16x16x32_bf16 v[64:67], v[190:193], v[226:229], v[64:67]
	v_mfma_f32_16x16x32_bf16 v[116:119], v[186:189], v[202:205], v[116:119]
	v_mfma_f32_16x16x32_bf16 v[112:115], v[194:197], v[202:205], v[112:115]
	v_mfma_f32_16x16x32_bf16 v[100:103], v[186:189], v[214:217], v[100:103]
	v_mfma_f32_16x16x32_bf16 v[96:99], v[194:197], v[214:217], v[96:99]
	v_mfma_f32_16x16x32_bf16 v[84:87], v[186:189], v[222:225], v[84:87]
	v_mfma_f32_16x16x32_bf16 v[80:83], v[194:197], v[222:225], v[80:83]
	v_mfma_f32_16x16x32_bf16 v[68:71], v[186:189], v[230:233], v[68:71]
	v_mfma_f32_16x16x32_bf16 v[64:67], v[194:197], v[230:233], v[64:67]
	s_barrier
	s_add_i32 s34, s41, s15
	v_lshl_add_u64 v[148:149], v[148:149], 0, s[8:9]
	s_mov_b32 m0, s34
	ds_read_b128 v[198:201], v165 offset:49152
	ds_read_b128 v[202:205], v165 offset:50176
	ds_read_b128 v[206:209], v165 offset:51200
	ds_read_b128 v[214:217], v165 offset:52224
	ds_read_b128 v[218:221], v165 offset:53248
	ds_read_b128 v[222:225], v165 offset:54272
	ds_read_b128 v[226:229], v165 offset:55296
	ds_read_b128 v[230:233], v165 offset:56320
	global_load_lds_dwordx4 v[148:149], off
	s_add_i32 m0, s34, 0x2000
	s_add_u32 s30, s30, 0x40080
	v_lshl_add_u64 v[148:149], v[152:153], 0, s[8:9]
	s_addc_u32 s31, s31, 0
	s_add_i32 s34, s44, s15
	global_load_lds_dwordx4 v[148:149], off
	v_lshl_add_u64 v[148:149], s[30:31], 0, v[132:133]
	s_mov_b32 m0, s34
	s_nop 0
	global_load_lds_dwordx4 v[148:149], off
	v_lshl_add_u64 v[148:149], s[30:31], 0, v[128:129]
	s_add_i32 m0, s34, 0x2000
	s_nop 0
	global_load_lds_dwordx4 v[148:149], off
	v_lshl_add_u64 v[148:149], v[162:163], 0, s[8:9]
	s_mov_b32 m0, s33
	s_nop 0
	global_load_lds_dwordx4 v[148:149], off
	v_lshl_add_u64 v[148:149], v[166:167], 0, s[8:9]
	s_mov_b32 m0, s36
	s_nop 0
	global_load_lds_dwordx4 v[148:149], off
	s_waitcnt vmcnt(8)
	s_waitcnt lgkmcnt(0)
	s_barrier
; #define PG8_MMA(ai, bj, At, Bt) do { __builtin_amdgcn_s_setprio(1); _Pragma("unroll") for (int m = 0; m < 4; ++m) _Pragma("unroll") for (int n = 0; n < 2; ++n) _Pragma("unroll") for (int k = 0; k < 2; ++k) \
;     acc[ai][bj][m][n] = __builtin_amdgcn_mfma_f32_16x16x32_bf16(Bt[n][k], At[m][k], acc[ai][bj][m][n], 0, 0, 0); __builtin_amdgcn_s_setprio(0); } while (0)
; #define PG8_WAIT_V(n) asm volatile("s_waitcnt vmcnt(" #n ")" ::: "memory")
; #define PG8_WAIT_L(n) asm volatile("s_waitcnt lgkmcnt(" #n ")" ::: "memory")
; #define PG8_BAR __builtin_amdgcn_s_barrier()
; #define PG8_SCHED __builtin_amdgcn_sched_barrier(0)
; DI void rows_rstd(float (&rs)[2][4], const float* ps, const Unit& u, int wr, int fr, int fq, int p_lo, int p_hi, float inv_dim) {
;   f32x4 pv[2][4];
; #pragma unroll
;   for (int ai = 0; ai < 2; ++ai)
; #pragma unroll
;     for (int m = 0; m < 4; ++m) pv[ai][m] = *(const f32x4*)(ps + (size_t)(u.pm * BM + ai * HALF + wr * 64 + m * 16 + fr) * 16 + 4 * fq);
; template <class Epi, class Sched>
; DI void gemm_phase(PG8_LAS unsigned char* lds, const Gemm g, const Sched& S, const Epi& E) {
;     ...
;       PG8_WAIT_V(8); PG8_WAIT_L(0); PG8_BAR; PG8_MMA(1, 0, At, B0); PG8_MMA(1, 1, At, B1); PG8_BAR; PG8_SCHED;
;     }
	s_waitcnt lgkmcnt(0)
	v_mfma_f32_16x16x32_bf16 v[60:63], v[144:147], v[198:201], v[60:63]
	v_mfma_f32_16x16x32_bf16 v[56:59], v[174:177], v[198:201], v[56:59]
	v_mfma_f32_16x16x32_bf16 v[44:47], v[144:147], v[206:209], v[44:47]
	v_mfma_f32_16x16x32_bf16 v[40:43], v[174:177], v[206:209], v[40:43]
	v_mfma_f32_16x16x32_bf16 v[28:31], v[144:147], v[218:221], v[28:31]
	v_mfma_f32_16x16x32_bf16 v[24:27], v[174:177], v[218:221], v[24:27]
	v_mfma_f32_16x16x32_bf16 v[12:15], v[144:147], v[226:229], v[12:15]
	v_mfma_f32_16x16x32_bf16 v[8:11], v[174:177], v[226:229], v[8:11]
	v_mfma_f32_16x16x32_bf16 v[60:63], v[156:159], v[202:205], v[60:63]
	v_mfma_f32_16x16x32_bf16 v[56:59], v[178:181], v[202:205], v[56:59]
	v_mfma_f32_16x16x32_bf16 v[44:47], v[156:159], v[214:217], v[44:47]
	v_mfma_f32_16x16x32_bf16 v[40:43], v[178:181], v[214:217], v[40:43]
	v_mfma_f32_16x16x32_bf16 v[28:31], v[156:159], v[222:225], v[28:31]
	v_mfma_f32_16x16x32_bf16 v[24:27], v[178:181], v[222:225], v[24:27]
	v_mfma_f32_16x16x32_bf16 v[12:15], v[156:159], v[230:233], v[12:15]
	v_mfma_f32_16x16x32_bf16 v[8:11], v[178:181], v[230:233], v[8:11]
	v_mfma_f32_16x16x32_bf16 v[52:55], v[182:185], v[198:201], v[52:55]
	v_mfma_f32_16x16x32_bf16 v[48:51], v[190:193], v[198:201], v[48:51]
	v_mfma_f32_16x16x32_bf16 v[36:39], v[182:185], v[206:209], v[36:39]
	v_mfma_f32_16x16x32_bf16 v[32:35], v[190:193], v[206:209], v[32:35]
	v_mfma_f32_16x16x32_bf16 v[20:23], v[182:185], v[218:221], v[20:23]
	v_mfma_f32_16x16x32_bf16 v[16:19], v[190:193], v[218:221], v[16:19]
	v_mfma_f32_16x16x32_bf16 v[4:7], v[182:185], v[226:229], v[4:7]
	v_mfma_f32_16x16x32_bf16 v[0:3], v[190:193], v[226:229], v[0:3]
	v_mfma_f32_16x16x32_bf16 v[52:55], v[186:189], v[202:205], v[52:55]
	v_mfma_f32_16x16x32_bf16 v[48:51], v[194:197], v[202:205], v[48:51]
	v_mfma_f32_16x16x32_bf16 v[36:39], v[186:189], v[214:217], v[36:39]
	v_mfma_f32_16x16x32_bf16 v[32:35], v[194:197], v[214:217], v[32:35]
	v_mfma_f32_16x16x32_bf16 v[20:23], v[186:189], v[222:225], v[20:23]
	v_mfma_f32_16x16x32_bf16 v[16:19], v[194:197], v[222:225], v[16:19]
	v_mfma_f32_16x16x32_bf16 v[4:7], v[186:189], v[230:233], v[4:7]
	v_mfma_f32_16x16x32_bf16 v[0:3], v[194:197], v[230:233], v[0:3]
	s_barrier
	s_add_i32 s55, s55, 2
	s_add_u32 s2, s2, 0x100
	s_addc_u32 s3, s3, 0
	s_add_u32 s53, s53, 0x100
	s_addc_u32 s54, s54, 0
	s_cmp_gt_u32 s55, 13
	s_cbranch_scc0 .LBB0_1384
	v_lshl_add_u32 v166, s0, 8, v151
	v_or_b32_e32 v162, 16, v166
	v_ashrrev_i32_e32 v167, 31, v166
	v_ashrrev_i32_e32 v163, 31, v162
	v_or_b32_e32 v158, 32, v166
	v_lshlrev_b64 v[146:147], 6, v[166:167]
	v_lshlrev_b64 v[144:145], 6, v[162:163]
	v_ashrrev_i32_e32 v159, 31, v158
	v_lshl_add_u64 v[146:147], v[138:139], 0, v[146:147]
	v_or_b32_e32 v156, 48, v166
	v_lshl_add_u64 v[144:145], v[138:139], 0, v[144:145]
	global_load_dwordx4 v[174:177], v[146:147], off
	v_lshlrev_b64 v[146:147], 6, v[158:159]
	v_ashrrev_i32_e32 v157, 31, v156
	v_lshl_add_u64 v[146:147], v[138:139], 0, v[146:147]
	global_load_dwordx4 v[178:181], v[144:145], off
	global_load_dwordx4 v[182:185], v[146:147], off
	v_lshlrev_b64 v[144:145], 6, v[156:157]
	v_lshl_add_u64 v[144:145], v[138:139], 0, v[144:145]
	global_load_dwordx4 v[186:189], v[144:145], off
	v_add_u32_e32 v152, 0x80, v166
	v_ashrrev_i32_e32 v153, 31, v152
	v_lshlrev_b64 v[144:145], 6, v[152:153]
	v_add_u32_e32 v148, 0x90, v166
	v_lshl_add_u64 v[144:145], v[138:139], 0, v[144:145]
	v_ashrrev_i32_e32 v149, 31, v148
	global_load_dwordx4 v[190:193], v[144:145], off
	v_lshlrev_b64 v[144:145], 6, v[148:149]
	v_lshl_add_u64 v[144:145], v[138:139], 0, v[144:145]
	global_load_dwordx4 v[194:197], v[144:145], off
	v_add_u32_e32 v144, 0xb0, v166
	v_ashrrev_i32_e32 v145, 31, v144
	v_lshlrev_b64 v[146:147], 6, v[144:145]
	v_lshl_add_u64 v[146:147], v[138:139], 0, v[146:147]
	global_load_dwordx4 v[198:201], v[146:147], off
	v_and_b32_e32 v147, 64, v169
	v_add_u32_e32 v146, 0xa0, v166
	v_add_u32_e32 v150, 64, v147
	v_ashrrev_i32_e32 v147, 31, v146
	v_lshlrev_b64 v[202:203], 6, v[146:147]
	v_lshl_add_u64 v[202:203], v[138:139], 0, v[202:203]
	global_load_dwordx4 v[202:205], v[202:203], off
	s_and_b64 vcc, exec, s[10:11]
	s_cbranch_vccz .LBB0_1387
	s_barrier

; #define PG8_STAGE(bufoff, gbase, voff) do { _Pragma("unroll") for (int _i = 0; _i < 2; ++_i) \
;     __builtin_amdgcn_global_load_lds((const unsigned*)((const char*)(gbase) + (voff)[_i]), (PG8_LAS unsigned*)(lds + (bufoff) + ldsw + _i * 8192), 16, 0, 0); } while (0)
; #define PG8_LDA(dst, b, h) do { _Pragma("unroll") for (int m = 0; m < 4; ++m) _Pragma("unroll") for (int k = 0; k < 2; ++k) dst[m][k] = *(const PG8_LAS bf16x8*)(lds + PG8_SA(b, h) + aoff + m * 2048 + k * 1024); } while (0)
; #define PG8_LDB(dst, b, h) do { _Pragma("unroll") for (int n = 0; n < 2; ++n) _Pragma("unroll") for (int k = 0; k < 2; ++k) dst[n][k] = *(const PG8_LAS bf16x8*)(lds + PG8_SB(b, h) + boff + n * 2048 + k * 1024); } while (0)
; #define PG8_MMA(ai, bj, At, Bt) do { __builtin_amdgcn_s_setprio(1); _Pragma("unroll") for (int m = 0; m < 4; ++m) _Pragma("unroll") for (int n = 0; n < 2; ++n) _Pragma("unroll") for (int k = 0; k < 2; ++k) \
;     acc[ai][bj][m][n] = __builtin_amdgcn_mfma_f32_16x16x32_bf16(Bt[n][k], At[m][k], acc[ai][bj][m][n], 0, 0, 0); __builtin_amdgcn_s_setprio(0); } while (0)
; #define PG8_WAIT_V(n) asm volatile("s_waitcnt vmcnt(" #n ")" ::: "memory")
; #define PG8_WAIT_L(n) asm volatile("s_waitcnt lgkmcnt(" #n ")" ::: "memory")
; #define PG8_BAR __builtin_amdgcn_s_barrier()
; #define PG8_SCHED __builtin_amdgcn_sched_barrier(0)
; template <class Epi, class Sched>
; DI void gemm_phase(PG8_LAS unsigned char* lds, const Gemm g, const Sched& S, const Epi& E) {
;     ...
;     for (int t = 0; t < nt; t += 2) {
;       const bool last = (t == nt - 2);
;       const char* a1 = cA + (size_t)(t + 1) * kstep;
;       const char* a2 = last ? nA : cA + (size_t)(t + 2) * kstep; const char* b2 = last ? nB : cB + (size_t)(t + 2) * kstep;
;       const char* a3 = a2 + kstep; const char* b3 = b2 + kstep;
;       PG8_LDB(B0, 0, 0); PG8_LDB(B1, 0, 1); PG8_SCHED; PG8_LDA(At, 0, 0); PG8_STAGE(PG8_SA(1, 1), a1 + hstepA, voffA);
;       PG8_WAIT_V(8); PG8_WAIT_L(0); PG8_BAR; PG8_MMA(0, 0, At, B0); PG8_MMA(0, 1, At, B1); PG8_BAR; PG8_SCHED;
;     ...
; #pragma unroll
;     for (int a = 0; a < 2; ++a)
; #pragma unroll
;       for (int b = 0; b < 2; ++b)
; #pragma unroll
;         for (int m = 0; m < 4; ++m)
; #pragma unroll
;           for (int n = 0; n < 2; ++n) acc[a][b][m][n] = (f32x4){0.f, 0.f, 0.f, 0.f};
;     cur = nxt; cA = nA; cB = nB; ++ui;
.LBB0_1455:
	s_add_u32 s58, s14, 0x100
	v_mov_b32_e32 v0, 0
	s_addc_u32 s59, s15, 0
	s_mov_b32 s60, -2
	v_mov_b32_e32 v1, v0
	v_mov_b32_e32 v2, v0
	v_mov_b32_e32 v3, v0
	v_mov_b32_e32 v4, v0
	v_mov_b32_e32 v5, v0
	v_mov_b32_e32 v6, v0
	v_mov_b32_e32 v7, v0
	v_mov_b32_e32 v12, v0
	v_mov_b32_e32 v13, v0
	v_mov_b32_e32 v14, v0
	v_mov_b32_e32 v15, v0
	v_mov_b32_e32 v20, v0
	v_mov_b32_e32 v21, v0
	v_mov_b32_e32 v22, v0
	v_mov_b32_e32 v23, v0
	v_mov_b32_e32 v32, v0
	v_mov_b32_e32 v33, v0
	v_mov_b32_e32 v34, v0
	v_mov_b32_e32 v35, v0
	v_mov_b32_e32 v36, v0
	v_mov_b32_e32 v37, v0
	v_mov_b32_e32 v38, v0
	v_mov_b32_e32 v39, v0
	v_mov_b32_e32 v48, v0
	v_mov_b32_e32 v49, v0
	v_mov_b32_e32 v50, v0
	v_mov_b32_e32 v51, v0
	v_mov_b32_e32 v52, v0
	v_mov_b32_e32 v53, v0
	v_mov_b32_e32 v54, v0
	v_mov_b32_e32 v55, v0
	v_mov_b32_e32 v8, v0
	v_mov_b32_e32 v9, v0
	v_mov_b32_e32 v10, v0
	v_mov_b32_e32 v11, v0
	v_mov_b32_e32 v16, v0
	v_mov_b32_e32 v17, v0
	v_mov_b32_e32 v18, v0
	v_mov_b32_e32 v19, v0
	v_mov_b32_e32 v24, v0
	v_mov_b32_e32 v25, v0
	v_mov_b32_e32 v26, v0
	v_mov_b32_e32 v27, v0
	v_mov_b32_e32 v28, v0
	v_mov_b32_e32 v29, v0
	v_mov_b32_e32 v30, v0
	v_mov_b32_e32 v31, v0
	v_mov_b32_e32 v40, v0
	v_mov_b32_e32 v41, v0
	v_mov_b32_e32 v42, v0
	v_mov_b32_e32 v43, v0
	v_mov_b32_e32 v44, v0
	v_mov_b32_e32 v45, v0
	v_mov_b32_e32 v46, v0
	v_mov_b32_e32 v47, v0
	v_mov_b32_e32 v56, v0
	v_mov_b32_e32 v57, v0
	v_mov_b32_e32 v58, v0
	v_mov_b32_e32 v59, v0
	v_mov_b32_e32 v60, v0
	v_mov_b32_e32 v61, v0
	v_mov_b32_e32 v62, v0
	v_mov_b32_e32 v63, v0
	v_mov_b32_e32 v64, v0
	v_mov_b32_e32 v65, v0
	v_mov_b32_e32 v66, v0
	v_mov_b32_e32 v67, v0
	v_mov_b32_e32 v68, v0
	v_mov_b32_e32 v69, v0
	v_mov_b32_e32 v70, v0
	v_mov_b32_e32 v71, v0
	v_mov_b32_e32 v80, v0
	v_mov_b32_e32 v81, v0
	v_mov_b32_e32 v82, v0
	v_mov_b32_e32 v83, v0
	v_mov_b32_e32 v84, v0
	v_mov_b32_e32 v85, v0
	v_mov_b32_e32 v86, v0
	v_mov_b32_e32 v87, v0
	v_mov_b32_e32 v96, v0
	v_mov_b32_e32 v97, v0
	v_mov_b32_e32 v98, v0
	v_mov_b32_e32 v99, v0
	v_mov_b32_e32 v100, v0
	v_mov_b32_e32 v101, v0
	v_mov_b32_e32 v102, v0
	v_mov_b32_e32 v103, v0
	s_waitcnt vmcnt(0)
	v_mov_b32_e32 v112, v0
	v_mov_b32_e32 v113, v0
	v_mov_b32_e32 v114, v0
	v_mov_b32_e32 v115, v0
	v_mov_b32_e32 v116, v0
	v_mov_b32_e32 v117, v0
	v_mov_b32_e32 v118, v0
	v_mov_b32_e32 v119, v0
	v_mov_b32_e32 v72, v0
	v_mov_b32_e32 v73, v0
	v_mov_b32_e32 v74, v0
	v_mov_b32_e32 v75, v0
	v_mov_b32_e32 v76, v0
	v_mov_b32_e32 v77, v0
	v_mov_b32_e32 v78, v0
	v_mov_b32_e32 v79, v0
	v_mov_b32_e32 v88, v0
	v_mov_b32_e32 v89, v0
	v_mov_b32_e32 v90, v0
	v_mov_b32_e32 v91, v0
	v_mov_b32_e32 v92, v0
	v_mov_b32_e32 v93, v0
	v_mov_b32_e32 v94, v0
	v_mov_b32_e32 v95, v0
	v_mov_b32_e32 v104, v0
	v_mov_b32_e32 v105, v0
	v_mov_b32_e32 v106, v0
	v_mov_b32_e32 v107, v0
	v_mov_b32_e32 v108, v0
	v_mov_b32_e32 v109, v0
	v_mov_b32_e32 v110, v0
	v_mov_b32_e32 v111, v0
	v_mov_b32_e32 v120, v0
	v_mov_b32_e32 v121, v0
	v_mov_b32_e32 v122, v0
	v_mov_b32_e32 v123, v0
	v_mov_b32_e32 v124, v0
	v_mov_b32_e32 v125, v0
	v_mov_b32_e32 v126, v0
	v_mov_b32_e32 v127, v0
	v_readfirstlane_b32 s100, v212
	s_nop 3
	s_lshr_b32 s100, s100, 8
	s_cmp_lg_u32 s100, 0
	s_cbranch_scc0 .Lgp_8
	s_setprio 1
.Lgp_8:
.LBB0_1456:
	ds_read_b128 v[150:153], v145
	ds_read_b128 v[154:157], v145 offset:1024
	ds_read_b128 v[158:161], v145 offset:2048
	ds_read_b128 v[162:165], v145 offset:3072
	ds_read_b128 v[166:169], v146
	ds_read_b128 v[170:173], v146 offset:1024
	ds_read_b128 v[174:177], v146 offset:2048
	ds_read_b128 v[178:181], v146 offset:3072
	s_add_u32 s14, s12, 0x100
	s_addc_u32 s15, s13, 0
	s_cmp_eq_u32 s60, 40
	s_cselect_b32 s19, s9, s15
	s_cselect_b32 s18, s8, s14
	s_cselect_b32 s17, s11, s59
	s_cselect_b32 s16, s10, s58
	s_mov_b32 m0, s49
	v_lshl_add_u64 v[142:143], s[12:13], 0, v[138:139]
	ds_read_b128 v[182:185], v147
	ds_read_b128 v[186:189], v147 offset:1024
	ds_read_b128 v[190:193], v147 offset:2048
	ds_read_b128 v[194:197], v147 offset:3072
	ds_read_b128 v[198:201], v147 offset:4096
	ds_read_b128 v[202:205], v147 offset:5120
	ds_read_b128 v[206:209], v147 offset:6144
	ds_read_b128 v[210:213], v147 offset:7168
	global_load_lds_dwordx4 v[142:143], off
	v_lshl_add_u64 v[142:143], s[12:13], 0, v[140:141]
	s_mov_b32 m0, s52
	s_nop 0
	global_load_lds_dwordx4 v[142:143], off
	s_waitcnt vmcnt(8)
	s_waitcnt lgkmcnt(0)
	s_barrier
	s_waitcnt lgkmcnt(0)
	v_mfma_f32_16x16x32_bf16 v[124:127], v[150:153], v[182:185], v[124:127]
	v_mfma_f32_16x16x32_bf16 v[120:123], v[158:161], v[182:185], v[120:123]
	v_mfma_f32_16x16x32_bf16 v[108:111], v[150:153], v[190:193], v[108:111]
	v_mfma_f32_16x16x32_bf16 v[104:107], v[158:161], v[190:193], v[104:107]
	v_mfma_f32_16x16x32_bf16 v[92:95], v[150:153], v[198:201], v[92:95]
	v_mfma_f32_16x16x32_bf16 v[88:91], v[158:161], v[198:201], v[88:91]
	v_mfma_f32_16x16x32_bf16 v[76:79], v[150:153], v[206:209], v[76:79]
	v_mfma_f32_16x16x32_bf16 v[72:75], v[158:161], v[206:209], v[72:75]
	v_mfma_f32_16x16x32_bf16 v[124:127], v[154:157], v[186:189], v[124:127]
	v_mfma_f32_16x16x32_bf16 v[120:123], v[162:165], v[186:189], v[120:123]
	v_mfma_f32_16x16x32_bf16 v[108:111], v[154:157], v[194:197], v[108:111]
	v_mfma_f32_16x16x32_bf16 v[104:107], v[162:165], v[194:197], v[104:107]
	v_mfma_f32_16x16x32_bf16 v[92:95], v[154:157], v[202:205], v[92:95]
	v_mfma_f32_16x16x32_bf16 v[88:91], v[162:165], v[202:205], v[88:91]
	v_mfma_f32_16x16x32_bf16 v[76:79], v[154:157], v[210:213], v[76:79]
	v_mfma_f32_16x16x32_bf16 v[72:75], v[162:165], v[210:213], v[72:75]
	v_mfma_f32_16x16x32_bf16 v[116:119], v[166:169], v[182:185], v[116:119]
	v_mfma_f32_16x16x32_bf16 v[112:115], v[174:177], v[182:185], v[112:115]
	v_mfma_f32_16x16x32_bf16 v[100:103], v[166:169], v[190:193], v[100:103]
	v_mfma_f32_16x16x32_bf16 v[96:99], v[174:177], v[190:193], v[96:99]
	v_mfma_f32_16x16x32_bf16 v[84:87], v[166:169], v[198:201], v[84:87]
	v_mfma_f32_16x16x32_bf16 v[80:83], v[174:177], v[198:201], v[80:83]
	v_mfma_f32_16x16x32_bf16 v[68:71], v[166:169], v[206:209], v[68:71]
	v_mfma_f32_16x16x32_bf16 v[64:67], v[174:177], v[206:209], v[64:67]
	v_mfma_f32_16x16x32_bf16 v[116:119], v[170:173], v[186:189], v[116:119]
	v_mfma_f32_16x16x32_bf16 v[112:115], v[178:181], v[186:189], v[112:115]
	v_mfma_f32_16x16x32_bf16 v[100:103], v[170:173], v[194:197], v[100:103]
	v_mfma_f32_16x16x32_bf16 v[96:99], v[178:181], v[194:197], v[96:99]
	v_mfma_f32_16x16x32_bf16 v[84:87], v[170:173], v[202:205], v[84:87]
	v_mfma_f32_16x16x32_bf16 v[80:83], v[178:181], v[202:205], v[80:83]
	v_mfma_f32_16x16x32_bf16 v[68:71], v[170:173], v[210:213], v[68:71]
	v_mfma_f32_16x16x32_bf16 v[64:67], v[178:181], v[210:213], v[64:67]
	s_barrier
; #define PG8_STAGE(bufoff, gbase, voff) do { _Pragma("unroll") for (int _i = 0; _i < 2; ++_i) \
;     __builtin_amdgcn_global_load_lds((const unsigned*)((const char*)(gbase) + (voff)[_i]), (PG8_LAS unsigned*)(lds + (bufoff) + ldsw + _i * 8192), 16, 0, 0); } while (0)
; #define PG8_LDA(dst, b, h) do { _Pragma("unroll") for (int m = 0; m < 4; ++m) _Pragma("unroll") for (int k = 0; k < 2; ++k) dst[m][k] = *(const PG8_LAS bf16x8*)(lds + PG8_SA(b, h) + aoff + m * 2048 + k * 1024); } while (0)
; #define PG8_LDB(dst, b, h) do { _Pragma("unroll") for (int n = 0; n < 2; ++n) _Pragma("unroll") for (int k = 0; k < 2; ++k) dst[n][k] = *(const PG8_LAS bf16x8*)(lds + PG8_SB(b, h) + boff + n * 2048 + k * 1024); } while (0)
; #define PG8_MMA(ai, bj, At, Bt) do { __builtin_amdgcn_s_setprio(1); _Pragma("unroll") for (int m = 0; m < 4; ++m) _Pragma("unroll") for (int n = 0; n < 2; ++n) _Pragma("unroll") for (int k = 0; k < 2; ++k) \
;     acc[ai][bj][m][n] = __builtin_amdgcn_mfma_f32_16x16x32_bf16(Bt[n][k], At[m][k], acc[ai][bj][m][n], 0, 0, 0); __builtin_amdgcn_s_setprio(0); } while (0)
; #define PG8_WAIT_V(n) asm volatile("s_waitcnt vmcnt(" #n ")" ::: "memory")
; #define PG8_WAIT_L(n) asm volatile("s_waitcnt lgkmcnt(" #n ")" ::: "memory")
; #define PG8_BAR __builtin_amdgcn_s_barrier()
; #define PG8_SCHED __builtin_amdgcn_sched_barrier(0)
; template <class Epi, class Sched>
; DI void gemm_phase(PG8_LAS unsigned char* lds, const Gemm g, const Sched& S, const Epi& E) {
;     ...
;       PG8_LDA(At, 0, 1); PG8_STAGE(PG8_SB(0, 0), b2, voffB); PG8_STAGE(PG8_SB(0, 1), b2 + hstepB, voffB); PG8_STAGE(PG8_SA(0, 0), a2, voffA);
;       PG8_WAIT_V(8); PG8_WAIT_L(0); PG8_BAR; PG8_MMA(1, 0, At, B0); PG8_MMA(1, 1, At, B1); PG8_BAR; PG8_SCHED;
;       PG8_LDB(B0, 1, 0); PG8_LDB(B1, 1, 1); PG8_SCHED; PG8_LDA(At, 1, 0); PG8_STAGE(PG8_SA(0, 1), a2 + hstepA, voffA);
;       PG8_WAIT_V(8); PG8_WAIT_L(0); PG8_BAR; PG8_MMA(0, 0, At, B0); PG8_MMA(0, 1, At, B1); PG8_BAR; PG8_SCHED;
	s_add_i32 s12, s33, s20
	v_lshl_add_u64 v[142:143], s[16:17], 0, v[132:133]
	s_mov_b32 m0, s12
	ds_read_b128 v[182:185], v147 offset:16384
	ds_read_b128 v[186:189], v147 offset:17408
	ds_read_b128 v[190:193], v147 offset:18432
	ds_read_b128 v[194:197], v147 offset:19456
	ds_read_b128 v[198:201], v147 offset:20480
	ds_read_b128 v[202:205], v147 offset:21504
	ds_read_b128 v[206:209], v147 offset:22528
	ds_read_b128 v[210:213], v147 offset:23552
	global_load_lds_dwordx4 v[142:143], off
	s_add_i32 m0, s12, 0x2000
	s_add_u32 s12, s16, 0xb0000
	v_lshl_add_u64 v[214:215], s[16:17], 0, v[128:129]
	s_addc_u32 s13, s17, 0
	s_add_i32 s61, s34, s20
	global_load_lds_dwordx4 v[214:215], off
	v_lshl_add_u64 v[216:217], s[12:13], 0, v[132:133]
	s_mov_b32 m0, s61
	v_lshl_add_u64 v[218:219], s[18:19], 0, v[130:131]
	global_load_lds_dwordx4 v[216:217], off
	v_lshl_add_u64 v[216:217], s[12:13], 0, v[128:129]
	s_add_i32 m0, s61, 0x2000
	s_nop 0
	global_load_lds_dwordx4 v[216:217], off
	v_lshl_add_u64 v[216:217], s[18:19], 0, v[134:135]
	s_mov_b32 m0, s22
	s_nop 0
	global_load_lds_dwordx4 v[216:217], off
	s_mov_b32 m0, s23
	s_nop 0
	global_load_lds_dwordx4 v[218:219], off
	s_waitcnt vmcnt(8)
	s_waitcnt lgkmcnt(0)
	s_barrier
	s_waitcnt lgkmcnt(0)
	v_mfma_f32_16x16x32_bf16 v[60:63], v[150:153], v[182:185], v[60:63]
	v_mfma_f32_16x16x32_bf16 v[56:59], v[158:161], v[182:185], v[56:59]
	v_mfma_f32_16x16x32_bf16 v[44:47], v[150:153], v[190:193], v[44:47]
	v_mfma_f32_16x16x32_bf16 v[40:43], v[158:161], v[190:193], v[40:43]
	v_mfma_f32_16x16x32_bf16 v[28:31], v[150:153], v[198:201], v[28:31]
	v_mfma_f32_16x16x32_bf16 v[24:27], v[158:161], v[198:201], v[24:27]
	v_mfma_f32_16x16x32_bf16 v[16:19], v[150:153], v[206:209], v[16:19]
	v_mfma_f32_16x16x32_bf16 v[8:11], v[158:161], v[206:209], v[8:11]
	v_mfma_f32_16x16x32_bf16 v[60:63], v[154:157], v[186:189], v[60:63]
	v_mfma_f32_16x16x32_bf16 v[56:59], v[162:165], v[186:189], v[56:59]
	v_mfma_f32_16x16x32_bf16 v[44:47], v[154:157], v[194:197], v[44:47]
	v_mfma_f32_16x16x32_bf16 v[40:43], v[162:165], v[194:197], v[40:43]
	v_mfma_f32_16x16x32_bf16 v[28:31], v[154:157], v[202:205], v[28:31]
	v_mfma_f32_16x16x32_bf16 v[24:27], v[162:165], v[202:205], v[24:27]
	v_mfma_f32_16x16x32_bf16 v[16:19], v[154:157], v[210:213], v[16:19]
	v_mfma_f32_16x16x32_bf16 v[8:11], v[162:165], v[210:213], v[8:11]
	v_mfma_f32_16x16x32_bf16 v[52:55], v[166:169], v[182:185], v[52:55]
	v_mfma_f32_16x16x32_bf16 v[48:51], v[174:177], v[182:185], v[48:51]
	v_mfma_f32_16x16x32_bf16 v[36:39], v[166:169], v[190:193], v[36:39]
	v_mfma_f32_16x16x32_bf16 v[32:35], v[174:177], v[190:193], v[32:35]
	v_mfma_f32_16x16x32_bf16 v[20:23], v[166:169], v[198:201], v[20:23]
	v_mfma_f32_16x16x32_bf16 v[12:15], v[174:177], v[198:201], v[12:15]
	v_mfma_f32_16x16x32_bf16 v[4:7], v[166:169], v[206:209], v[4:7]
	v_mfma_f32_16x16x32_bf16 v[0:3], v[174:177], v[206:209], v[0:3]
	v_mfma_f32_16x16x32_bf16 v[52:55], v[170:173], v[186:189], v[52:55]
	v_mfma_f32_16x16x32_bf16 v[48:51], v[178:181], v[186:189], v[48:51]
	v_mfma_f32_16x16x32_bf16 v[36:39], v[170:173], v[194:197], v[36:39]
	v_mfma_f32_16x16x32_bf16 v[32:35], v[178:181], v[194:197], v[32:35]
	v_mfma_f32_16x16x32_bf16 v[20:23], v[170:173], v[202:205], v[20:23]
	v_mfma_f32_16x16x32_bf16 v[12:15], v[178:181], v[202:205], v[12:15]
	v_mfma_f32_16x16x32_bf16 v[4:7], v[170:173], v[210:213], v[4:7]
	v_mfma_f32_16x16x32_bf16 v[0:3], v[178:181], v[210:213], v[0:3]
	s_barrier
	s_add_i32 s61, s30, 0x110
	v_add_u32_e32 v149, s61, v144
	ds_read_b128 v[150:153], v149
	ds_read_b128 v[154:157], v149 offset:1024
	ds_read_b128 v[158:161], v149 offset:2048
	ds_read_b128 v[162:165], v149 offset:3072
	ds_read_b128 v[166:169], v148
	ds_read_b128 v[170:173], v148 offset:1024
	ds_read_b128 v[174:177], v148 offset:2048
	ds_read_b128 v[178:181], v148 offset:3072
	s_add_u32 s12, s18, 0xb0000
	s_addc_u32 s13, s19, 0
	s_mov_b32 m0, s24
	v_lshl_add_u64 v[220:221], s[12:13], 0, v[134:135]
	ds_read_b128 v[182:185], v147 offset:32768
	ds_read_b128 v[186:189], v147 offset:33792
	ds_read_b128 v[190:193], v147 offset:34816
	ds_read_b128 v[194:197], v147 offset:35840
	ds_read_b128 v[198:201], v147 offset:36864
	ds_read_b128 v[202:205], v147 offset:37888
	ds_read_b128 v[206:209], v147 offset:38912
	ds_read_b128 v[210:213], v147 offset:39936
	global_load_lds_dwordx4 v[220:221], off
	v_lshl_add_u64 v[220:221], s[12:13], 0, v[130:131]
	s_mov_b32 m0, s25
	s_nop 0
	global_load_lds_dwordx4 v[220:221], off
	s_waitcnt vmcnt(8)
	s_waitcnt lgkmcnt(0)
	s_barrier
; #define PG8_STAGE(bufoff, gbase, voff) do { _Pragma("unroll") for (int _i = 0; _i < 2; ++_i) \
;     __builtin_amdgcn_global_load_lds((const unsigned*)((const char*)(gbase) + (voff)[_i]), (PG8_LAS unsigned*)(lds + (bufoff) + ldsw + _i * 8192), 16, 0, 0); } while (0)
; #define PG8_LDA(dst, b, h) do { _Pragma("unroll") for (int m = 0; m < 4; ++m) _Pragma("unroll") for (int k = 0; k < 2; ++k) dst[m][k] = *(const PG8_LAS bf16x8*)(lds + PG8_SA(b, h) + aoff + m * 2048 + k * 1024); } while (0)
; #define PG8_MMA(ai, bj, At, Bt) do { __builtin_amdgcn_s_setprio(1); _Pragma("unroll") for (int m = 0; m < 4; ++m) _Pragma("unroll") for (int n = 0; n < 2; ++n) _Pragma("unroll") for (int k = 0; k < 2; ++k) \
;     acc[ai][bj][m][n] = __builtin_amdgcn_mfma_f32_16x16x32_bf16(Bt[n][k], At[m][k], acc[ai][bj][m][n], 0, 0, 0); __builtin_amdgcn_s_setprio(0); } while (0)
; #define PG8_WAIT_V(n) asm volatile("s_waitcnt vmcnt(" #n ")" ::: "memory")
; #define PG8_WAIT_L(n) asm volatile("s_waitcnt lgkmcnt(" #n ")" ::: "memory")
; #define PG8_BAR __builtin_amdgcn_s_barrier()
; #define PG8_SCHED __builtin_amdgcn_sched_barrier(0)
;   DI void operator()(const f32x4 (&acc)[2][2][4][2], const Unit& u, int wr, int wc, int fr, int fq) const {
;     ...
;     RES_LD(0)
; template <class Epi, class Sched>
; DI void gemm_phase(PG8_LAS unsigned char* lds, const Gemm g, const Sched& S, const Epi& E) {
;     ...
;       PG8_LDA(At, 1, 1); PG8_STAGE(PG8_SB(1, 0), b3, voffB); PG8_STAGE(PG8_SB(1, 1), b3 + hstepB, voffB); PG8_STAGE(PG8_SA(1, 0), a3, voffA);
;       PG8_WAIT_V(8); PG8_WAIT_L(0); PG8_BAR; PG8_MMA(1, 0, At, B0); PG8_MMA(1, 1, At, B1); PG8_BAR; PG8_SCHED;
;     }
	s_waitcnt lgkmcnt(0)
	v_mfma_f32_16x16x32_bf16 v[124:127], v[150:153], v[182:185], v[124:127]
	v_mfma_f32_16x16x32_bf16 v[120:123], v[158:161], v[182:185], v[120:123]
	v_mfma_f32_16x16x32_bf16 v[108:111], v[150:153], v[190:193], v[108:111]
	v_mfma_f32_16x16x32_bf16 v[104:107], v[158:161], v[190:193], v[104:107]
	v_mfma_f32_16x16x32_bf16 v[92:95], v[150:153], v[198:201], v[92:95]
	v_mfma_f32_16x16x32_bf16 v[88:91], v[158:161], v[198:201], v[88:91]
	v_mfma_f32_16x16x32_bf16 v[76:79], v[150:153], v[206:209], v[76:79]
	v_mfma_f32_16x16x32_bf16 v[72:75], v[158:161], v[206:209], v[72:75]
	v_mfma_f32_16x16x32_bf16 v[124:127], v[154:157], v[186:189], v[124:127]
	v_mfma_f32_16x16x32_bf16 v[120:123], v[162:165], v[186:189], v[120:123]
	v_mfma_f32_16x16x32_bf16 v[108:111], v[154:157], v[194:197], v[108:111]
	v_mfma_f32_16x16x32_bf16 v[104:107], v[162:165], v[194:197], v[104:107]
	v_mfma_f32_16x16x32_bf16 v[92:95], v[154:157], v[202:205], v[92:95]
	v_mfma_f32_16x16x32_bf16 v[88:91], v[162:165], v[202:205], v[88:91]
	v_mfma_f32_16x16x32_bf16 v[76:79], v[154:157], v[210:213], v[76:79]
	v_mfma_f32_16x16x32_bf16 v[72:75], v[162:165], v[210:213], v[72:75]
	v_mfma_f32_16x16x32_bf16 v[116:119], v[166:169], v[182:185], v[116:119]
	v_mfma_f32_16x16x32_bf16 v[112:115], v[174:177], v[182:185], v[112:115]
	v_mfma_f32_16x16x32_bf16 v[100:103], v[166:169], v[190:193], v[100:103]
	v_mfma_f32_16x16x32_bf16 v[96:99], v[174:177], v[190:193], v[96:99]
	v_mfma_f32_16x16x32_bf16 v[84:87], v[166:169], v[198:201], v[84:87]
	v_mfma_f32_16x16x32_bf16 v[80:83], v[174:177], v[198:201], v[80:83]
	v_mfma_f32_16x16x32_bf16 v[68:71], v[166:169], v[206:209], v[68:71]
	v_mfma_f32_16x16x32_bf16 v[64:67], v[174:177], v[206:209], v[64:67]
	v_mfma_f32_16x16x32_bf16 v[116:119], v[170:173], v[186:189], v[116:119]
	v_mfma_f32_16x16x32_bf16 v[112:115], v[178:181], v[186:189], v[112:115]
	v_mfma_f32_16x16x32_bf16 v[100:103], v[170:173], v[194:197], v[100:103]
	v_mfma_f32_16x16x32_bf16 v[96:99], v[178:181], v[194:197], v[96:99]
	v_mfma_f32_16x16x32_bf16 v[84:87], v[170:173], v[202:205], v[84:87]
	v_mfma_f32_16x16x32_bf16 v[80:83], v[178:181], v[202:205], v[80:83]
	v_mfma_f32_16x16x32_bf16 v[68:71], v[170:173], v[210:213], v[68:71]
	v_mfma_f32_16x16x32_bf16 v[64:67], v[178:181], v[210:213], v[64:67]
	s_barrier
	s_add_i32 s12, s61, s20
	v_lshl_add_u64 v[142:143], v[142:143], 0, s[4:5]
	s_mov_b32 m0, s12
	ds_read_b128 v[182:185], v147 offset:49152
	ds_read_b128 v[186:189], v147 offset:50176
	ds_read_b128 v[190:193], v147 offset:51200
	ds_read_b128 v[194:197], v147 offset:52224
	ds_read_b128 v[198:201], v147 offset:53248
	ds_read_b128 v[202:205], v147 offset:54272
	ds_read_b128 v[206:209], v147 offset:55296
	ds_read_b128 v[210:213], v147 offset:56320
	global_load_lds_dwordx4 v[142:143], off
	s_add_i32 m0, s12, 0x2000
	s_add_u32 s12, s16, 0xb0080
	v_lshl_add_u64 v[142:143], v[214:215], 0, s[4:5]
	s_addc_u32 s13, s17, 0
	s_add_i32 s16, s53, s20
	global_load_lds_dwordx4 v[142:143], off
	v_lshl_add_u64 v[142:143], s[12:13], 0, v[132:133]
	s_mov_b32 m0, s16
	s_nop 0
	global_load_lds_dwordx4 v[142:143], off
	v_lshl_add_u64 v[142:143], s[12:13], 0, v[128:129]
	s_add_i32 m0, s16, 0x2000
	s_nop 0
	global_load_lds_dwordx4 v[142:143], off
	v_lshl_add_u64 v[142:143], v[216:217], 0, s[4:5]
	s_mov_b32 m0, s28
	s_nop 0
	global_load_lds_dwordx4 v[142:143], off
	v_lshl_add_u64 v[142:143], v[218:219], 0, s[4:5]
	s_mov_b32 m0, s29
	s_nop 0
	global_load_lds_dwordx4 v[142:143], off
	s_waitcnt vmcnt(8)
	s_waitcnt lgkmcnt(0)
	s_barrier
	s_waitcnt lgkmcnt(0)
	v_mfma_f32_16x16x32_bf16 v[60:63], v[150:153], v[182:185], v[60:63]
	v_mfma_f32_16x16x32_bf16 v[56:59], v[158:161], v[182:185], v[56:59]
	v_mfma_f32_16x16x32_bf16 v[44:47], v[150:153], v[190:193], v[44:47]
	v_mfma_f32_16x16x32_bf16 v[40:43], v[158:161], v[190:193], v[40:43]
	v_mfma_f32_16x16x32_bf16 v[28:31], v[150:153], v[198:201], v[28:31]
	v_mfma_f32_16x16x32_bf16 v[24:27], v[158:161], v[198:201], v[24:27]
	v_mfma_f32_16x16x32_bf16 v[16:19], v[150:153], v[206:209], v[16:19]
	v_mfma_f32_16x16x32_bf16 v[8:11], v[158:161], v[206:209], v[8:11]
	v_mfma_f32_16x16x32_bf16 v[60:63], v[154:157], v[186:189], v[60:63]
	v_mfma_f32_16x16x32_bf16 v[56:59], v[162:165], v[186:189], v[56:59]
	v_mfma_f32_16x16x32_bf16 v[44:47], v[154:157], v[194:197], v[44:47]
	v_mfma_f32_16x16x32_bf16 v[40:43], v[162:165], v[194:197], v[40:43]
	v_mfma_f32_16x16x32_bf16 v[28:31], v[154:157], v[202:205], v[28:31]
	v_mfma_f32_16x16x32_bf16 v[24:27], v[162:165], v[202:205], v[24:27]
	v_mfma_f32_16x16x32_bf16 v[16:19], v[154:157], v[210:213], v[16:19]
	v_mfma_f32_16x16x32_bf16 v[8:11], v[162:165], v[210:213], v[8:11]
	v_mfma_f32_16x16x32_bf16 v[52:55], v[166:169], v[182:185], v[52:55]
	v_mfma_f32_16x16x32_bf16 v[48:51], v[174:177], v[182:185], v[48:51]
	v_mfma_f32_16x16x32_bf16 v[36:39], v[166:169], v[190:193], v[36:39]
	v_mfma_f32_16x16x32_bf16 v[32:35], v[174:177], v[190:193], v[32:35]
	v_mfma_f32_16x16x32_bf16 v[20:23], v[166:169], v[198:201], v[20:23]
	v_mfma_f32_16x16x32_bf16 v[12:15], v[174:177], v[198:201], v[12:15]
	v_mfma_f32_16x16x32_bf16 v[4:7], v[166:169], v[206:209], v[4:7]
	v_mfma_f32_16x16x32_bf16 v[0:3], v[174:177], v[206:209], v[0:3]
	v_mfma_f32_16x16x32_bf16 v[52:55], v[170:173], v[186:189], v[52:55]
	v_mfma_f32_16x16x32_bf16 v[48:51], v[178:181], v[186:189], v[48:51]
	v_mfma_f32_16x16x32_bf16 v[36:39], v[170:173], v[194:197], v[36:39]
	v_mfma_f32_16x16x32_bf16 v[32:35], v[178:181], v[194:197], v[32:35]
	v_mfma_f32_16x16x32_bf16 v[20:23], v[170:173], v[202:205], v[20:23]
	v_mfma_f32_16x16x32_bf16 v[12:15], v[178:181], v[202:205], v[12:15]
	v_mfma_f32_16x16x32_bf16 v[4:7], v[170:173], v[210:213], v[4:7]
	v_mfma_f32_16x16x32_bf16 v[0:3], v[178:181], v[210:213], v[0:3]
	s_barrier
	s_add_i32 s60, s60, 2
	s_add_u32 s58, s58, 0x100
	s_addc_u32 s59, s59, 0
	s_cmp_gt_u32 s60, 41
	s_mov_b64 s[12:13], s[14:15]
	s_cbranch_scc0 .LBB0_1456
	v_lshl_add_u32 v142, s57, 8, v137
	v_ashrrev_i32_e32 v143, 31, v142
	s_lshl_b32 s12, s56, 8
	v_lshlrev_b64 v[142:143], 10, v[142:143]
	s_ashr_i32 s13, s12, 31
	v_lshl_add_u64 v[166:167], v[142:143], 0, s[12:13]
	v_or_b32_e32 v166, v166, v136
	v_lshl_add_u64 v[142:143], v[166:167], 1, s[50:51]
	v_add_co_u32_e32 v162, vcc, s31, v142
	global_load_dwordx4 v[150:153], v[142:143], off
	global_load_dwordx4 v[154:157], v[142:143], off offset:256
	v_addc_co_u32_e32 v163, vcc, 0, v143, vcc
	global_load_dwordx4 v[158:161], v[162:163], off
	s_nop 0
	global_load_dwordx4 v[162:165], v[162:163], off offset:256
	s_and_b64 vcc, exec, s[6:7]
	s_cbranch_vccz .LBB0_1459
	s_barrier
